# loop-edge/segment-head hoist: scalar+address setup ahead of each load segment's first ds_read (and the K-loop pointer increments) moved into the preceding MFMA segment, one per MFMA gap
# speedup vs baseline: 1.0090x; 1.0090x over previous
; #define PG8_STAGE(bufoff, gbase, voff) do { _Pragma("unroll") for (int _i = 0; _i < 2; ++_i) \
;         __builtin_amdgcn_global_load_lds((const unsigned*)((const char*)(gbase) + (voff)[_i]), (LAS unsigned*)(lds + (bufoff) + ldsw + _i * 8192), 16, 0, 0); } while (0)
; #define PG8_LDA(dst, b, h) do { _Pragma("unroll") for (int m = 0; m < 4; ++m) _Pragma("unroll") for (int k = 0; k < 2; ++k) dst[m][k] = *(const LAS bf16x8*)(lds + PG8_SA(b, h) + aoff + m * 2048 + k * 1024); } while (0)
; #define PG8_LDB(dst, b, h) do { _Pragma("unroll") for (int n = 0; n < 2; ++n) _Pragma("unroll") for (int k = 0; k < 2; ++k) dst[n][k] = *(const LAS bf16x8*)(lds + PG8_SB(b, h) + boff + n * 2048 + k * 1024); } while (0)
; #define PG8_WAIT_V(n) asm volatile("s_waitcnt vmcnt(" #n ")" ::: "memory")
; #define PG8_WAIT_L(n) asm volatile("s_waitcnt lgkmcnt(" #n ")" ::: "memory")
; #define PG8_BAR __builtin_amdgcn_s_barrier()
; #define PG8_SCHED __builtin_amdgcn_sched_barrier(0)
; template <class Epi>
; __device__ __forceinline__ void gemm_phase(LAS unsigned char* lds, const Gemm g, const StaticOrder& S, const Epi& E, const int tid) {
;     ...
;             const bool last = (t == ntt - 2);
;             const bool s1 = Epi::TWO && (t >= nt), s2 = Epi::TWO && (t + 2 >= nt);
;             const char* a1 = (s1 ? cA2 + (size_t)(t - nt + 1) * kstep : cA + (size_t)(t + 1) * kstep);
;             const char* a2 = last ? nA : (s2 ? cA2 + (size_t)(t + 2 - nt) * kstep : cA + (size_t)(t + 2) * kstep);
;             const char* b2 = last ? nB : (s2 ? cB2 + (size_t)(t + 2 - nt) * kstep : cB + (size_t)(t + 2) * kstep);
;             const char* a3 = a2 + kstep; const char* b3 = b2 + kstep;
;             if constexpr (Epi::TWO) { if (t == nt) E.mid(acc, cur, wr, wc, fr, fq); }
;             if constexpr (SP2) {
;             PG8_LDB(B0, 0, 0); PG8_LDB(B1, 0, 1); PG8_SCHED; PG8_LDA(At, 0, 0); PG8_STAGE(PG8_SA(1, 1), a1 + hstep, voffA);
;             PG8_WAIT_V(8); PG8_WAIT_L(0); PG8_BAR; PG8_MMA(0, 0, At, B0); PG8_MMA(0, 1, At, B1); PG8_BAR; PG8_SCHED;
;             PG8_LDA(At, 0, 1); PG8_STAGE(PG8_SB(0, 0), b2, voffB); PG8_STAGE(PG8_SB(0, 1), b2 + bhs, voffB); PG8_STAGE(PG8_SA(0, 0), a2, voffA);
;             PG8_WAIT_V(8); PG8_WAIT_L(0); PG8_BAR; PG8_MMA(1, 0, At, B0); PG8_MMA(1, 1, At, B1); PG8_BAR; PG8_SCHED;
.LBB0_126:
	s_add_u32 s30, s28, 0xffe00080
	s_addc_u32 s31, s29, -1
	s_add_i32 s52, 0, 0x10000
	s_cmpk_eq_i32 s51, 0x7c
	s_cselect_b32 s35, s17, s31
	s_cselect_b32 s34, s27, s30
	s_cselect_b32 s31, s15, s50
	s_cselect_b32 s30, s33, s49
	s_add_i32 s54, 0, 0x14000
	v_add_u32_e32 v30, s52, v193
	v_add_u32_e32 v54, s54, v193
	ds_read_b128 v[18:21], v30
	ds_read_b128 v[22:25], v30 offset:1024
	ds_read_b128 v[26:29], v30 offset:2048
	ds_read_b128 v[30:33], v30 offset:3072
	ds_read_b128 v[42:45], v54
	ds_read_b128 v[46:49], v54 offset:1024
	ds_read_b128 v[50:53], v54 offset:2048
	ds_read_b128 v[54:57], v54 offset:3072
	v_lshl_add_u64 v[172:173], s[28:29], 0, v[180:181]
	s_add_i32 m0, s37, 0xc000
	ds_read_b128 v[182:185], v199
	global_load_lds_dwordx4 v[172:173], off
	ds_read_b128 v[186:189], v199 offset:1024
	ds_read_b128 v[212:215], v199 offset:2048
	v_lshl_add_u64 v[172:173], s[28:29], 0, v[178:179]
	s_add_i32 m0, s37, 0xe000
	s_nop 0
	global_load_lds_dwordx4 v[172:173], off
	ds_read_b128 v[216:219], v199 offset:3072
	ds_read_b128 v[220:223], v199 offset:4096
	ds_read_b128 v[224:227], v199 offset:5120
	ds_read_b128 v[228:231], v199 offset:6144
	ds_read_b128 v[232:235], v199 offset:7168
	s_waitcnt vmcnt(8)
	s_waitcnt lgkmcnt(0)
	s_barrier
	s_setprio 1
	s_waitcnt lgkmcnt(0)
	v_mfma_f32_16x16x32_bf16 v[158:161], v[18:21], v[182:185], v[158:161]
	v_mfma_f32_16x16x32_bf16 v[154:157], v[26:29], v[182:185], v[154:157]
	s_add_i32 s52, s52, s36
	v_mfma_f32_16x16x32_bf16 v[142:145], v[18:21], v[212:215], v[142:145]
	v_lshl_add_u64 v[172:173], s[30:31], 0, v[0:1]
	v_mfma_f32_16x16x32_bf16 v[138:141], v[26:29], v[212:215], v[138:141]
	s_mov_b32 m0, s52
	v_mfma_f32_16x16x32_bf16 v[126:129], v[18:21], v[220:223], v[126:129]
	v_mfma_f32_16x16x32_bf16 v[122:125], v[26:29], v[220:223], v[122:125]
	v_mfma_f32_16x16x32_bf16 v[110:113], v[18:21], v[228:231], v[110:113]
	v_mfma_f32_16x16x32_bf16 v[106:109], v[26:29], v[228:231], v[106:109]
	v_mfma_f32_16x16x32_bf16 v[158:161], v[22:25], v[186:189], v[158:161]
	v_mfma_f32_16x16x32_bf16 v[154:157], v[30:33], v[186:189], v[154:157]
	v_mfma_f32_16x16x32_bf16 v[142:145], v[22:25], v[216:219], v[142:145]
	v_mfma_f32_16x16x32_bf16 v[138:141], v[30:33], v[216:219], v[138:141]
	v_mfma_f32_16x16x32_bf16 v[126:129], v[22:25], v[224:227], v[126:129]
	v_mfma_f32_16x16x32_bf16 v[122:125], v[30:33], v[224:227], v[122:125]
	v_mfma_f32_16x16x32_bf16 v[110:113], v[22:25], v[232:235], v[110:113]
	v_mfma_f32_16x16x32_bf16 v[106:109], v[30:33], v[232:235], v[106:109]
	s_setprio 0
	s_setprio 1
	v_mfma_f32_16x16x32_bf16 v[150:153], v[42:45], v[182:185], v[150:153]
	v_mfma_f32_16x16x32_bf16 v[146:149], v[50:53], v[182:185], v[146:149]
	v_mfma_f32_16x16x32_bf16 v[134:137], v[42:45], v[212:215], v[134:137]
	v_mfma_f32_16x16x32_bf16 v[130:133], v[50:53], v[212:215], v[130:133]
	v_mfma_f32_16x16x32_bf16 v[118:121], v[42:45], v[220:223], v[118:121]
	v_mfma_f32_16x16x32_bf16 v[114:117], v[50:53], v[220:223], v[114:117]
	v_mfma_f32_16x16x32_bf16 v[102:105], v[42:45], v[228:231], v[102:105]
	v_mfma_f32_16x16x32_bf16 v[98:101], v[50:53], v[228:231], v[98:101]
	v_mfma_f32_16x16x32_bf16 v[150:153], v[46:49], v[186:189], v[150:153]
	v_mfma_f32_16x16x32_bf16 v[146:149], v[54:57], v[186:189], v[146:149]
	v_mfma_f32_16x16x32_bf16 v[134:137], v[46:49], v[216:219], v[134:137]
	v_mfma_f32_16x16x32_bf16 v[130:133], v[54:57], v[216:219], v[130:133]
	v_mfma_f32_16x16x32_bf16 v[118:121], v[46:49], v[224:227], v[118:121]
	v_mfma_f32_16x16x32_bf16 v[114:117], v[54:57], v[224:227], v[114:117]
	v_mfma_f32_16x16x32_bf16 v[102:105], v[46:49], v[232:235], v[102:105]
	v_mfma_f32_16x16x32_bf16 v[98:101], v[54:57], v[232:235], v[98:101]
	s_setprio 0
	s_barrier
	ds_read_b128 v[182:185], v199 offset:16384
	global_load_lds_dwordx4 v[172:173], off
	ds_read_b128 v[186:189], v199 offset:17408
	ds_read_b128 v[212:215], v199 offset:18432
	s_add_i32 m0, s52, 0x2000
	s_add_u32 s52, s30, 0x20000
	v_lshl_add_u64 v[174:175], s[30:31], 0, v[166:167]
	s_addc_u32 s53, s31, 0
	s_add_i32 s54, s54, s36
	global_load_lds_dwordx4 v[174:175], off
	ds_read_b128 v[216:219], v199 offset:19456
	ds_read_b128 v[220:223], v199 offset:20480
	v_lshl_add_u64 v[176:177], s[52:53], 0, v[0:1]
	s_mov_b32 m0, s54
	v_lshl_add_u64 v[200:201], s[34:35], 0, v[164:165]
	global_load_lds_dwordx4 v[176:177], off
	ds_read_b128 v[224:227], v199 offset:21504
	ds_read_b128 v[228:231], v199 offset:22528
	v_lshl_add_u64 v[176:177], s[52:53], 0, v[166:167]
	s_add_i32 m0, s54, 0x2000
	s_nop 0
	global_load_lds_dwordx4 v[176:177], off
	ds_read_b128 v[232:235], v199 offset:23552
	v_lshl_add_u64 v[176:177], s[34:35], 0, v[162:163]
	s_mov_b32 m0, s37
	s_nop 0
	global_load_lds_dwordx4 v[176:177], off
	s_mov_b32 m0, s38
	s_nop 0
	global_load_lds_dwordx4 v[200:201], off
	s_waitcnt vmcnt(8)
	s_waitcnt lgkmcnt(0)
	s_barrier
; #define PG8_STAGE(bufoff, gbase, voff) do { _Pragma("unroll") for (int _i = 0; _i < 2; ++_i) \
;         __builtin_amdgcn_global_load_lds((const unsigned*)((const char*)(gbase) + (voff)[_i]), (LAS unsigned*)(lds + (bufoff) + ldsw + _i * 8192), 16, 0, 0); } while (0)
; #define PG8_LDA(dst, b, h) do { _Pragma("unroll") for (int m = 0; m < 4; ++m) _Pragma("unroll") for (int k = 0; k < 2; ++k) dst[m][k] = *(const LAS bf16x8*)(lds + PG8_SA(b, h) + aoff + m * 2048 + k * 1024); } while (0)
; #define PG8_LDB(dst, b, h) do { _Pragma("unroll") for (int n = 0; n < 2; ++n) _Pragma("unroll") for (int k = 0; k < 2; ++k) dst[n][k] = *(const LAS bf16x8*)(lds + PG8_SB(b, h) + boff + n * 2048 + k * 1024); } while (0)
; #define PG8_MMA(ai, bj, At, Bt) do { __builtin_amdgcn_s_setprio(1); _Pragma("unroll") for (int m = 0; m < 4; ++m) _Pragma("unroll") for (int n = 0; n < 2; ++n) _Pragma("unroll") for (int k = 0; k < 2; ++k) \
;         acc[ai][bj][m][n] = __builtin_amdgcn_mfma_f32_16x16x32_bf16(Bt[n][k], At[m][k], acc[ai][bj][m][n], 0, 0, 0); __builtin_amdgcn_s_setprio(0); } while (0)
; #define PG8_WAIT_V(n) asm volatile("s_waitcnt vmcnt(" #n ")" ::: "memory")
; #define PG8_WAIT_L(n) asm volatile("s_waitcnt lgkmcnt(" #n ")" ::: "memory")
; #define PG8_BAR __builtin_amdgcn_s_barrier()
; #define PG8_SCHED __builtin_amdgcn_sched_barrier(0)
; template <class Epi>
; __device__ __forceinline__ void gemm_phase(LAS unsigned char* lds, const Gemm g, const StaticOrder& S, const Epi& E, const int tid) {
;     ...
;             PG8_WAIT_V(8); PG8_WAIT_L(0); PG8_BAR; PG8_MMA(1, 0, At, B0); PG8_MMA(1, 1, At, B1); PG8_BAR; PG8_SCHED;
;             PG8_LDB(B0, 1, 0); PG8_LDB(B1, 1, 1); PG8_SCHED; PG8_LDA(At, 1, 0); PG8_STAGE(PG8_SA(0, 1), a2 + hstep, voffA);
;             PG8_WAIT_V(8); PG8_WAIT_L(0); PG8_BAR; PG8_MMA(0, 0, At, B0); PG8_MMA(0, 1, At, B1); PG8_BAR; PG8_SCHED;
	s_setprio 1
	s_waitcnt lgkmcnt(0)
	v_mfma_f32_16x16x32_bf16 v[94:97], v[18:21], v[182:185], v[94:97]
	v_mfma_f32_16x16x32_bf16 v[90:93], v[26:29], v[182:185], v[90:93]
	s_add_i32 s52, 0, 0x18000
	v_mfma_f32_16x16x32_bf16 v[78:81], v[18:21], v[212:215], v[78:81]
	s_add_i32 s53, 0, 0x1c000
	v_mfma_f32_16x16x32_bf16 v[74:77], v[26:29], v[212:215], v[74:77]
	v_mfma_f32_16x16x32_bf16 v[62:65], v[18:21], v[220:223], v[62:65]
	v_mfma_f32_16x16x32_bf16 v[58:61], v[26:29], v[220:223], v[58:61]
	v_mfma_f32_16x16x32_bf16 v[14:17], v[18:21], v[228:231], v[14:17]
	v_mfma_f32_16x16x32_bf16 v[10:13], v[26:29], v[228:231], v[10:13]
	v_mfma_f32_16x16x32_bf16 v[94:97], v[22:25], v[186:189], v[94:97]
	v_mfma_f32_16x16x32_bf16 v[90:93], v[30:33], v[186:189], v[90:93]
	v_mfma_f32_16x16x32_bf16 v[78:81], v[22:25], v[216:219], v[78:81]
	v_mfma_f32_16x16x32_bf16 v[74:77], v[30:33], v[216:219], v[74:77]
	v_mfma_f32_16x16x32_bf16 v[62:65], v[22:25], v[224:227], v[62:65]
	v_mfma_f32_16x16x32_bf16 v[58:61], v[30:33], v[224:227], v[58:61]
	v_mfma_f32_16x16x32_bf16 v[14:17], v[22:25], v[232:235], v[14:17]
	v_mfma_f32_16x16x32_bf16 v[10:13], v[30:33], v[232:235], v[10:13]
	s_setprio 0
	s_setprio 1
	v_mfma_f32_16x16x32_bf16 v[38:41], v[42:45], v[220:223], v[38:41]
	v_mfma_f32_16x16x32_bf16 v[34:37], v[50:53], v[220:223], v[34:37]
	v_mfma_f32_16x16x32_bf16 v[6:9], v[42:45], v[228:231], v[6:9]
	v_mfma_f32_16x16x32_bf16 v[2:5], v[50:53], v[228:231], v[2:5]
	v_mfma_f32_16x16x32_bf16 v[18:21], v[42:45], v[182:185], v[86:89]
	v_mfma_f32_16x16x32_bf16 v[22:25], v[50:53], v[182:185], v[82:85]
	v_mfma_f32_16x16x32_bf16 v[26:29], v[42:45], v[212:215], v[70:73]
	v_mfma_f32_16x16x32_bf16 v[30:33], v[50:53], v[212:215], v[66:69]
	v_mfma_f32_16x16x32_bf16 v[38:41], v[46:49], v[224:227], v[38:41]
	v_mfma_f32_16x16x32_bf16 v[34:37], v[54:57], v[224:227], v[34:37]
	v_mfma_f32_16x16x32_bf16 v[6:9], v[46:49], v[232:235], v[6:9]
	v_mfma_f32_16x16x32_bf16 v[2:5], v[54:57], v[232:235], v[2:5]
	v_mfma_f32_16x16x32_bf16 v[18:21], v[46:49], v[186:189], v[18:21]
	v_mfma_f32_16x16x32_bf16 v[22:25], v[54:57], v[186:189], v[22:25]
	v_mfma_f32_16x16x32_bf16 v[26:29], v[46:49], v[216:219], v[26:29]
	v_mfma_f32_16x16x32_bf16 v[30:33], v[54:57], v[216:219], v[30:33]
	s_setprio 0
	s_barrier
	v_add_u32_e32 v54, s52, v193
	v_add_u32_e32 v66, s53, v193
	ds_read_b128 v[42:45], v54
	ds_read_b128 v[46:49], v54 offset:1024
	ds_read_b128 v[50:53], v54 offset:2048
	ds_read_b128 v[54:57], v54 offset:3072
	ds_read_b128 v[182:185], v66
	ds_read_b128 v[186:189], v66 offset:1024
	ds_read_b128 v[212:215], v66 offset:2048
	ds_read_b128 v[216:219], v66 offset:3072
	s_add_u32 s34, s34, 0x200000
	s_addc_u32 s35, s35, 0
	s_mov_b32 m0, s39
	v_lshl_add_u64 v[236:237], s[34:35], 0, v[162:163]
	ds_read_b128 v[66:69], v199 offset:32768
	global_load_lds_dwordx4 v[236:237], off
	ds_read_b128 v[70:73], v199 offset:33792
	ds_read_b128 v[82:85], v199 offset:34816
	v_lshl_add_u64 v[236:237], s[34:35], 0, v[164:165]
	s_mov_b32 m0, s44
	s_nop 0
	global_load_lds_dwordx4 v[236:237], off
	ds_read_b128 v[86:89], v199 offset:35840
	ds_read_b128 v[220:223], v199 offset:36864
	ds_read_b128 v[224:227], v199 offset:37888
	ds_read_b128 v[228:231], v199 offset:38912
	ds_read_b128 v[232:235], v199 offset:39936
	s_waitcnt vmcnt(8)
	s_waitcnt lgkmcnt(0)
	s_barrier
	s_setprio 1
	s_waitcnt lgkmcnt(0)
	v_mfma_f32_16x16x32_bf16 v[158:161], v[42:45], v[66:69], v[158:161]
	v_mfma_f32_16x16x32_bf16 v[154:157], v[50:53], v[66:69], v[154:157]
	v_mfma_f32_16x16x32_bf16 v[142:145], v[42:45], v[82:85], v[142:145]
	v_mfma_f32_16x16x32_bf16 v[138:141], v[50:53], v[82:85], v[138:141]
	v_mfma_f32_16x16x32_bf16 v[126:129], v[42:45], v[220:223], v[126:129]
	v_mfma_f32_16x16x32_bf16 v[122:125], v[50:53], v[220:223], v[122:125]
	v_mfma_f32_16x16x32_bf16 v[110:113], v[42:45], v[228:231], v[110:113]
	v_mfma_f32_16x16x32_bf16 v[106:109], v[50:53], v[228:231], v[106:109]
	v_mfma_f32_16x16x32_bf16 v[158:161], v[46:49], v[70:73], v[158:161]
	v_mfma_f32_16x16x32_bf16 v[154:157], v[54:57], v[70:73], v[154:157]
	v_mfma_f32_16x16x32_bf16 v[142:145], v[46:49], v[86:89], v[142:145]
	v_mfma_f32_16x16x32_bf16 v[138:141], v[54:57], v[86:89], v[138:141]
	v_mfma_f32_16x16x32_bf16 v[126:129], v[46:49], v[224:227], v[126:129]
	v_mfma_f32_16x16x32_bf16 v[122:125], v[54:57], v[224:227], v[122:125]
	v_mfma_f32_16x16x32_bf16 v[110:113], v[46:49], v[232:235], v[110:113]
	v_mfma_f32_16x16x32_bf16 v[106:109], v[54:57], v[232:235], v[106:109]
	s_setprio 0
	s_setprio 1
	v_mfma_f32_16x16x32_bf16 v[150:153], v[182:185], v[66:69], v[150:153]
	v_mfma_f32_16x16x32_bf16 v[66:69], v[212:215], v[66:69], v[146:149]
	v_mfma_f32_16x16x32_bf16 v[146:149], v[216:219], v[70:73], v[66:69]
	v_mfma_f32_16x16x32_bf16 v[66:69], v[182:185], v[82:85], v[134:137]
	v_mfma_f32_16x16x32_bf16 v[134:137], v[186:189], v[86:89], v[66:69]
	v_mfma_f32_16x16x32_bf16 v[66:69], v[212:215], v[82:85], v[130:133]
	v_mfma_f32_16x16x32_bf16 v[130:133], v[216:219], v[86:89], v[66:69]
	v_mfma_f32_16x16x32_bf16 v[66:69], v[182:185], v[220:223], v[118:121]
	v_mfma_f32_16x16x32_bf16 v[118:121], v[186:189], v[224:227], v[66:69]
	v_mfma_f32_16x16x32_bf16 v[66:69], v[212:215], v[220:223], v[114:117]
	v_mfma_f32_16x16x32_bf16 v[114:117], v[216:219], v[224:227], v[66:69]
	v_mfma_f32_16x16x32_bf16 v[66:69], v[182:185], v[228:231], v[102:105]
	v_mfma_f32_16x16x32_bf16 v[102:105], v[186:189], v[232:235], v[66:69]
	v_mfma_f32_16x16x32_bf16 v[66:69], v[212:215], v[228:231], v[98:101]
	v_mfma_f32_16x16x32_bf16 v[150:153], v[186:189], v[70:73], v[150:153]
	v_mfma_f32_16x16x32_bf16 v[98:101], v[216:219], v[232:235], v[66:69]
	s_setprio 0
	s_barrier
; #define PG8_STAGE(bufoff, gbase, voff) do { _Pragma("unroll") for (int _i = 0; _i < 2; ++_i) \
;         __builtin_amdgcn_global_load_lds((const unsigned*)((const char*)(gbase) + (voff)[_i]), (LAS unsigned*)(lds + (bufoff) + ldsw + _i * 8192), 16, 0, 0); } while (0)
; #define PG8_LDA(dst, b, h) do { _Pragma("unroll") for (int m = 0; m < 4; ++m) _Pragma("unroll") for (int k = 0; k < 2; ++k) dst[m][k] = *(const LAS bf16x8*)(lds + PG8_SA(b, h) + aoff + m * 2048 + k * 1024); } while (0)
; #define PG8_MMA(ai, bj, At, Bt) do { __builtin_amdgcn_s_setprio(1); _Pragma("unroll") for (int m = 0; m < 4; ++m) _Pragma("unroll") for (int n = 0; n < 2; ++n) _Pragma("unroll") for (int k = 0; k < 2; ++k) \
;         acc[ai][bj][m][n] = __builtin_amdgcn_mfma_f32_16x16x32_bf16(Bt[n][k], At[m][k], acc[ai][bj][m][n], 0, 0, 0); __builtin_amdgcn_s_setprio(0); } while (0)
; #define PG8_WAIT_V(n) asm volatile("s_waitcnt vmcnt(" #n ")" ::: "memory")
; #define PG8_WAIT_L(n) asm volatile("s_waitcnt lgkmcnt(" #n ")" ::: "memory")
; #define PG8_BAR __builtin_amdgcn_s_barrier()
; #define PG8_SCHED __builtin_amdgcn_sched_barrier(0)
; template <class Epi>
; __device__ __forceinline__ void gemm_phase(LAS unsigned char* lds, const Gemm g, const StaticOrder& S, const Epi& E, const int tid) {
;     ...
;             PG8_LDA(At, 1, 1); PG8_STAGE(PG8_SB(1, 0), b3, voffB); PG8_STAGE(PG8_SB(1, 1), b3 + bhs, voffB); PG8_STAGE(PG8_SA(1, 0), a3, voffA);
;             PG8_WAIT_V(8); PG8_WAIT_L(0); PG8_BAR; PG8_MMA(1, 0, At, B0); PG8_MMA(1, 1, At, B1); PG8_BAR; PG8_SCHED;
;     ...
;         if (ALIGN_EPI) { if (wr == 0) PG8_BAR; }
	s_add_i32 s34, s52, s36
	v_lshl_add_u64 v[82:83], v[172:173], 0, s[70:71]
	s_mov_b32 m0, s34
	s_nop 0
	ds_read_b128 v[66:69], v199 offset:49152
	global_load_lds_dwordx4 v[82:83], off
	ds_read_b128 v[70:73], v199 offset:50176
	ds_read_b128 v[220:223], v199 offset:51200
	s_add_i32 m0, s34, 0x2000
	s_add_u32 s30, s30, 0x20080
	v_lshl_add_u64 v[82:83], v[174:175], 0, s[70:71]
	s_addc_u32 s31, s31, 0
	s_add_i32 s34, s53, s36
	global_load_lds_dwordx4 v[82:83], off
	ds_read_b128 v[224:227], v199 offset:52224
	ds_read_b128 v[228:231], v199 offset:53248
	v_lshl_add_u64 v[82:83], s[30:31], 0, v[0:1]
	s_mov_b32 m0, s34
	s_nop 0
	global_load_lds_dwordx4 v[82:83], off
	ds_read_b128 v[232:235], v199 offset:54272
	ds_read_b128 v[236:239], v199 offset:55296
	v_lshl_add_u64 v[82:83], s[30:31], 0, v[166:167]
	s_add_i32 m0, s34, 0x2000
	s_nop 0
	global_load_lds_dwordx4 v[82:83], off
	ds_read_b128 v[240:243], v199 offset:56320
	v_lshl_add_u64 v[82:83], v[176:177], 0, s[70:71]
	s_mov_b32 m0, s45
	s_nop 0
	global_load_lds_dwordx4 v[82:83], off
	v_lshl_add_u64 v[82:83], v[200:201], 0, s[70:71]
	s_mov_b32 m0, s46
	s_nop 0
	global_load_lds_dwordx4 v[82:83], off
	s_waitcnt vmcnt(8)
	s_waitcnt lgkmcnt(0)
	s_barrier
	s_setprio 1
	s_waitcnt lgkmcnt(0)
	v_mfma_f32_16x16x32_bf16 v[82:85], v[42:45], v[66:69], v[94:97]
	v_mfma_f32_16x16x32_bf16 v[94:97], v[46:49], v[70:73], v[82:85]
	s_add_i32 s51, s51, 2
	v_mfma_f32_16x16x32_bf16 v[82:85], v[50:53], v[66:69], v[90:93]
	s_add_u32 s49, s49, 0x100
	v_mfma_f32_16x16x32_bf16 v[78:81], v[42:45], v[220:223], v[78:81]
	s_addc_u32 s50, s50, 0
	v_mfma_f32_16x16x32_bf16 v[74:77], v[50:53], v[220:223], v[74:77]
	s_add_u32 s28, s28, 0x100
	v_mfma_f32_16x16x32_bf16 v[62:65], v[42:45], v[228:231], v[62:65]
	s_addc_u32 s29, s29, 0
	v_mfma_f32_16x16x32_bf16 v[58:61], v[50:53], v[228:231], v[58:61]
	v_mfma_f32_16x16x32_bf16 v[14:17], v[42:45], v[236:239], v[14:17]
	v_mfma_f32_16x16x32_bf16 v[10:13], v[50:53], v[236:239], v[10:13]
	v_mfma_f32_16x16x32_bf16 v[90:93], v[54:57], v[70:73], v[82:85]
	v_mfma_f32_16x16x32_bf16 v[78:81], v[46:49], v[224:227], v[78:81]
	v_mfma_f32_16x16x32_bf16 v[74:77], v[54:57], v[224:227], v[74:77]
	v_mfma_f32_16x16x32_bf16 v[62:65], v[46:49], v[232:235], v[62:65]
	v_mfma_f32_16x16x32_bf16 v[58:61], v[54:57], v[232:235], v[58:61]
	v_mfma_f32_16x16x32_bf16 v[14:17], v[46:49], v[240:243], v[14:17]
	v_mfma_f32_16x16x32_bf16 v[10:13], v[54:57], v[240:243], v[10:13]
	s_setprio 0
	s_setprio 1
	v_mfma_f32_16x16x32_bf16 v[18:21], v[182:185], v[66:69], v[18:21]
	v_mfma_f32_16x16x32_bf16 v[86:89], v[186:189], v[70:73], v[18:21]
	v_mfma_f32_16x16x32_bf16 v[18:21], v[212:215], v[66:69], v[22:25]
	v_mfma_f32_16x16x32_bf16 v[82:85], v[216:219], v[70:73], v[18:21]
	v_mfma_f32_16x16x32_bf16 v[18:21], v[182:185], v[220:223], v[26:29]
	v_mfma_f32_16x16x32_bf16 v[70:73], v[186:189], v[224:227], v[18:21]
	v_mfma_f32_16x16x32_bf16 v[18:21], v[212:215], v[220:223], v[30:33]
	v_mfma_f32_16x16x32_bf16 v[66:69], v[216:219], v[224:227], v[18:21]
	v_mfma_f32_16x16x32_bf16 v[18:21], v[182:185], v[228:231], v[38:41]
	v_mfma_f32_16x16x32_bf16 v[38:41], v[186:189], v[232:235], v[18:21]
	v_mfma_f32_16x16x32_bf16 v[18:21], v[212:215], v[228:231], v[34:37]
	v_mfma_f32_16x16x32_bf16 v[6:9], v[182:185], v[236:239], v[6:9]
	v_mfma_f32_16x16x32_bf16 v[2:5], v[212:215], v[236:239], v[2:5]
	v_mfma_f32_16x16x32_bf16 v[34:37], v[216:219], v[232:235], v[18:21]
	v_mfma_f32_16x16x32_bf16 v[6:9], v[186:189], v[240:243], v[6:9]
	v_mfma_f32_16x16x32_bf16 v[2:5], v[216:219], v[240:243], v[2:5]
	s_setprio 0
	s_barrier
	s_cmpk_gt_u32 s51, 0x7d
	s_cbranch_scc0 .LBB0_126
	s_and_b64 vcc, exec, s[12:13]
	s_cbranch_vccz .LBB0_129
	s_barrier

; #define PG8_STAGE(bufoff, gbase, voff) do { _Pragma("unroll") for (int _i = 0; _i < 2; ++_i) \
;         __builtin_amdgcn_global_load_lds((const unsigned*)((const char*)(gbase) + (voff)[_i]), (LAS unsigned*)(lds + (bufoff) + ldsw + _i * 8192), 16, 0, 0); } while (0)
; #define PG8_LDA(dst, b, h) do { _Pragma("unroll") for (int m = 0; m < 4; ++m) _Pragma("unroll") for (int k = 0; k < 2; ++k) dst[m][k] = *(const LAS bf16x8*)(lds + PG8_SA(b, h) + aoff + m * 2048 + k * 1024); } while (0)
; #define PG8_LDB(dst, b, h) do { _Pragma("unroll") for (int n = 0; n < 2; ++n) _Pragma("unroll") for (int k = 0; k < 2; ++k) dst[n][k] = *(const LAS bf16x8*)(lds + PG8_SB(b, h) + boff + n * 2048 + k * 1024); } while (0)
; #define PG8_WAIT_V(n) asm volatile("s_waitcnt vmcnt(" #n ")" ::: "memory")
; #define PG8_WAIT_L(n) asm volatile("s_waitcnt lgkmcnt(" #n ")" ::: "memory")
; #define PG8_BAR __builtin_amdgcn_s_barrier()
; #define PG8_SCHED __builtin_amdgcn_sched_barrier(0)
; template <class Epi>
; __device__ __forceinline__ void gemm_phase(LAS unsigned char* lds, const Gemm g, const StaticOrder& S, const Epi& E, const int tid) {
;     ...
;             const bool last = (t == ntt - 2);
;             const bool s1 = Epi::TWO && (t >= nt), s2 = Epi::TWO && (t + 2 >= nt);
;             const char* a1 = (s1 ? cA2 + (size_t)(t - nt + 1) * kstep : cA + (size_t)(t + 1) * kstep);
;             const char* a2 = last ? nA : (s2 ? cA2 + (size_t)(t + 2 - nt) * kstep : cA + (size_t)(t + 2) * kstep);
;             const char* b2 = last ? nB : (s2 ? cB2 + (size_t)(t + 2 - nt) * kstep : cB + (size_t)(t + 2) * kstep);
;             const char* a3 = a2 + kstep; const char* b3 = b2 + kstep;
;             if constexpr (Epi::TWO) { if (t == nt) E.mid(acc, cur, wr, wc, fr, fq); }
;             if constexpr (SP2) {
;             PG8_LDB(B0, 0, 0); PG8_LDB(B1, 0, 1); PG8_SCHED; PG8_LDA(At, 0, 0); PG8_STAGE(PG8_SA(1, 1), a1 + hstep, voffA);
;             PG8_WAIT_V(8); PG8_WAIT_L(0); PG8_BAR; PG8_MMA(0, 0, At, B0); PG8_MMA(0, 1, At, B1); PG8_BAR; PG8_SCHED;
;             PG8_LDA(At, 0, 1); PG8_STAGE(PG8_SB(0, 0), b2, voffB); PG8_STAGE(PG8_SB(0, 1), b2 + bhs, voffB); PG8_STAGE(PG8_SA(0, 0), a2, voffA);
;             PG8_WAIT_V(8); PG8_WAIT_L(0); PG8_BAR; PG8_MMA(1, 0, At, B0); PG8_MMA(1, 1, At, B1); PG8_BAR; PG8_SCHED;
.LBB0_173:
	s_add_u32 s28, s26, 0xfff80080
	s_addc_u32 s29, s27, -1
	s_add_i32 s47, 0, 0x10000
	s_cmp_eq_u32 s46, 28
	s_cselect_b32 s31, s17, s29
	s_cselect_b32 s30, s42, s28
	v_add_u32_e32 v142, s47, v149
	s_cselect_b32 s29, s15, s45
	s_cselect_b32 s28, s43, s44
	s_add_i32 s50, 0, 0x14000
	ds_read_b128 v[156:159], v142
	ds_read_b128 v[160:163], v142 offset:1024
	ds_read_b128 v[164:167], v142 offset:2048
	ds_read_b128 v[178:181], v142 offset:3072
	v_add_u32_e32 v142, s50, v149
	ds_read_b128 v[182:185], v142
	ds_read_b128 v[186:189], v142 offset:1024
	ds_read_b128 v[190:193], v142 offset:2048
	ds_read_b128 v[194:197], v142 offset:3072
	v_lshl_add_u64 v[142:143], s[26:27], 0, v[140:141]
	s_add_i32 m0, s2, 0xc000
	ds_read_b128 v[198:201], v154
	global_load_lds_dwordx4 v[142:143], off
	ds_read_b128 v[212:215], v154 offset:1024
	ds_read_b128 v[216:219], v154 offset:2048
	v_lshl_add_u64 v[142:143], s[26:27], 0, v[138:139]
	s_add_i32 m0, s2, 0xe000
	s_nop 0
	global_load_lds_dwordx4 v[142:143], off
	ds_read_b128 v[220:223], v154 offset:3072
	ds_read_b128 v[224:227], v154 offset:4096
	ds_read_b128 v[228:231], v154 offset:5120
	ds_read_b128 v[232:235], v154 offset:6144
	ds_read_b128 v[236:239], v154 offset:7168
	s_waitcnt vmcnt(8)
	s_waitcnt lgkmcnt(0)
	s_barrier
	s_setprio 1
	s_waitcnt lgkmcnt(0)
	v_mfma_f32_16x16x32_bf16 v[126:129], v[156:159], v[198:201], v[126:129]
	v_mfma_f32_16x16x32_bf16 v[122:125], v[164:167], v[198:201], v[122:125]
	s_add_i32 s47, s47, s34
	v_mfma_f32_16x16x32_bf16 v[110:113], v[156:159], v[216:219], v[110:113]
	v_lshl_add_u64 v[142:143], s[28:29], 0, v[0:1]
	v_mfma_f32_16x16x32_bf16 v[106:109], v[164:167], v[216:219], v[106:109]
	s_mov_b32 m0, s47
	v_mfma_f32_16x16x32_bf16 v[94:97], v[156:159], v[224:227], v[94:97]
	v_mfma_f32_16x16x32_bf16 v[90:93], v[164:167], v[224:227], v[90:93]
	v_mfma_f32_16x16x32_bf16 v[78:81], v[156:159], v[232:235], v[78:81]
	v_mfma_f32_16x16x32_bf16 v[74:77], v[164:167], v[232:235], v[74:77]
	v_mfma_f32_16x16x32_bf16 v[126:129], v[160:163], v[212:215], v[126:129]
	v_mfma_f32_16x16x32_bf16 v[122:125], v[178:181], v[212:215], v[122:125]
	v_mfma_f32_16x16x32_bf16 v[110:113], v[160:163], v[220:223], v[110:113]
	v_mfma_f32_16x16x32_bf16 v[106:109], v[178:181], v[220:223], v[106:109]
	v_mfma_f32_16x16x32_bf16 v[94:97], v[160:163], v[228:231], v[94:97]
	v_mfma_f32_16x16x32_bf16 v[90:93], v[178:181], v[228:231], v[90:93]
	v_mfma_f32_16x16x32_bf16 v[78:81], v[160:163], v[236:239], v[78:81]
	v_mfma_f32_16x16x32_bf16 v[74:77], v[178:181], v[236:239], v[74:77]
	s_setprio 0
	s_setprio 1
	v_mfma_f32_16x16x32_bf16 v[118:121], v[182:185], v[198:201], v[118:121]
	v_mfma_f32_16x16x32_bf16 v[114:117], v[190:193], v[198:201], v[114:117]
	v_mfma_f32_16x16x32_bf16 v[102:105], v[182:185], v[216:219], v[102:105]
	v_mfma_f32_16x16x32_bf16 v[98:101], v[190:193], v[216:219], v[98:101]
	v_mfma_f32_16x16x32_bf16 v[86:89], v[182:185], v[224:227], v[86:89]
	v_mfma_f32_16x16x32_bf16 v[82:85], v[190:193], v[224:227], v[82:85]
	v_mfma_f32_16x16x32_bf16 v[70:73], v[182:185], v[232:235], v[70:73]
	v_mfma_f32_16x16x32_bf16 v[66:69], v[190:193], v[232:235], v[66:69]
	v_mfma_f32_16x16x32_bf16 v[118:121], v[186:189], v[212:215], v[118:121]
	v_mfma_f32_16x16x32_bf16 v[114:117], v[194:197], v[212:215], v[114:117]
	v_mfma_f32_16x16x32_bf16 v[102:105], v[186:189], v[220:223], v[102:105]
	v_mfma_f32_16x16x32_bf16 v[98:101], v[194:197], v[220:223], v[98:101]
	v_mfma_f32_16x16x32_bf16 v[86:89], v[186:189], v[228:231], v[86:89]
	v_mfma_f32_16x16x32_bf16 v[82:85], v[194:197], v[228:231], v[82:85]
	v_mfma_f32_16x16x32_bf16 v[70:73], v[186:189], v[236:239], v[70:73]
	v_mfma_f32_16x16x32_bf16 v[66:69], v[194:197], v[236:239], v[66:69]
	s_setprio 0
	s_barrier
	ds_read_b128 v[198:201], v154 offset:16384
	global_load_lds_dwordx4 v[142:143], off
	ds_read_b128 v[212:215], v154 offset:17408
	ds_read_b128 v[216:219], v154 offset:18432
	s_add_i32 m0, s47, 0x2000
	s_add_u32 s48, s28, 0x8000
	v_lshl_add_u64 v[168:169], s[28:29], 0, v[134:135]
	s_addc_u32 s49, s29, 0
	s_add_i32 s47, s50, s34
	global_load_lds_dwordx4 v[168:169], off
	ds_read_b128 v[220:223], v154 offset:19456
	ds_read_b128 v[224:227], v154 offset:20480
	v_lshl_add_u64 v[172:173], s[48:49], 0, v[0:1]
	s_mov_b32 m0, s47
	v_lshl_add_u64 v[174:175], s[30:31], 0, v[132:133]
	global_load_lds_dwordx4 v[172:173], off
	ds_read_b128 v[228:231], v154 offset:21504
	ds_read_b128 v[232:235], v154 offset:22528
	v_lshl_add_u64 v[172:173], s[48:49], 0, v[134:135]
	s_add_i32 m0, s47, 0x2000
	s_nop 0
	global_load_lds_dwordx4 v[172:173], off
	ds_read_b128 v[236:239], v154 offset:23552
	v_lshl_add_u64 v[172:173], s[30:31], 0, v[130:131]
	s_mov_b32 m0, s2
	s_nop 0
	global_load_lds_dwordx4 v[172:173], off
	s_mov_b32 m0, s25
	s_nop 0
	global_load_lds_dwordx4 v[174:175], off
	s_waitcnt vmcnt(8)
	s_waitcnt lgkmcnt(0)
	s_barrier
; #define PG8_STAGE(bufoff, gbase, voff) do { _Pragma("unroll") for (int _i = 0; _i < 2; ++_i) \
;         __builtin_amdgcn_global_load_lds((const unsigned*)((const char*)(gbase) + (voff)[_i]), (LAS unsigned*)(lds + (bufoff) + ldsw + _i * 8192), 16, 0, 0); } while (0)
; #define PG8_LDA(dst, b, h) do { _Pragma("unroll") for (int m = 0; m < 4; ++m) _Pragma("unroll") for (int k = 0; k < 2; ++k) dst[m][k] = *(const LAS bf16x8*)(lds + PG8_SA(b, h) + aoff + m * 2048 + k * 1024); } while (0)
; #define PG8_LDB(dst, b, h) do { _Pragma("unroll") for (int n = 0; n < 2; ++n) _Pragma("unroll") for (int k = 0; k < 2; ++k) dst[n][k] = *(const LAS bf16x8*)(lds + PG8_SB(b, h) + boff + n * 2048 + k * 1024); } while (0)
; #define PG8_MMA(ai, bj, At, Bt) do { __builtin_amdgcn_s_setprio(1); _Pragma("unroll") for (int m = 0; m < 4; ++m) _Pragma("unroll") for (int n = 0; n < 2; ++n) _Pragma("unroll") for (int k = 0; k < 2; ++k) \
;         acc[ai][bj][m][n] = __builtin_amdgcn_mfma_f32_16x16x32_bf16(Bt[n][k], At[m][k], acc[ai][bj][m][n], 0, 0, 0); __builtin_amdgcn_s_setprio(0); } while (0)
; #define PG8_WAIT_V(n) asm volatile("s_waitcnt vmcnt(" #n ")" ::: "memory")
; #define PG8_WAIT_L(n) asm volatile("s_waitcnt lgkmcnt(" #n ")" ::: "memory")
; #define PG8_BAR __builtin_amdgcn_s_barrier()
; #define PG8_SCHED __builtin_amdgcn_sched_barrier(0)
; template <class Epi>
; __device__ __forceinline__ void gemm_phase(LAS unsigned char* lds, const Gemm g, const StaticOrder& S, const Epi& E, const int tid) {
;     ...
;             PG8_WAIT_V(8); PG8_WAIT_L(0); PG8_BAR; PG8_MMA(1, 0, At, B0); PG8_MMA(1, 1, At, B1); PG8_BAR; PG8_SCHED;
;             PG8_LDB(B0, 1, 0); PG8_LDB(B1, 1, 1); PG8_SCHED; PG8_LDA(At, 1, 0); PG8_STAGE(PG8_SA(0, 1), a2 + hstep, voffA);
;             PG8_WAIT_V(8); PG8_WAIT_L(0); PG8_BAR; PG8_MMA(0, 0, At, B0); PG8_MMA(0, 1, At, B1); PG8_BAR; PG8_SCHED;
;             PG8_LDA(At, 1, 1); PG8_STAGE(PG8_SB(1, 0), b3, voffB); PG8_STAGE(PG8_SB(1, 1), b3 + bhs, voffB); PG8_STAGE(PG8_SA(1, 0), a3, voffA);
	s_setprio 1
	s_waitcnt lgkmcnt(0)
	v_mfma_f32_16x16x32_bf16 v[62:65], v[156:159], v[198:201], v[62:65]
	v_mfma_f32_16x16x32_bf16 v[58:61], v[164:167], v[198:201], v[58:61]
	s_add_i32 s47, 0, 0x18000
	v_mfma_f32_16x16x32_bf16 v[46:49], v[156:159], v[216:219], v[46:49]
	v_add_u32_e32 v155, s47, v149
	v_mfma_f32_16x16x32_bf16 v[42:45], v[164:167], v[216:219], v[42:45]
	s_add_i32 s48, 0, 0x1c000
	v_mfma_f32_16x16x32_bf16 v[30:33], v[156:159], v[224:227], v[30:33]
	v_mfma_f32_16x16x32_bf16 v[26:29], v[164:167], v[224:227], v[26:29]
	v_mfma_f32_16x16x32_bf16 v[14:17], v[156:159], v[232:235], v[14:17]
	v_mfma_f32_16x16x32_bf16 v[10:13], v[164:167], v[232:235], v[10:13]
	v_mfma_f32_16x16x32_bf16 v[62:65], v[160:163], v[212:215], v[62:65]
	v_mfma_f32_16x16x32_bf16 v[58:61], v[178:181], v[212:215], v[58:61]
	v_mfma_f32_16x16x32_bf16 v[46:49], v[160:163], v[220:223], v[46:49]
	v_mfma_f32_16x16x32_bf16 v[42:45], v[178:181], v[220:223], v[42:45]
	v_mfma_f32_16x16x32_bf16 v[30:33], v[160:163], v[228:231], v[30:33]
	v_mfma_f32_16x16x32_bf16 v[26:29], v[178:181], v[228:231], v[26:29]
	v_mfma_f32_16x16x32_bf16 v[14:17], v[160:163], v[236:239], v[14:17]
	v_mfma_f32_16x16x32_bf16 v[10:13], v[178:181], v[236:239], v[10:13]
	s_setprio 0
	s_setprio 1
	v_mfma_f32_16x16x32_bf16 v[54:57], v[182:185], v[198:201], v[54:57]
	v_mfma_f32_16x16x32_bf16 v[50:53], v[190:193], v[198:201], v[50:53]
	v_mfma_f32_16x16x32_bf16 v[38:41], v[182:185], v[216:219], v[38:41]
	v_mfma_f32_16x16x32_bf16 v[34:37], v[190:193], v[216:219], v[34:37]
	v_mfma_f32_16x16x32_bf16 v[22:25], v[182:185], v[224:227], v[22:25]
	v_mfma_f32_16x16x32_bf16 v[18:21], v[190:193], v[224:227], v[18:21]
	v_mfma_f32_16x16x32_bf16 v[6:9], v[182:185], v[232:235], v[6:9]
	v_mfma_f32_16x16x32_bf16 v[2:5], v[190:193], v[232:235], v[2:5]
	v_mfma_f32_16x16x32_bf16 v[54:57], v[186:189], v[212:215], v[54:57]
	v_mfma_f32_16x16x32_bf16 v[50:53], v[194:197], v[212:215], v[50:53]
	v_mfma_f32_16x16x32_bf16 v[38:41], v[186:189], v[220:223], v[38:41]
	v_mfma_f32_16x16x32_bf16 v[34:37], v[194:197], v[220:223], v[34:37]
	v_mfma_f32_16x16x32_bf16 v[22:25], v[186:189], v[228:231], v[22:25]
	v_mfma_f32_16x16x32_bf16 v[18:21], v[194:197], v[228:231], v[18:21]
	v_mfma_f32_16x16x32_bf16 v[6:9], v[186:189], v[236:239], v[6:9]
	v_mfma_f32_16x16x32_bf16 v[2:5], v[194:197], v[236:239], v[2:5]
	s_setprio 0
	s_barrier
	ds_read_b128 v[156:159], v155
	ds_read_b128 v[160:163], v155 offset:1024
	ds_read_b128 v[164:167], v155 offset:2048
	ds_read_b128 v[178:181], v155 offset:3072
	v_add_u32_e32 v155, s48, v149
	ds_read_b128 v[182:185], v155
	ds_read_b128 v[186:189], v155 offset:1024
	ds_read_b128 v[190:193], v155 offset:2048
	ds_read_b128 v[194:197], v155 offset:3072
	s_add_u32 s30, s30, 0x80000
	s_addc_u32 s31, s31, 0
	s_mov_b32 m0, s35
	v_lshl_add_u64 v[176:177], s[30:31], 0, v[130:131]
	ds_read_b128 v[198:201], v154 offset:32768
	global_load_lds_dwordx4 v[176:177], off
	ds_read_b128 v[212:215], v154 offset:33792
	ds_read_b128 v[216:219], v154 offset:34816
	v_lshl_add_u64 v[176:177], s[30:31], 0, v[132:133]
	s_mov_b32 m0, s36
	s_nop 0
	global_load_lds_dwordx4 v[176:177], off
	ds_read_b128 v[220:223], v154 offset:35840
	ds_read_b128 v[224:227], v154 offset:36864
	ds_read_b128 v[228:231], v154 offset:37888
	ds_read_b128 v[232:235], v154 offset:38912
	ds_read_b128 v[236:239], v154 offset:39936
	s_waitcnt vmcnt(8)
	s_waitcnt lgkmcnt(0)
	s_barrier
	s_setprio 1
	s_waitcnt lgkmcnt(0)
	v_mfma_f32_16x16x32_bf16 v[126:129], v[156:159], v[198:201], v[126:129]
	v_mfma_f32_16x16x32_bf16 v[122:125], v[164:167], v[198:201], v[122:125]
	s_add_i32 s30, s47, s34
	v_mfma_f32_16x16x32_bf16 v[110:113], v[156:159], v[216:219], v[110:113]
	v_lshl_add_u64 v[142:143], v[142:143], 0, s[70:71]
	v_mfma_f32_16x16x32_bf16 v[106:109], v[164:167], v[216:219], v[106:109]
	s_mov_b32 m0, s30
	v_mfma_f32_16x16x32_bf16 v[94:97], v[156:159], v[224:227], v[94:97]
	v_mfma_f32_16x16x32_bf16 v[90:93], v[164:167], v[224:227], v[90:93]
	v_mfma_f32_16x16x32_bf16 v[78:81], v[156:159], v[232:235], v[78:81]
	v_mfma_f32_16x16x32_bf16 v[74:77], v[164:167], v[232:235], v[74:77]
	v_mfma_f32_16x16x32_bf16 v[126:129], v[160:163], v[212:215], v[126:129]
	v_mfma_f32_16x16x32_bf16 v[122:125], v[178:181], v[212:215], v[122:125]
	v_mfma_f32_16x16x32_bf16 v[110:113], v[160:163], v[220:223], v[110:113]
	v_mfma_f32_16x16x32_bf16 v[106:109], v[178:181], v[220:223], v[106:109]
	v_mfma_f32_16x16x32_bf16 v[94:97], v[160:163], v[228:231], v[94:97]
	v_mfma_f32_16x16x32_bf16 v[90:93], v[178:181], v[228:231], v[90:93]
	v_mfma_f32_16x16x32_bf16 v[78:81], v[160:163], v[236:239], v[78:81]
	v_mfma_f32_16x16x32_bf16 v[74:77], v[178:181], v[236:239], v[74:77]
	s_setprio 0
	s_setprio 1
	v_mfma_f32_16x16x32_bf16 v[118:121], v[182:185], v[198:201], v[118:121]
	v_mfma_f32_16x16x32_bf16 v[114:117], v[190:193], v[198:201], v[114:117]
	v_mfma_f32_16x16x32_bf16 v[102:105], v[182:185], v[216:219], v[102:105]
	v_mfma_f32_16x16x32_bf16 v[98:101], v[190:193], v[216:219], v[98:101]
	v_mfma_f32_16x16x32_bf16 v[86:89], v[182:185], v[224:227], v[86:89]
	v_mfma_f32_16x16x32_bf16 v[82:85], v[190:193], v[224:227], v[82:85]
	v_mfma_f32_16x16x32_bf16 v[70:73], v[182:185], v[232:235], v[70:73]
	v_mfma_f32_16x16x32_bf16 v[66:69], v[190:193], v[232:235], v[66:69]
	v_mfma_f32_16x16x32_bf16 v[118:121], v[186:189], v[212:215], v[118:121]
	v_mfma_f32_16x16x32_bf16 v[114:117], v[194:197], v[212:215], v[114:117]
	v_mfma_f32_16x16x32_bf16 v[102:105], v[186:189], v[220:223], v[102:105]
	v_mfma_f32_16x16x32_bf16 v[98:101], v[194:197], v[220:223], v[98:101]
	v_mfma_f32_16x16x32_bf16 v[86:89], v[186:189], v[228:231], v[86:89]
	v_mfma_f32_16x16x32_bf16 v[82:85], v[194:197], v[228:231], v[82:85]
	v_mfma_f32_16x16x32_bf16 v[70:73], v[186:189], v[236:239], v[70:73]
	v_mfma_f32_16x16x32_bf16 v[66:69], v[194:197], v[236:239], v[66:69]
	s_setprio 0
	s_barrier
; #define PG8_STAGE(bufoff, gbase, voff) do { _Pragma("unroll") for (int _i = 0; _i < 2; ++_i) \
;         __builtin_amdgcn_global_load_lds((const unsigned*)((const char*)(gbase) + (voff)[_i]), (LAS unsigned*)(lds + (bufoff) + ldsw + _i * 8192), 16, 0, 0); } while (0)
; #define PG8_LDA(dst, b, h) do { _Pragma("unroll") for (int m = 0; m < 4; ++m) _Pragma("unroll") for (int k = 0; k < 2; ++k) dst[m][k] = *(const LAS bf16x8*)(lds + PG8_SA(b, h) + aoff + m * 2048 + k * 1024); } while (0)
; #define PG8_MMA(ai, bj, At, Bt) do { __builtin_amdgcn_s_setprio(1); _Pragma("unroll") for (int m = 0; m < 4; ++m) _Pragma("unroll") for (int n = 0; n < 2; ++n) _Pragma("unroll") for (int k = 0; k < 2; ++k) \
;         acc[ai][bj][m][n] = __builtin_amdgcn_mfma_f32_16x16x32_bf16(Bt[n][k], At[m][k], acc[ai][bj][m][n], 0, 0, 0); __builtin_amdgcn_s_setprio(0); } while (0)
; #define PG8_WAIT_V(n) asm volatile("s_waitcnt vmcnt(" #n ")" ::: "memory")
; #define PG8_WAIT_L(n) asm volatile("s_waitcnt lgkmcnt(" #n ")" ::: "memory")
; #define PG8_BAR __builtin_amdgcn_s_barrier()
; #define PG8_SCHED __builtin_amdgcn_sched_barrier(0)
; template <class Epi>
; __device__ __forceinline__ void gemm_phase(LAS unsigned char* lds, const Gemm g, const StaticOrder& S, const Epi& E, const int tid) {
;     ...
;             PG8_LDA(At, 1, 1); PG8_STAGE(PG8_SB(1, 0), b3, voffB); PG8_STAGE(PG8_SB(1, 1), b3 + bhs, voffB); PG8_STAGE(PG8_SA(1, 0), a3, voffA);
;             PG8_WAIT_V(8); PG8_WAIT_L(0); PG8_BAR; PG8_MMA(1, 0, At, B0); PG8_MMA(1, 1, At, B1); PG8_BAR; PG8_SCHED;
;     ...
;         if (ALIGN_EPI) { if (wr == 0) PG8_BAR; }
	ds_read_b128 v[198:201], v154 offset:49152
	global_load_lds_dwordx4 v[142:143], off
	ds_read_b128 v[212:215], v154 offset:50176
	ds_read_b128 v[216:219], v154 offset:51200
	s_add_i32 m0, s30, 0x2000
	s_add_u32 s28, s28, 0x8080
	v_lshl_add_u64 v[142:143], v[168:169], 0, s[70:71]
	s_addc_u32 s29, s29, 0
	s_add_i32 s30, s48, s34
	global_load_lds_dwordx4 v[142:143], off
	ds_read_b128 v[220:223], v154 offset:52224
	ds_read_b128 v[224:227], v154 offset:53248
	v_lshl_add_u64 v[142:143], s[28:29], 0, v[0:1]
	s_mov_b32 m0, s30
	s_nop 0
	global_load_lds_dwordx4 v[142:143], off
	ds_read_b128 v[228:231], v154 offset:54272
	ds_read_b128 v[232:235], v154 offset:55296
	v_lshl_add_u64 v[142:143], s[28:29], 0, v[134:135]
	s_add_i32 m0, s30, 0x2000
	s_nop 0
	global_load_lds_dwordx4 v[142:143], off
	ds_read_b128 v[236:239], v154 offset:56320
	v_lshl_add_u64 v[142:143], v[172:173], 0, s[70:71]
	s_mov_b32 m0, s37
	s_nop 0
	global_load_lds_dwordx4 v[142:143], off
	v_lshl_add_u64 v[142:143], v[174:175], 0, s[70:71]
	s_mov_b32 m0, s38
	s_nop 0
	global_load_lds_dwordx4 v[142:143], off
	s_waitcnt vmcnt(8)
	s_waitcnt lgkmcnt(0)
	s_barrier
	s_setprio 1
	s_waitcnt lgkmcnt(0)
	v_mfma_f32_16x16x32_bf16 v[62:65], v[156:159], v[198:201], v[62:65]
	v_mfma_f32_16x16x32_bf16 v[58:61], v[164:167], v[198:201], v[58:61]
	s_add_i32 s46, s46, 2
	v_mfma_f32_16x16x32_bf16 v[46:49], v[156:159], v[216:219], v[46:49]
	s_add_u32 s44, s44, 0x100
	v_mfma_f32_16x16x32_bf16 v[42:45], v[164:167], v[216:219], v[42:45]
	s_addc_u32 s45, s45, 0
	v_mfma_f32_16x16x32_bf16 v[30:33], v[156:159], v[224:227], v[30:33]
	s_add_u32 s26, s26, 0x100
	v_mfma_f32_16x16x32_bf16 v[26:29], v[164:167], v[224:227], v[26:29]
	s_addc_u32 s27, s27, 0
	v_mfma_f32_16x16x32_bf16 v[14:17], v[156:159], v[232:235], v[14:17]
	v_mfma_f32_16x16x32_bf16 v[10:13], v[164:167], v[232:235], v[10:13]
	v_mfma_f32_16x16x32_bf16 v[62:65], v[160:163], v[212:215], v[62:65]
	v_mfma_f32_16x16x32_bf16 v[58:61], v[178:181], v[212:215], v[58:61]
	v_mfma_f32_16x16x32_bf16 v[46:49], v[160:163], v[220:223], v[46:49]
	v_mfma_f32_16x16x32_bf16 v[42:45], v[178:181], v[220:223], v[42:45]
	v_mfma_f32_16x16x32_bf16 v[30:33], v[160:163], v[228:231], v[30:33]
	v_mfma_f32_16x16x32_bf16 v[26:29], v[178:181], v[228:231], v[26:29]
	v_mfma_f32_16x16x32_bf16 v[14:17], v[160:163], v[236:239], v[14:17]
	v_mfma_f32_16x16x32_bf16 v[10:13], v[178:181], v[236:239], v[10:13]
	s_setprio 0
	s_setprio 1
	v_mfma_f32_16x16x32_bf16 v[54:57], v[182:185], v[198:201], v[54:57]
	v_mfma_f32_16x16x32_bf16 v[50:53], v[190:193], v[198:201], v[50:53]
	v_mfma_f32_16x16x32_bf16 v[38:41], v[182:185], v[216:219], v[38:41]
	v_mfma_f32_16x16x32_bf16 v[34:37], v[190:193], v[216:219], v[34:37]
	v_mfma_f32_16x16x32_bf16 v[22:25], v[182:185], v[224:227], v[22:25]
	v_mfma_f32_16x16x32_bf16 v[18:21], v[190:193], v[224:227], v[18:21]
	v_mfma_f32_16x16x32_bf16 v[6:9], v[182:185], v[232:235], v[6:9]
	v_mfma_f32_16x16x32_bf16 v[2:5], v[190:193], v[232:235], v[2:5]
	v_mfma_f32_16x16x32_bf16 v[54:57], v[186:189], v[212:215], v[54:57]
	v_mfma_f32_16x16x32_bf16 v[50:53], v[194:197], v[212:215], v[50:53]
	v_mfma_f32_16x16x32_bf16 v[38:41], v[186:189], v[220:223], v[38:41]
	v_mfma_f32_16x16x32_bf16 v[34:37], v[194:197], v[220:223], v[34:37]
	v_mfma_f32_16x16x32_bf16 v[22:25], v[186:189], v[228:231], v[22:25]
	v_mfma_f32_16x16x32_bf16 v[18:21], v[194:197], v[228:231], v[18:21]
	v_mfma_f32_16x16x32_bf16 v[6:9], v[186:189], v[236:239], v[6:9]
	v_mfma_f32_16x16x32_bf16 v[2:5], v[194:197], v[236:239], v[2:5]
	s_setprio 0
	s_barrier
	s_cmp_gt_u32 s46, 29
	s_cbranch_scc0 .LBB0_173
	v_readlane_b32 s42, v251, 53
	s_and_b64 vcc, exec, s[12:13]
	v_readlane_b32 s43, v251, 54
	s_cbranch_vccz .LBB0_176
	s_barrier

; #define PG8_STAGE(bufoff, gbase, voff) do { _Pragma("unroll") for (int _i = 0; _i < 2; ++_i) \
;         __builtin_amdgcn_global_load_lds((const unsigned*)((const char*)(gbase) + (voff)[_i]), (LAS unsigned*)(lds + (bufoff) + ldsw + _i * 8192), 16, 0, 0); } while (0)
; #define PG8_LDA(dst, b, h) do { _Pragma("unroll") for (int m = 0; m < 4; ++m) _Pragma("unroll") for (int k = 0; k < 2; ++k) dst[m][k] = *(const LAS bf16x8*)(lds + PG8_SA(b, h) + aoff + m * 2048 + k * 1024); } while (0)
; #define PG8_LDB(dst, b, h) do { _Pragma("unroll") for (int n = 0; n < 2; ++n) _Pragma("unroll") for (int k = 0; k < 2; ++k) dst[n][k] = *(const LAS bf16x8*)(lds + PG8_SB(b, h) + boff + n * 2048 + k * 1024); } while (0)
; #define PG8_WAIT_V(n) asm volatile("s_waitcnt vmcnt(" #n ")" ::: "memory")
; #define PG8_WAIT_L(n) asm volatile("s_waitcnt lgkmcnt(" #n ")" ::: "memory")
; #define PG8_BAR __builtin_amdgcn_s_barrier()
; #define PG8_SCHED __builtin_amdgcn_sched_barrier(0)
; template <class Epi>
; __device__ __forceinline__ void gemm_phase(LAS unsigned char* lds, const Gemm g, const StaticOrder& S, const Epi& E, const int tid) {
;     ...
;             const bool last = (t == ntt - 2);
;             const bool s1 = Epi::TWO && (t >= nt), s2 = Epi::TWO && (t + 2 >= nt);
;             const char* a1 = (s1 ? cA2 + (size_t)(t - nt + 1) * kstep : cA + (size_t)(t + 1) * kstep);
;             const char* a2 = last ? nA : (s2 ? cA2 + (size_t)(t + 2 - nt) * kstep : cA + (size_t)(t + 2) * kstep);
;             const char* b2 = last ? nB : (s2 ? cB2 + (size_t)(t + 2 - nt) * kstep : cB + (size_t)(t + 2) * kstep);
;             const char* a3 = a2 + kstep; const char* b3 = b2 + kstep;
;             if constexpr (Epi::TWO) { if (t == nt) E.mid(acc, cur, wr, wc, fr, fq); }
;             if constexpr (SP2) {
;             PG8_LDB(B0, 0, 0); PG8_LDB(B1, 0, 1); PG8_SCHED; PG8_LDA(At, 0, 0); PG8_STAGE(PG8_SA(1, 1), a1 + hstep, voffA);
;             PG8_WAIT_V(8); PG8_WAIT_L(0); PG8_BAR; PG8_MMA(0, 0, At, B0); PG8_MMA(0, 1, At, B1); PG8_BAR; PG8_SCHED;
;             PG8_LDA(At, 0, 1); PG8_STAGE(PG8_SB(0, 0), b2, voffB); PG8_STAGE(PG8_SB(0, 1), b2 + bhs, voffB); PG8_STAGE(PG8_SA(0, 0), a2, voffA);
;             PG8_WAIT_V(8); PG8_WAIT_L(0); PG8_BAR; PG8_MMA(1, 0, At, B0); PG8_MMA(1, 1, At, B1); PG8_BAR; PG8_SCHED;
.LBB0_206:
	s_add_u32 s30, s28, 0xfffe0080
	s_addc_u32 s31, s29, -1
	s_add_i32 s52, 0, 0x10000
	s_cmp_eq_u32 s51, 4
	s_cselect_b32 s35, s17, s31
	s_cselect_b32 s34, s27, s30
	s_cselect_b32 s31, s15, s50
	s_cselect_b32 s30, s33, s49
	s_add_i32 s54, 0, 0x14000
	v_add_u32_e32 v30, s52, v193
	v_add_u32_e32 v54, s54, v193
	ds_read_b128 v[18:21], v30
	ds_read_b128 v[22:25], v30 offset:1024
	ds_read_b128 v[26:29], v30 offset:2048
	ds_read_b128 v[30:33], v30 offset:3072
	ds_read_b128 v[42:45], v54
	ds_read_b128 v[46:49], v54 offset:1024
	ds_read_b128 v[50:53], v54 offset:2048
	ds_read_b128 v[54:57], v54 offset:3072
	v_lshl_add_u64 v[172:173], s[28:29], 0, v[180:181]
	s_add_i32 m0, s37, 0xc000
	ds_read_b128 v[182:185], v199
	global_load_lds_dwordx4 v[172:173], off
	ds_read_b128 v[186:189], v199 offset:1024
	ds_read_b128 v[212:215], v199 offset:2048
	v_lshl_add_u64 v[172:173], s[28:29], 0, v[178:179]
	s_add_i32 m0, s37, 0xe000
	s_nop 0
	global_load_lds_dwordx4 v[172:173], off
	ds_read_b128 v[216:219], v199 offset:3072
	ds_read_b128 v[220:223], v199 offset:4096
	ds_read_b128 v[224:227], v199 offset:5120
	ds_read_b128 v[228:231], v199 offset:6144
	ds_read_b128 v[232:235], v199 offset:7168
	s_waitcnt vmcnt(8)
	s_waitcnt lgkmcnt(0)
	s_barrier
	s_setprio 1
	s_waitcnt lgkmcnt(0)
	v_mfma_f32_16x16x32_bf16 v[158:161], v[18:21], v[182:185], v[158:161]
	v_mfma_f32_16x16x32_bf16 v[154:157], v[26:29], v[182:185], v[154:157]
	s_add_i32 s52, s52, s36
	v_mfma_f32_16x16x32_bf16 v[142:145], v[18:21], v[212:215], v[142:145]
	v_lshl_add_u64 v[172:173], s[30:31], 0, v[0:1]
	v_mfma_f32_16x16x32_bf16 v[138:141], v[26:29], v[212:215], v[138:141]
	s_mov_b32 m0, s52
	v_mfma_f32_16x16x32_bf16 v[126:129], v[18:21], v[220:223], v[126:129]
	v_mfma_f32_16x16x32_bf16 v[122:125], v[26:29], v[220:223], v[122:125]
	v_mfma_f32_16x16x32_bf16 v[110:113], v[18:21], v[228:231], v[110:113]
	v_mfma_f32_16x16x32_bf16 v[106:109], v[26:29], v[228:231], v[106:109]
	v_mfma_f32_16x16x32_bf16 v[158:161], v[22:25], v[186:189], v[158:161]
	v_mfma_f32_16x16x32_bf16 v[154:157], v[30:33], v[186:189], v[154:157]
	v_mfma_f32_16x16x32_bf16 v[142:145], v[22:25], v[216:219], v[142:145]
	v_mfma_f32_16x16x32_bf16 v[138:141], v[30:33], v[216:219], v[138:141]
	v_mfma_f32_16x16x32_bf16 v[126:129], v[22:25], v[224:227], v[126:129]
	v_mfma_f32_16x16x32_bf16 v[122:125], v[30:33], v[224:227], v[122:125]
	v_mfma_f32_16x16x32_bf16 v[110:113], v[22:25], v[232:235], v[110:113]
	v_mfma_f32_16x16x32_bf16 v[106:109], v[30:33], v[232:235], v[106:109]
	s_setprio 0
	s_setprio 1
	v_mfma_f32_16x16x32_bf16 v[150:153], v[42:45], v[182:185], v[150:153]
	v_mfma_f32_16x16x32_bf16 v[146:149], v[50:53], v[182:185], v[146:149]
	v_mfma_f32_16x16x32_bf16 v[134:137], v[42:45], v[212:215], v[134:137]
	v_mfma_f32_16x16x32_bf16 v[130:133], v[50:53], v[212:215], v[130:133]
	v_mfma_f32_16x16x32_bf16 v[118:121], v[42:45], v[220:223], v[118:121]
	v_mfma_f32_16x16x32_bf16 v[114:117], v[50:53], v[220:223], v[114:117]
	v_mfma_f32_16x16x32_bf16 v[102:105], v[42:45], v[228:231], v[102:105]
	v_mfma_f32_16x16x32_bf16 v[98:101], v[50:53], v[228:231], v[98:101]
	v_mfma_f32_16x16x32_bf16 v[150:153], v[46:49], v[186:189], v[150:153]
	v_mfma_f32_16x16x32_bf16 v[146:149], v[54:57], v[186:189], v[146:149]
	v_mfma_f32_16x16x32_bf16 v[134:137], v[46:49], v[216:219], v[134:137]
	v_mfma_f32_16x16x32_bf16 v[130:133], v[54:57], v[216:219], v[130:133]
	v_mfma_f32_16x16x32_bf16 v[118:121], v[46:49], v[224:227], v[118:121]
	v_mfma_f32_16x16x32_bf16 v[114:117], v[54:57], v[224:227], v[114:117]
	v_mfma_f32_16x16x32_bf16 v[102:105], v[46:49], v[232:235], v[102:105]
	v_mfma_f32_16x16x32_bf16 v[98:101], v[54:57], v[232:235], v[98:101]
	s_setprio 0
	s_barrier
	ds_read_b128 v[182:185], v199 offset:16384
	global_load_lds_dwordx4 v[172:173], off
	ds_read_b128 v[186:189], v199 offset:17408
	ds_read_b128 v[212:215], v199 offset:18432
	s_add_i32 m0, s52, 0x2000
	s_add_u32 s52, s30, 0x2000
	v_lshl_add_u64 v[174:175], s[30:31], 0, v[166:167]
	s_addc_u32 s53, s31, 0
	s_add_i32 s54, s54, s36
	global_load_lds_dwordx4 v[174:175], off
	ds_read_b128 v[216:219], v199 offset:19456
	ds_read_b128 v[220:223], v199 offset:20480
	v_lshl_add_u64 v[176:177], s[52:53], 0, v[0:1]
	s_mov_b32 m0, s54
	v_lshl_add_u64 v[200:201], s[34:35], 0, v[164:165]
	global_load_lds_dwordx4 v[176:177], off
	ds_read_b128 v[224:227], v199 offset:21504
	ds_read_b128 v[228:231], v199 offset:22528
	v_lshl_add_u64 v[176:177], s[52:53], 0, v[166:167]
	s_add_i32 m0, s54, 0x2000
	s_nop 0
	global_load_lds_dwordx4 v[176:177], off
	ds_read_b128 v[232:235], v199 offset:23552
	v_lshl_add_u64 v[176:177], s[34:35], 0, v[162:163]
	s_mov_b32 m0, s37
	s_nop 0
	global_load_lds_dwordx4 v[176:177], off
	s_mov_b32 m0, s38
	s_nop 0
	global_load_lds_dwordx4 v[200:201], off
	s_waitcnt vmcnt(8)
	s_waitcnt lgkmcnt(0)
	s_barrier
; #define PG8_STAGE(bufoff, gbase, voff) do { _Pragma("unroll") for (int _i = 0; _i < 2; ++_i) \
;         __builtin_amdgcn_global_load_lds((const unsigned*)((const char*)(gbase) + (voff)[_i]), (LAS unsigned*)(lds + (bufoff) + ldsw + _i * 8192), 16, 0, 0); } while (0)
; #define PG8_LDA(dst, b, h) do { _Pragma("unroll") for (int m = 0; m < 4; ++m) _Pragma("unroll") for (int k = 0; k < 2; ++k) dst[m][k] = *(const LAS bf16x8*)(lds + PG8_SA(b, h) + aoff + m * 2048 + k * 1024); } while (0)
; #define PG8_LDB(dst, b, h) do { _Pragma("unroll") for (int n = 0; n < 2; ++n) _Pragma("unroll") for (int k = 0; k < 2; ++k) dst[n][k] = *(const LAS bf16x8*)(lds + PG8_SB(b, h) + boff + n * 2048 + k * 1024); } while (0)
; #define PG8_MMA(ai, bj, At, Bt) do { __builtin_amdgcn_s_setprio(1); _Pragma("unroll") for (int m = 0; m < 4; ++m) _Pragma("unroll") for (int n = 0; n < 2; ++n) _Pragma("unroll") for (int k = 0; k < 2; ++k) \
;         acc[ai][bj][m][n] = __builtin_amdgcn_mfma_f32_16x16x32_bf16(Bt[n][k], At[m][k], acc[ai][bj][m][n], 0, 0, 0); __builtin_amdgcn_s_setprio(0); } while (0)
; #define PG8_WAIT_V(n) asm volatile("s_waitcnt vmcnt(" #n ")" ::: "memory")
; #define PG8_WAIT_L(n) asm volatile("s_waitcnt lgkmcnt(" #n ")" ::: "memory")
; #define PG8_BAR __builtin_amdgcn_s_barrier()
; #define PG8_SCHED __builtin_amdgcn_sched_barrier(0)
; template <class Epi>
; __device__ __forceinline__ void gemm_phase(LAS unsigned char* lds, const Gemm g, const StaticOrder& S, const Epi& E, const int tid) {
;     ...
;             PG8_WAIT_V(8); PG8_WAIT_L(0); PG8_BAR; PG8_MMA(1, 0, At, B0); PG8_MMA(1, 1, At, B1); PG8_BAR; PG8_SCHED;
;             PG8_LDB(B0, 1, 0); PG8_LDB(B1, 1, 1); PG8_SCHED; PG8_LDA(At, 1, 0); PG8_STAGE(PG8_SA(0, 1), a2 + hstep, voffA);
;             PG8_WAIT_V(8); PG8_WAIT_L(0); PG8_BAR; PG8_MMA(0, 0, At, B0); PG8_MMA(0, 1, At, B1); PG8_BAR; PG8_SCHED;
	s_setprio 1
	s_waitcnt lgkmcnt(0)
	v_mfma_f32_16x16x32_bf16 v[94:97], v[18:21], v[182:185], v[94:97]
	v_mfma_f32_16x16x32_bf16 v[90:93], v[26:29], v[182:185], v[90:93]
	s_add_i32 s52, 0, 0x18000
	v_mfma_f32_16x16x32_bf16 v[78:81], v[18:21], v[212:215], v[78:81]
	s_add_i32 s53, 0, 0x1c000
	v_mfma_f32_16x16x32_bf16 v[74:77], v[26:29], v[212:215], v[74:77]
	v_mfma_f32_16x16x32_bf16 v[62:65], v[18:21], v[220:223], v[62:65]
	v_mfma_f32_16x16x32_bf16 v[58:61], v[26:29], v[220:223], v[58:61]
	v_mfma_f32_16x16x32_bf16 v[14:17], v[18:21], v[228:231], v[14:17]
	v_mfma_f32_16x16x32_bf16 v[10:13], v[26:29], v[228:231], v[10:13]
	v_mfma_f32_16x16x32_bf16 v[94:97], v[22:25], v[186:189], v[94:97]
	v_mfma_f32_16x16x32_bf16 v[90:93], v[30:33], v[186:189], v[90:93]
	v_mfma_f32_16x16x32_bf16 v[78:81], v[22:25], v[216:219], v[78:81]
	v_mfma_f32_16x16x32_bf16 v[74:77], v[30:33], v[216:219], v[74:77]
	v_mfma_f32_16x16x32_bf16 v[62:65], v[22:25], v[224:227], v[62:65]
	v_mfma_f32_16x16x32_bf16 v[58:61], v[30:33], v[224:227], v[58:61]
	v_mfma_f32_16x16x32_bf16 v[14:17], v[22:25], v[232:235], v[14:17]
	v_mfma_f32_16x16x32_bf16 v[10:13], v[30:33], v[232:235], v[10:13]
	s_setprio 0
	s_setprio 1
	v_mfma_f32_16x16x32_bf16 v[38:41], v[42:45], v[220:223], v[38:41]
	v_mfma_f32_16x16x32_bf16 v[34:37], v[50:53], v[220:223], v[34:37]
	v_mfma_f32_16x16x32_bf16 v[6:9], v[42:45], v[228:231], v[6:9]
	v_mfma_f32_16x16x32_bf16 v[2:5], v[50:53], v[228:231], v[2:5]
	v_mfma_f32_16x16x32_bf16 v[18:21], v[42:45], v[182:185], v[86:89]
	v_mfma_f32_16x16x32_bf16 v[22:25], v[50:53], v[182:185], v[82:85]
	v_mfma_f32_16x16x32_bf16 v[26:29], v[42:45], v[212:215], v[70:73]
	v_mfma_f32_16x16x32_bf16 v[30:33], v[50:53], v[212:215], v[66:69]
	v_mfma_f32_16x16x32_bf16 v[38:41], v[46:49], v[224:227], v[38:41]
	v_mfma_f32_16x16x32_bf16 v[34:37], v[54:57], v[224:227], v[34:37]
	v_mfma_f32_16x16x32_bf16 v[6:9], v[46:49], v[232:235], v[6:9]
	v_mfma_f32_16x16x32_bf16 v[2:5], v[54:57], v[232:235], v[2:5]
	v_mfma_f32_16x16x32_bf16 v[18:21], v[46:49], v[186:189], v[18:21]
	v_mfma_f32_16x16x32_bf16 v[22:25], v[54:57], v[186:189], v[22:25]
	v_mfma_f32_16x16x32_bf16 v[26:29], v[46:49], v[216:219], v[26:29]
	v_mfma_f32_16x16x32_bf16 v[30:33], v[54:57], v[216:219], v[30:33]
	s_setprio 0
	s_barrier
	v_add_u32_e32 v54, s52, v193
	v_add_u32_e32 v66, s53, v193
	ds_read_b128 v[42:45], v54
	ds_read_b128 v[46:49], v54 offset:1024
	ds_read_b128 v[50:53], v54 offset:2048
	ds_read_b128 v[54:57], v54 offset:3072
	ds_read_b128 v[182:185], v66
	ds_read_b128 v[186:189], v66 offset:1024
	ds_read_b128 v[212:215], v66 offset:2048
	ds_read_b128 v[216:219], v66 offset:3072
	s_add_u32 s34, s34, 0x20000
	s_addc_u32 s35, s35, 0
	s_mov_b32 m0, s39
	v_lshl_add_u64 v[236:237], s[34:35], 0, v[162:163]
	ds_read_b128 v[66:69], v199 offset:32768
	global_load_lds_dwordx4 v[236:237], off
	ds_read_b128 v[70:73], v199 offset:33792
	ds_read_b128 v[82:85], v199 offset:34816
	v_lshl_add_u64 v[236:237], s[34:35], 0, v[164:165]
	s_mov_b32 m0, s44
	s_nop 0
	global_load_lds_dwordx4 v[236:237], off
	ds_read_b128 v[86:89], v199 offset:35840
	ds_read_b128 v[220:223], v199 offset:36864
	ds_read_b128 v[224:227], v199 offset:37888
	ds_read_b128 v[228:231], v199 offset:38912
	ds_read_b128 v[232:235], v199 offset:39936
	s_waitcnt vmcnt(8)
	s_waitcnt lgkmcnt(0)
	s_barrier
	s_setprio 1
	s_waitcnt lgkmcnt(0)
	v_mfma_f32_16x16x32_bf16 v[158:161], v[42:45], v[66:69], v[158:161]
	v_mfma_f32_16x16x32_bf16 v[154:157], v[50:53], v[66:69], v[154:157]
	v_mfma_f32_16x16x32_bf16 v[142:145], v[42:45], v[82:85], v[142:145]
	v_mfma_f32_16x16x32_bf16 v[138:141], v[50:53], v[82:85], v[138:141]
	v_mfma_f32_16x16x32_bf16 v[126:129], v[42:45], v[220:223], v[126:129]
	v_mfma_f32_16x16x32_bf16 v[122:125], v[50:53], v[220:223], v[122:125]
	v_mfma_f32_16x16x32_bf16 v[110:113], v[42:45], v[228:231], v[110:113]
	v_mfma_f32_16x16x32_bf16 v[106:109], v[50:53], v[228:231], v[106:109]
	v_mfma_f32_16x16x32_bf16 v[158:161], v[46:49], v[70:73], v[158:161]
	v_mfma_f32_16x16x32_bf16 v[154:157], v[54:57], v[70:73], v[154:157]
	v_mfma_f32_16x16x32_bf16 v[142:145], v[46:49], v[86:89], v[142:145]
	v_mfma_f32_16x16x32_bf16 v[138:141], v[54:57], v[86:89], v[138:141]
	v_mfma_f32_16x16x32_bf16 v[126:129], v[46:49], v[224:227], v[126:129]
	v_mfma_f32_16x16x32_bf16 v[122:125], v[54:57], v[224:227], v[122:125]
	v_mfma_f32_16x16x32_bf16 v[110:113], v[46:49], v[232:235], v[110:113]
	v_mfma_f32_16x16x32_bf16 v[106:109], v[54:57], v[232:235], v[106:109]
	s_setprio 0
	s_setprio 1
	v_mfma_f32_16x16x32_bf16 v[150:153], v[182:185], v[66:69], v[150:153]
	v_mfma_f32_16x16x32_bf16 v[66:69], v[212:215], v[66:69], v[146:149]
	v_mfma_f32_16x16x32_bf16 v[146:149], v[216:219], v[70:73], v[66:69]
	v_mfma_f32_16x16x32_bf16 v[66:69], v[182:185], v[82:85], v[134:137]
	v_mfma_f32_16x16x32_bf16 v[134:137], v[186:189], v[86:89], v[66:69]
	v_mfma_f32_16x16x32_bf16 v[66:69], v[212:215], v[82:85], v[130:133]
	v_mfma_f32_16x16x32_bf16 v[130:133], v[216:219], v[86:89], v[66:69]
	v_mfma_f32_16x16x32_bf16 v[66:69], v[182:185], v[220:223], v[118:121]
	v_mfma_f32_16x16x32_bf16 v[118:121], v[186:189], v[224:227], v[66:69]
	v_mfma_f32_16x16x32_bf16 v[66:69], v[212:215], v[220:223], v[114:117]
	v_mfma_f32_16x16x32_bf16 v[114:117], v[216:219], v[224:227], v[66:69]
	v_mfma_f32_16x16x32_bf16 v[66:69], v[182:185], v[228:231], v[102:105]
	v_mfma_f32_16x16x32_bf16 v[102:105], v[186:189], v[232:235], v[66:69]
	v_mfma_f32_16x16x32_bf16 v[66:69], v[212:215], v[228:231], v[98:101]
	v_mfma_f32_16x16x32_bf16 v[150:153], v[186:189], v[70:73], v[150:153]
	v_mfma_f32_16x16x32_bf16 v[98:101], v[216:219], v[232:235], v[66:69]
	s_setprio 0
	s_barrier
; #define PG8_STAGE(bufoff, gbase, voff) do { _Pragma("unroll") for (int _i = 0; _i < 2; ++_i) \
;         __builtin_amdgcn_global_load_lds((const unsigned*)((const char*)(gbase) + (voff)[_i]), (LAS unsigned*)(lds + (bufoff) + ldsw + _i * 8192), 16, 0, 0); } while (0)
; #define PG8_LDA(dst, b, h) do { _Pragma("unroll") for (int m = 0; m < 4; ++m) _Pragma("unroll") for (int k = 0; k < 2; ++k) dst[m][k] = *(const LAS bf16x8*)(lds + PG8_SA(b, h) + aoff + m * 2048 + k * 1024); } while (0)
; #define PG8_MMA(ai, bj, At, Bt) do { __builtin_amdgcn_s_setprio(1); _Pragma("unroll") for (int m = 0; m < 4; ++m) _Pragma("unroll") for (int n = 0; n < 2; ++n) _Pragma("unroll") for (int k = 0; k < 2; ++k) \
;         acc[ai][bj][m][n] = __builtin_amdgcn_mfma_f32_16x16x32_bf16(Bt[n][k], At[m][k], acc[ai][bj][m][n], 0, 0, 0); __builtin_amdgcn_s_setprio(0); } while (0)
; #define PG8_WAIT_V(n) asm volatile("s_waitcnt vmcnt(" #n ")" ::: "memory")
; #define PG8_WAIT_L(n) asm volatile("s_waitcnt lgkmcnt(" #n ")" ::: "memory")
; #define PG8_BAR __builtin_amdgcn_s_barrier()
; #define PG8_SCHED __builtin_amdgcn_sched_barrier(0)
; template <class Epi>
; __device__ __forceinline__ void gemm_phase(LAS unsigned char* lds, const Gemm g, const StaticOrder& S, const Epi& E, const int tid) {
;     ...
;             PG8_LDA(At, 1, 1); PG8_STAGE(PG8_SB(1, 0), b3, voffB); PG8_STAGE(PG8_SB(1, 1), b3 + bhs, voffB); PG8_STAGE(PG8_SA(1, 0), a3, voffA);
;             PG8_WAIT_V(8); PG8_WAIT_L(0); PG8_BAR; PG8_MMA(1, 0, At, B0); PG8_MMA(1, 1, At, B1); PG8_BAR; PG8_SCHED;
;     ...
;         if (ALIGN_EPI) { if (wr == 0) PG8_BAR; }
	s_add_i32 s34, s52, s36
	v_lshl_add_u64 v[82:83], v[172:173], 0, s[70:71]
	s_mov_b32 m0, s34
	s_nop 0
	ds_read_b128 v[66:69], v199 offset:49152
	global_load_lds_dwordx4 v[82:83], off
	ds_read_b128 v[70:73], v199 offset:50176
	ds_read_b128 v[220:223], v199 offset:51200
	s_add_i32 m0, s34, 0x2000
	s_add_u32 s30, s30, 0x2080
	v_lshl_add_u64 v[82:83], v[174:175], 0, s[70:71]
	s_addc_u32 s31, s31, 0
	s_add_i32 s34, s53, s36
	global_load_lds_dwordx4 v[82:83], off
	ds_read_b128 v[224:227], v199 offset:52224
	ds_read_b128 v[228:231], v199 offset:53248
	v_lshl_add_u64 v[82:83], s[30:31], 0, v[0:1]
	s_mov_b32 m0, s34
	s_nop 0
	global_load_lds_dwordx4 v[82:83], off
	ds_read_b128 v[232:235], v199 offset:54272
	ds_read_b128 v[236:239], v199 offset:55296
	v_lshl_add_u64 v[82:83], s[30:31], 0, v[166:167]
	s_add_i32 m0, s34, 0x2000
	s_nop 0
	global_load_lds_dwordx4 v[82:83], off
	ds_read_b128 v[240:243], v199 offset:56320
	v_lshl_add_u64 v[82:83], v[176:177], 0, s[70:71]
	s_mov_b32 m0, s45
	s_nop 0
	global_load_lds_dwordx4 v[82:83], off
	v_lshl_add_u64 v[82:83], v[200:201], 0, s[70:71]
	s_mov_b32 m0, s46
	s_nop 0
	global_load_lds_dwordx4 v[82:83], off
	s_waitcnt vmcnt(8)
	s_waitcnt lgkmcnt(0)
	s_barrier
	s_setprio 1
	s_waitcnt lgkmcnt(0)
	v_mfma_f32_16x16x32_bf16 v[82:85], v[42:45], v[66:69], v[94:97]
	v_mfma_f32_16x16x32_bf16 v[94:97], v[46:49], v[70:73], v[82:85]
	s_add_i32 s51, s51, 2
	v_mfma_f32_16x16x32_bf16 v[82:85], v[50:53], v[66:69], v[90:93]
	s_add_u32 s49, s49, 0x100
	v_mfma_f32_16x16x32_bf16 v[78:81], v[42:45], v[220:223], v[78:81]
	s_addc_u32 s50, s50, 0
	v_mfma_f32_16x16x32_bf16 v[74:77], v[50:53], v[220:223], v[74:77]
	s_add_u32 s28, s28, 0x100
	v_mfma_f32_16x16x32_bf16 v[62:65], v[42:45], v[228:231], v[62:65]
	s_addc_u32 s29, s29, 0
	v_mfma_f32_16x16x32_bf16 v[58:61], v[50:53], v[228:231], v[58:61]
	v_mfma_f32_16x16x32_bf16 v[14:17], v[42:45], v[236:239], v[14:17]
	v_mfma_f32_16x16x32_bf16 v[10:13], v[50:53], v[236:239], v[10:13]
	v_mfma_f32_16x16x32_bf16 v[90:93], v[54:57], v[70:73], v[82:85]
	v_mfma_f32_16x16x32_bf16 v[78:81], v[46:49], v[224:227], v[78:81]
	v_mfma_f32_16x16x32_bf16 v[74:77], v[54:57], v[224:227], v[74:77]
	v_mfma_f32_16x16x32_bf16 v[62:65], v[46:49], v[232:235], v[62:65]
	v_mfma_f32_16x16x32_bf16 v[58:61], v[54:57], v[232:235], v[58:61]
	v_mfma_f32_16x16x32_bf16 v[14:17], v[46:49], v[240:243], v[14:17]
	v_mfma_f32_16x16x32_bf16 v[10:13], v[54:57], v[240:243], v[10:13]
	s_setprio 0
	s_setprio 1
	v_mfma_f32_16x16x32_bf16 v[18:21], v[182:185], v[66:69], v[18:21]
	v_mfma_f32_16x16x32_bf16 v[86:89], v[186:189], v[70:73], v[18:21]
	v_mfma_f32_16x16x32_bf16 v[18:21], v[212:215], v[66:69], v[22:25]
	v_mfma_f32_16x16x32_bf16 v[82:85], v[216:219], v[70:73], v[18:21]
	v_mfma_f32_16x16x32_bf16 v[18:21], v[182:185], v[220:223], v[26:29]
	v_mfma_f32_16x16x32_bf16 v[70:73], v[186:189], v[224:227], v[18:21]
	v_mfma_f32_16x16x32_bf16 v[18:21], v[212:215], v[220:223], v[30:33]
	v_mfma_f32_16x16x32_bf16 v[66:69], v[216:219], v[224:227], v[18:21]
	v_mfma_f32_16x16x32_bf16 v[18:21], v[182:185], v[228:231], v[38:41]
	v_mfma_f32_16x16x32_bf16 v[38:41], v[186:189], v[232:235], v[18:21]
	v_mfma_f32_16x16x32_bf16 v[18:21], v[212:215], v[228:231], v[34:37]
	v_mfma_f32_16x16x32_bf16 v[6:9], v[182:185], v[236:239], v[6:9]
	v_mfma_f32_16x16x32_bf16 v[2:5], v[212:215], v[236:239], v[2:5]
	v_mfma_f32_16x16x32_bf16 v[34:37], v[216:219], v[232:235], v[18:21]
	v_mfma_f32_16x16x32_bf16 v[6:9], v[186:189], v[240:243], v[6:9]
	v_mfma_f32_16x16x32_bf16 v[2:5], v[216:219], v[240:243], v[2:5]
	s_setprio 0
	s_barrier
	s_cmp_gt_u32 s51, 5
	s_cbranch_scc0 .LBB0_206
	s_and_b64 vcc, exec, s[12:13]
	s_cbranch_vccz .LBB0_209
	s_barrier

; #define PG8_STAGE(bufoff, gbase, voff) do { _Pragma("unroll") for (int _i = 0; _i < 2; ++_i) \
;         __builtin_amdgcn_global_load_lds((const unsigned*)((const char*)(gbase) + (voff)[_i]), (LAS unsigned*)(lds + (bufoff) + ldsw + _i * 8192), 16, 0, 0); } while (0)
; #define PG8_LDA(dst, b, h) do { _Pragma("unroll") for (int m = 0; m < 4; ++m) _Pragma("unroll") for (int k = 0; k < 2; ++k) dst[m][k] = *(const LAS bf16x8*)(lds + PG8_SA(b, h) + aoff + m * 2048 + k * 1024); } while (0)
; #define PG8_LDB(dst, b, h) do { _Pragma("unroll") for (int n = 0; n < 2; ++n) _Pragma("unroll") for (int k = 0; k < 2; ++k) dst[n][k] = *(const LAS bf16x8*)(lds + PG8_SB(b, h) + boff + n * 2048 + k * 1024); } while (0)
; #define PG8_WAIT_V(n) asm volatile("s_waitcnt vmcnt(" #n ")" ::: "memory")
; #define PG8_WAIT_L(n) asm volatile("s_waitcnt lgkmcnt(" #n ")" ::: "memory")
; #define PG8_BAR __builtin_amdgcn_s_barrier()
; #define PG8_SCHED __builtin_amdgcn_sched_barrier(0)
; template <class Epi>
; __device__ __forceinline__ void gemm_phase(LAS unsigned char* lds, const Gemm g, const StaticOrder& S, const Epi& E, const int tid) {
;     ...
;             const bool last = (t == ntt - 2);
;             const bool s1 = Epi::TWO && (t >= nt), s2 = Epi::TWO && (t + 2 >= nt);
;             const char* a1 = (s1 ? cA2 + (size_t)(t - nt + 1) * kstep : cA + (size_t)(t + 1) * kstep);
;             const char* a2 = last ? nA : (s2 ? cA2 + (size_t)(t + 2 - nt) * kstep : cA + (size_t)(t + 2) * kstep);
;             const char* b2 = last ? nB : (s2 ? cB2 + (size_t)(t + 2 - nt) * kstep : cB + (size_t)(t + 2) * kstep);
;             const char* a3 = a2 + kstep; const char* b3 = b2 + kstep;
;             if constexpr (Epi::TWO) { if (t == nt) E.mid(acc, cur, wr, wc, fr, fq); }
;             if constexpr (SP2) {
;             PG8_LDB(B0, 0, 0); PG8_LDB(B1, 0, 1); PG8_SCHED; PG8_LDA(At, 0, 0); PG8_STAGE(PG8_SA(1, 1), a1 + hstep, voffA);
;             PG8_WAIT_V(8); PG8_WAIT_L(0); PG8_BAR; PG8_MMA(0, 0, At, B0); PG8_MMA(0, 1, At, B1); PG8_BAR; PG8_SCHED;
;             PG8_LDA(At, 0, 1); PG8_STAGE(PG8_SB(0, 0), b2, voffB); PG8_STAGE(PG8_SB(0, 1), b2 + bhs, voffB); PG8_STAGE(PG8_SA(0, 0), a2, voffA);
;             PG8_WAIT_V(8); PG8_WAIT_L(0); PG8_BAR; PG8_MMA(1, 0, At, B0); PG8_MMA(1, 1, At, B1); PG8_BAR; PG8_SCHED;
.LBB0_261:
	s_add_u32 s30, s28, 0xfff80080
	s_addc_u32 s31, s29, -1
	s_add_i32 s49, 0, 0x10000
	s_cmp_eq_u32 s48, 28
	s_cselect_b32 s35, s19, s31
	s_cselect_b32 s34, s44, s30
	v_add_u32_e32 v142, s49, v149
	s_cselect_b32 s31, s17, s47
	s_cselect_b32 s30, s45, s46
	s_add_i32 s52, 0, 0x14000
	ds_read_b128 v[156:159], v142
	ds_read_b128 v[160:163], v142 offset:1024
	ds_read_b128 v[164:167], v142 offset:2048
	ds_read_b128 v[178:181], v142 offset:3072
	v_add_u32_e32 v142, s52, v149
	ds_read_b128 v[182:185], v142
	ds_read_b128 v[186:189], v142 offset:1024
	ds_read_b128 v[190:193], v142 offset:2048
	ds_read_b128 v[194:197], v142 offset:3072
	v_lshl_add_u64 v[142:143], s[28:29], 0, v[140:141]
	s_add_i32 m0, s2, 0xc000
	ds_read_b128 v[198:201], v154
	global_load_lds_dwordx4 v[142:143], off
	ds_read_b128 v[212:215], v154 offset:1024
	ds_read_b128 v[216:219], v154 offset:2048
	v_lshl_add_u64 v[142:143], s[28:29], 0, v[138:139]
	s_add_i32 m0, s2, 0xe000
	s_nop 0
	global_load_lds_dwordx4 v[142:143], off
	ds_read_b128 v[220:223], v154 offset:3072
	ds_read_b128 v[224:227], v154 offset:4096
	ds_read_b128 v[228:231], v154 offset:5120
	ds_read_b128 v[232:235], v154 offset:6144
	ds_read_b128 v[236:239], v154 offset:7168
	s_waitcnt vmcnt(8)
	s_waitcnt lgkmcnt(0)
	s_barrier
	s_setprio 1
	s_waitcnt lgkmcnt(0)
	v_mfma_f32_16x16x32_bf16 v[126:129], v[156:159], v[198:201], v[126:129]
	v_mfma_f32_16x16x32_bf16 v[122:125], v[164:167], v[198:201], v[122:125]
	s_add_i32 s49, s49, s36
	v_mfma_f32_16x16x32_bf16 v[110:113], v[156:159], v[216:219], v[110:113]
	v_lshl_add_u64 v[142:143], s[30:31], 0, v[0:1]
	v_mfma_f32_16x16x32_bf16 v[106:109], v[164:167], v[216:219], v[106:109]
	s_mov_b32 m0, s49
	v_mfma_f32_16x16x32_bf16 v[94:97], v[156:159], v[224:227], v[94:97]
	v_mfma_f32_16x16x32_bf16 v[90:93], v[164:167], v[224:227], v[90:93]
	v_mfma_f32_16x16x32_bf16 v[78:81], v[156:159], v[232:235], v[78:81]
	v_mfma_f32_16x16x32_bf16 v[74:77], v[164:167], v[232:235], v[74:77]
	v_mfma_f32_16x16x32_bf16 v[126:129], v[160:163], v[212:215], v[126:129]
	v_mfma_f32_16x16x32_bf16 v[122:125], v[178:181], v[212:215], v[122:125]
	v_mfma_f32_16x16x32_bf16 v[110:113], v[160:163], v[220:223], v[110:113]
	v_mfma_f32_16x16x32_bf16 v[106:109], v[178:181], v[220:223], v[106:109]
	v_mfma_f32_16x16x32_bf16 v[94:97], v[160:163], v[228:231], v[94:97]
	v_mfma_f32_16x16x32_bf16 v[90:93], v[178:181], v[228:231], v[90:93]
	v_mfma_f32_16x16x32_bf16 v[78:81], v[160:163], v[236:239], v[78:81]
	v_mfma_f32_16x16x32_bf16 v[74:77], v[178:181], v[236:239], v[74:77]
	s_setprio 0
	s_setprio 1
	v_mfma_f32_16x16x32_bf16 v[118:121], v[182:185], v[198:201], v[118:121]
	v_mfma_f32_16x16x32_bf16 v[114:117], v[190:193], v[198:201], v[114:117]
	v_mfma_f32_16x16x32_bf16 v[102:105], v[182:185], v[216:219], v[102:105]
	v_mfma_f32_16x16x32_bf16 v[98:101], v[190:193], v[216:219], v[98:101]
	v_mfma_f32_16x16x32_bf16 v[86:89], v[182:185], v[224:227], v[86:89]
	v_mfma_f32_16x16x32_bf16 v[82:85], v[190:193], v[224:227], v[82:85]
	v_mfma_f32_16x16x32_bf16 v[70:73], v[182:185], v[232:235], v[70:73]
	v_mfma_f32_16x16x32_bf16 v[66:69], v[190:193], v[232:235], v[66:69]
	v_mfma_f32_16x16x32_bf16 v[118:121], v[186:189], v[212:215], v[118:121]
	v_mfma_f32_16x16x32_bf16 v[114:117], v[194:197], v[212:215], v[114:117]
	v_mfma_f32_16x16x32_bf16 v[102:105], v[186:189], v[220:223], v[102:105]
	v_mfma_f32_16x16x32_bf16 v[98:101], v[194:197], v[220:223], v[98:101]
	v_mfma_f32_16x16x32_bf16 v[86:89], v[186:189], v[228:231], v[86:89]
	v_mfma_f32_16x16x32_bf16 v[82:85], v[194:197], v[228:231], v[82:85]
	v_mfma_f32_16x16x32_bf16 v[70:73], v[186:189], v[236:239], v[70:73]
	v_mfma_f32_16x16x32_bf16 v[66:69], v[194:197], v[236:239], v[66:69]
	s_setprio 0
	s_barrier
	ds_read_b128 v[198:201], v154 offset:16384
	global_load_lds_dwordx4 v[142:143], off
	ds_read_b128 v[212:215], v154 offset:17408
	ds_read_b128 v[216:219], v154 offset:18432
	s_add_i32 m0, s49, 0x2000
	s_add_u32 s50, s30, 0x8000
	v_lshl_add_u64 v[168:169], s[30:31], 0, v[134:135]
	s_addc_u32 s51, s31, 0
	s_add_i32 s49, s52, s36
	global_load_lds_dwordx4 v[168:169], off
	ds_read_b128 v[220:223], v154 offset:19456
	ds_read_b128 v[224:227], v154 offset:20480
	v_lshl_add_u64 v[172:173], s[50:51], 0, v[0:1]
	s_mov_b32 m0, s49
	v_lshl_add_u64 v[174:175], s[34:35], 0, v[132:133]
	global_load_lds_dwordx4 v[172:173], off
	ds_read_b128 v[228:231], v154 offset:21504
	ds_read_b128 v[232:235], v154 offset:22528
	v_lshl_add_u64 v[172:173], s[50:51], 0, v[134:135]
	s_add_i32 m0, s49, 0x2000
	s_nop 0
	global_load_lds_dwordx4 v[172:173], off
	ds_read_b128 v[236:239], v154 offset:23552
	v_lshl_add_u64 v[172:173], s[34:35], 0, v[130:131]
	s_mov_b32 m0, s2
	s_nop 0
	global_load_lds_dwordx4 v[172:173], off
	s_mov_b32 m0, s27
	s_nop 0
	global_load_lds_dwordx4 v[174:175], off
	s_waitcnt vmcnt(8)
	s_waitcnt lgkmcnt(0)
	s_barrier
; #define PG8_STAGE(bufoff, gbase, voff) do { _Pragma("unroll") for (int _i = 0; _i < 2; ++_i) \
;         __builtin_amdgcn_global_load_lds((const unsigned*)((const char*)(gbase) + (voff)[_i]), (LAS unsigned*)(lds + (bufoff) + ldsw + _i * 8192), 16, 0, 0); } while (0)
; #define PG8_LDA(dst, b, h) do { _Pragma("unroll") for (int m = 0; m < 4; ++m) _Pragma("unroll") for (int k = 0; k < 2; ++k) dst[m][k] = *(const LAS bf16x8*)(lds + PG8_SA(b, h) + aoff + m * 2048 + k * 1024); } while (0)
; #define PG8_LDB(dst, b, h) do { _Pragma("unroll") for (int n = 0; n < 2; ++n) _Pragma("unroll") for (int k = 0; k < 2; ++k) dst[n][k] = *(const LAS bf16x8*)(lds + PG8_SB(b, h) + boff + n * 2048 + k * 1024); } while (0)
; #define PG8_MMA(ai, bj, At, Bt) do { __builtin_amdgcn_s_setprio(1); _Pragma("unroll") for (int m = 0; m < 4; ++m) _Pragma("unroll") for (int n = 0; n < 2; ++n) _Pragma("unroll") for (int k = 0; k < 2; ++k) \
;         acc[ai][bj][m][n] = __builtin_amdgcn_mfma_f32_16x16x32_bf16(Bt[n][k], At[m][k], acc[ai][bj][m][n], 0, 0, 0); __builtin_amdgcn_s_setprio(0); } while (0)
; #define PG8_WAIT_V(n) asm volatile("s_waitcnt vmcnt(" #n ")" ::: "memory")
; #define PG8_WAIT_L(n) asm volatile("s_waitcnt lgkmcnt(" #n ")" ::: "memory")
; #define PG8_BAR __builtin_amdgcn_s_barrier()
; #define PG8_SCHED __builtin_amdgcn_sched_barrier(0)
; template <class Epi>
; __device__ __forceinline__ void gemm_phase(LAS unsigned char* lds, const Gemm g, const StaticOrder& S, const Epi& E, const int tid) {
;     ...
;             PG8_WAIT_V(8); PG8_WAIT_L(0); PG8_BAR; PG8_MMA(1, 0, At, B0); PG8_MMA(1, 1, At, B1); PG8_BAR; PG8_SCHED;
;             PG8_LDB(B0, 1, 0); PG8_LDB(B1, 1, 1); PG8_SCHED; PG8_LDA(At, 1, 0); PG8_STAGE(PG8_SA(0, 1), a2 + hstep, voffA);
;             PG8_WAIT_V(8); PG8_WAIT_L(0); PG8_BAR; PG8_MMA(0, 0, At, B0); PG8_MMA(0, 1, At, B1); PG8_BAR; PG8_SCHED;
;             PG8_LDA(At, 1, 1); PG8_STAGE(PG8_SB(1, 0), b3, voffB); PG8_STAGE(PG8_SB(1, 1), b3 + bhs, voffB); PG8_STAGE(PG8_SA(1, 0), a3, voffA);
	s_setprio 1
	s_waitcnt lgkmcnt(0)
	v_mfma_f32_16x16x32_bf16 v[62:65], v[156:159], v[198:201], v[62:65]
	v_mfma_f32_16x16x32_bf16 v[58:61], v[164:167], v[198:201], v[58:61]
	s_add_i32 s49, 0, 0x18000
	v_mfma_f32_16x16x32_bf16 v[46:49], v[156:159], v[216:219], v[46:49]
	v_add_u32_e32 v155, s49, v149
	v_mfma_f32_16x16x32_bf16 v[42:45], v[164:167], v[216:219], v[42:45]
	s_add_i32 s50, 0, 0x1c000
	v_mfma_f32_16x16x32_bf16 v[30:33], v[156:159], v[224:227], v[30:33]
	v_mfma_f32_16x16x32_bf16 v[26:29], v[164:167], v[224:227], v[26:29]
	v_mfma_f32_16x16x32_bf16 v[14:17], v[156:159], v[232:235], v[14:17]
	v_mfma_f32_16x16x32_bf16 v[10:13], v[164:167], v[232:235], v[10:13]
	v_mfma_f32_16x16x32_bf16 v[62:65], v[160:163], v[212:215], v[62:65]
	v_mfma_f32_16x16x32_bf16 v[58:61], v[178:181], v[212:215], v[58:61]
	v_mfma_f32_16x16x32_bf16 v[46:49], v[160:163], v[220:223], v[46:49]
	v_mfma_f32_16x16x32_bf16 v[42:45], v[178:181], v[220:223], v[42:45]
	v_mfma_f32_16x16x32_bf16 v[30:33], v[160:163], v[228:231], v[30:33]
	v_mfma_f32_16x16x32_bf16 v[26:29], v[178:181], v[228:231], v[26:29]
	v_mfma_f32_16x16x32_bf16 v[14:17], v[160:163], v[236:239], v[14:17]
	v_mfma_f32_16x16x32_bf16 v[10:13], v[178:181], v[236:239], v[10:13]
	s_setprio 0
	s_setprio 1
	v_mfma_f32_16x16x32_bf16 v[54:57], v[182:185], v[198:201], v[54:57]
	v_mfma_f32_16x16x32_bf16 v[50:53], v[190:193], v[198:201], v[50:53]
	v_mfma_f32_16x16x32_bf16 v[38:41], v[182:185], v[216:219], v[38:41]
	v_mfma_f32_16x16x32_bf16 v[34:37], v[190:193], v[216:219], v[34:37]
	v_mfma_f32_16x16x32_bf16 v[22:25], v[182:185], v[224:227], v[22:25]
	v_mfma_f32_16x16x32_bf16 v[18:21], v[190:193], v[224:227], v[18:21]
	v_mfma_f32_16x16x32_bf16 v[6:9], v[182:185], v[232:235], v[6:9]
	v_mfma_f32_16x16x32_bf16 v[2:5], v[190:193], v[232:235], v[2:5]
	v_mfma_f32_16x16x32_bf16 v[54:57], v[186:189], v[212:215], v[54:57]
	v_mfma_f32_16x16x32_bf16 v[50:53], v[194:197], v[212:215], v[50:53]
	v_mfma_f32_16x16x32_bf16 v[38:41], v[186:189], v[220:223], v[38:41]
	v_mfma_f32_16x16x32_bf16 v[34:37], v[194:197], v[220:223], v[34:37]
	v_mfma_f32_16x16x32_bf16 v[22:25], v[186:189], v[228:231], v[22:25]
	v_mfma_f32_16x16x32_bf16 v[18:21], v[194:197], v[228:231], v[18:21]
	v_mfma_f32_16x16x32_bf16 v[6:9], v[186:189], v[236:239], v[6:9]
	v_mfma_f32_16x16x32_bf16 v[2:5], v[194:197], v[236:239], v[2:5]
	s_setprio 0
	s_barrier
	ds_read_b128 v[156:159], v155
	ds_read_b128 v[160:163], v155 offset:1024
	ds_read_b128 v[164:167], v155 offset:2048
	ds_read_b128 v[178:181], v155 offset:3072
	v_add_u32_e32 v155, s50, v149
	ds_read_b128 v[182:185], v155
	ds_read_b128 v[186:189], v155 offset:1024
	ds_read_b128 v[190:193], v155 offset:2048
	ds_read_b128 v[194:197], v155 offset:3072
	s_add_u32 s34, s34, 0x80000
	s_addc_u32 s35, s35, 0
	s_mov_b32 m0, s37
	v_lshl_add_u64 v[176:177], s[34:35], 0, v[130:131]
	ds_read_b128 v[198:201], v154 offset:32768
	global_load_lds_dwordx4 v[176:177], off
	ds_read_b128 v[212:215], v154 offset:33792
	ds_read_b128 v[216:219], v154 offset:34816
	v_lshl_add_u64 v[176:177], s[34:35], 0, v[132:133]
	s_mov_b32 m0, s38
	s_nop 0
	global_load_lds_dwordx4 v[176:177], off
	ds_read_b128 v[220:223], v154 offset:35840
	ds_read_b128 v[224:227], v154 offset:36864
	ds_read_b128 v[228:231], v154 offset:37888
	ds_read_b128 v[232:235], v154 offset:38912
	ds_read_b128 v[236:239], v154 offset:39936
	s_waitcnt vmcnt(8)
	s_waitcnt lgkmcnt(0)
	s_barrier
	s_setprio 1
	s_waitcnt lgkmcnt(0)
	v_mfma_f32_16x16x32_bf16 v[126:129], v[156:159], v[198:201], v[126:129]
	v_mfma_f32_16x16x32_bf16 v[122:125], v[164:167], v[198:201], v[122:125]
	s_add_i32 s34, s49, s36
	v_mfma_f32_16x16x32_bf16 v[110:113], v[156:159], v[216:219], v[110:113]
	v_lshl_add_u64 v[142:143], v[142:143], 0, s[70:71]
	v_mfma_f32_16x16x32_bf16 v[106:109], v[164:167], v[216:219], v[106:109]
	s_mov_b32 m0, s34
	v_mfma_f32_16x16x32_bf16 v[94:97], v[156:159], v[224:227], v[94:97]
	v_mfma_f32_16x16x32_bf16 v[90:93], v[164:167], v[224:227], v[90:93]
	v_mfma_f32_16x16x32_bf16 v[78:81], v[156:159], v[232:235], v[78:81]
	v_mfma_f32_16x16x32_bf16 v[74:77], v[164:167], v[232:235], v[74:77]
	v_mfma_f32_16x16x32_bf16 v[126:129], v[160:163], v[212:215], v[126:129]
	v_mfma_f32_16x16x32_bf16 v[122:125], v[178:181], v[212:215], v[122:125]
	v_mfma_f32_16x16x32_bf16 v[110:113], v[160:163], v[220:223], v[110:113]
	v_mfma_f32_16x16x32_bf16 v[106:109], v[178:181], v[220:223], v[106:109]
	v_mfma_f32_16x16x32_bf16 v[94:97], v[160:163], v[228:231], v[94:97]
	v_mfma_f32_16x16x32_bf16 v[90:93], v[178:181], v[228:231], v[90:93]
	v_mfma_f32_16x16x32_bf16 v[78:81], v[160:163], v[236:239], v[78:81]
	v_mfma_f32_16x16x32_bf16 v[74:77], v[178:181], v[236:239], v[74:77]
	s_setprio 0
	s_setprio 1
	v_mfma_f32_16x16x32_bf16 v[118:121], v[182:185], v[198:201], v[118:121]
	v_mfma_f32_16x16x32_bf16 v[114:117], v[190:193], v[198:201], v[114:117]
	v_mfma_f32_16x16x32_bf16 v[102:105], v[182:185], v[216:219], v[102:105]
	v_mfma_f32_16x16x32_bf16 v[98:101], v[190:193], v[216:219], v[98:101]
	v_mfma_f32_16x16x32_bf16 v[86:89], v[182:185], v[224:227], v[86:89]
	v_mfma_f32_16x16x32_bf16 v[82:85], v[190:193], v[224:227], v[82:85]
	v_mfma_f32_16x16x32_bf16 v[70:73], v[182:185], v[232:235], v[70:73]
	v_mfma_f32_16x16x32_bf16 v[66:69], v[190:193], v[232:235], v[66:69]
	v_mfma_f32_16x16x32_bf16 v[118:121], v[186:189], v[212:215], v[118:121]
	v_mfma_f32_16x16x32_bf16 v[114:117], v[194:197], v[212:215], v[114:117]
	v_mfma_f32_16x16x32_bf16 v[102:105], v[186:189], v[220:223], v[102:105]
	v_mfma_f32_16x16x32_bf16 v[98:101], v[194:197], v[220:223], v[98:101]
	v_mfma_f32_16x16x32_bf16 v[86:89], v[186:189], v[228:231], v[86:89]
	v_mfma_f32_16x16x32_bf16 v[82:85], v[194:197], v[228:231], v[82:85]
	v_mfma_f32_16x16x32_bf16 v[70:73], v[186:189], v[236:239], v[70:73]
	v_mfma_f32_16x16x32_bf16 v[66:69], v[194:197], v[236:239], v[66:69]
	s_setprio 0
	s_barrier
; #define PG8_STAGE(bufoff, gbase, voff) do { _Pragma("unroll") for (int _i = 0; _i < 2; ++_i) \
;         __builtin_amdgcn_global_load_lds((const unsigned*)((const char*)(gbase) + (voff)[_i]), (LAS unsigned*)(lds + (bufoff) + ldsw + _i * 8192), 16, 0, 0); } while (0)
; #define PG8_LDA(dst, b, h) do { _Pragma("unroll") for (int m = 0; m < 4; ++m) _Pragma("unroll") for (int k = 0; k < 2; ++k) dst[m][k] = *(const LAS bf16x8*)(lds + PG8_SA(b, h) + aoff + m * 2048 + k * 1024); } while (0)
; #define PG8_MMA(ai, bj, At, Bt) do { __builtin_amdgcn_s_setprio(1); _Pragma("unroll") for (int m = 0; m < 4; ++m) _Pragma("unroll") for (int n = 0; n < 2; ++n) _Pragma("unroll") for (int k = 0; k < 2; ++k) \
;         acc[ai][bj][m][n] = __builtin_amdgcn_mfma_f32_16x16x32_bf16(Bt[n][k], At[m][k], acc[ai][bj][m][n], 0, 0, 0); __builtin_amdgcn_s_setprio(0); } while (0)
; #define PG8_WAIT_V(n) asm volatile("s_waitcnt vmcnt(" #n ")" ::: "memory")
; #define PG8_WAIT_L(n) asm volatile("s_waitcnt lgkmcnt(" #n ")" ::: "memory")
; #define PG8_BAR __builtin_amdgcn_s_barrier()
; #define PG8_SCHED __builtin_amdgcn_sched_barrier(0)
; template <class Epi>
; __device__ __forceinline__ void gemm_phase(LAS unsigned char* lds, const Gemm g, const StaticOrder& S, const Epi& E, const int tid) {
;     ...
;             PG8_LDA(At, 1, 1); PG8_STAGE(PG8_SB(1, 0), b3, voffB); PG8_STAGE(PG8_SB(1, 1), b3 + bhs, voffB); PG8_STAGE(PG8_SA(1, 0), a3, voffA);
;             PG8_WAIT_V(8); PG8_WAIT_L(0); PG8_BAR; PG8_MMA(1, 0, At, B0); PG8_MMA(1, 1, At, B1); PG8_BAR; PG8_SCHED;
;     ...
;         if (ALIGN_EPI) { if (wr == 0) PG8_BAR; }
	ds_read_b128 v[198:201], v154 offset:49152
	global_load_lds_dwordx4 v[142:143], off
	ds_read_b128 v[212:215], v154 offset:50176
	ds_read_b128 v[216:219], v154 offset:51200
	s_add_i32 m0, s34, 0x2000
	s_add_u32 s30, s30, 0x8080
	v_lshl_add_u64 v[142:143], v[168:169], 0, s[70:71]
	s_addc_u32 s31, s31, 0
	s_add_i32 s34, s50, s36
	global_load_lds_dwordx4 v[142:143], off
	ds_read_b128 v[220:223], v154 offset:52224
	ds_read_b128 v[224:227], v154 offset:53248
	v_lshl_add_u64 v[142:143], s[30:31], 0, v[0:1]
	s_mov_b32 m0, s34
	s_nop 0
	global_load_lds_dwordx4 v[142:143], off
	ds_read_b128 v[228:231], v154 offset:54272
	ds_read_b128 v[232:235], v154 offset:55296
	v_lshl_add_u64 v[142:143], s[30:31], 0, v[134:135]
	s_add_i32 m0, s34, 0x2000
	s_nop 0
	global_load_lds_dwordx4 v[142:143], off
	ds_read_b128 v[236:239], v154 offset:56320
	v_lshl_add_u64 v[142:143], v[172:173], 0, s[70:71]
	s_mov_b32 m0, s39
	s_nop 0
	global_load_lds_dwordx4 v[142:143], off
	v_lshl_add_u64 v[142:143], v[174:175], 0, s[70:71]
	s_mov_b32 m0, s40
	s_nop 0
	global_load_lds_dwordx4 v[142:143], off
	s_waitcnt vmcnt(8)
	s_waitcnt lgkmcnt(0)
	s_barrier
	s_setprio 1
	s_waitcnt lgkmcnt(0)
	v_mfma_f32_16x16x32_bf16 v[62:65], v[156:159], v[198:201], v[62:65]
	v_mfma_f32_16x16x32_bf16 v[58:61], v[164:167], v[198:201], v[58:61]
	s_add_i32 s48, s48, 2
	v_mfma_f32_16x16x32_bf16 v[46:49], v[156:159], v[216:219], v[46:49]
	s_add_u32 s46, s46, 0x100
	v_mfma_f32_16x16x32_bf16 v[42:45], v[164:167], v[216:219], v[42:45]
	s_addc_u32 s47, s47, 0
	v_mfma_f32_16x16x32_bf16 v[30:33], v[156:159], v[224:227], v[30:33]
	s_add_u32 s28, s28, 0x100
	v_mfma_f32_16x16x32_bf16 v[26:29], v[164:167], v[224:227], v[26:29]
	s_addc_u32 s29, s29, 0
	v_mfma_f32_16x16x32_bf16 v[14:17], v[156:159], v[232:235], v[14:17]
	v_mfma_f32_16x16x32_bf16 v[10:13], v[164:167], v[232:235], v[10:13]
	v_mfma_f32_16x16x32_bf16 v[62:65], v[160:163], v[212:215], v[62:65]
	v_mfma_f32_16x16x32_bf16 v[58:61], v[178:181], v[212:215], v[58:61]
	v_mfma_f32_16x16x32_bf16 v[46:49], v[160:163], v[220:223], v[46:49]
	v_mfma_f32_16x16x32_bf16 v[42:45], v[178:181], v[220:223], v[42:45]
	v_mfma_f32_16x16x32_bf16 v[30:33], v[160:163], v[228:231], v[30:33]
	v_mfma_f32_16x16x32_bf16 v[26:29], v[178:181], v[228:231], v[26:29]
	v_mfma_f32_16x16x32_bf16 v[14:17], v[160:163], v[236:239], v[14:17]
	v_mfma_f32_16x16x32_bf16 v[10:13], v[178:181], v[236:239], v[10:13]
	s_setprio 0
	s_setprio 1
	v_mfma_f32_16x16x32_bf16 v[54:57], v[182:185], v[198:201], v[54:57]
	v_mfma_f32_16x16x32_bf16 v[50:53], v[190:193], v[198:201], v[50:53]
	v_mfma_f32_16x16x32_bf16 v[38:41], v[182:185], v[216:219], v[38:41]
	v_mfma_f32_16x16x32_bf16 v[34:37], v[190:193], v[216:219], v[34:37]
	v_mfma_f32_16x16x32_bf16 v[22:25], v[182:185], v[224:227], v[22:25]
	v_mfma_f32_16x16x32_bf16 v[18:21], v[190:193], v[224:227], v[18:21]
	v_mfma_f32_16x16x32_bf16 v[6:9], v[182:185], v[232:235], v[6:9]
	v_mfma_f32_16x16x32_bf16 v[2:5], v[190:193], v[232:235], v[2:5]
	v_mfma_f32_16x16x32_bf16 v[54:57], v[186:189], v[212:215], v[54:57]
	v_mfma_f32_16x16x32_bf16 v[50:53], v[194:197], v[212:215], v[50:53]
	v_mfma_f32_16x16x32_bf16 v[38:41], v[186:189], v[220:223], v[38:41]
	v_mfma_f32_16x16x32_bf16 v[34:37], v[194:197], v[220:223], v[34:37]
	v_mfma_f32_16x16x32_bf16 v[22:25], v[186:189], v[228:231], v[22:25]
	v_mfma_f32_16x16x32_bf16 v[18:21], v[194:197], v[228:231], v[18:21]
	v_mfma_f32_16x16x32_bf16 v[6:9], v[186:189], v[236:239], v[6:9]
	v_mfma_f32_16x16x32_bf16 v[2:5], v[194:197], v[236:239], v[2:5]
	s_setprio 0
	s_barrier
	s_cmp_gt_u32 s48, 29
	s_cbranch_scc0 .LBB0_261
	s_and_b64 vcc, exec, s[14:15]
	s_cbranch_vccz .LBB0_264
	s_barrier

; #define PG8_STAGE(bufoff, gbase, voff) do { _Pragma("unroll") for (int _i = 0; _i < 2; ++_i) \
;         __builtin_amdgcn_global_load_lds((const unsigned*)((const char*)(gbase) + (voff)[_i]), (LAS unsigned*)(lds + (bufoff) + ldsw + _i * 8192), 16, 0, 0); } while (0)
; #define PG8_LDA(dst, b, h) do { _Pragma("unroll") for (int m = 0; m < 4; ++m) _Pragma("unroll") for (int k = 0; k < 2; ++k) dst[m][k] = *(const LAS bf16x8*)(lds + PG8_SA(b, h) + aoff + m * 2048 + k * 1024); } while (0)
; #define PG8_LDB(dst, b, h) do { _Pragma("unroll") for (int n = 0; n < 2; ++n) _Pragma("unroll") for (int k = 0; k < 2; ++k) dst[n][k] = *(const LAS bf16x8*)(lds + PG8_SB(b, h) + boff + n * 2048 + k * 1024); } while (0)
; #define PG8_MMA(ai, bj, At, Bt) do { __builtin_amdgcn_s_setprio(1); _Pragma("unroll") for (int m = 0; m < 4; ++m) _Pragma("unroll") for (int n = 0; n < 2; ++n) _Pragma("unroll") for (int k = 0; k < 2; ++k) \
;         acc[ai][bj][m][n] = __builtin_amdgcn_mfma_f32_16x16x32_bf16(Bt[n][k], At[m][k], acc[ai][bj][m][n], 0, 0, 0); __builtin_amdgcn_s_setprio(0); } while (0)
; #define PG8_BAR __builtin_amdgcn_s_barrier()
; template <class Epi>
; __device__ __forceinline__ void gemm_phase(LAS unsigned char* lds, const Gemm g, const StaticOrder& S, const Epi& E, const int tid) {
;     ...
;         for (int t = 0; t < ntt; t += 2) {
;             const bool last = (t == ntt - 2);
;             const bool s1 = Epi::TWO && (t >= nt), s2 = Epi::TWO && (t + 2 >= nt);
;             const char* a1 = (s1 ? cA2 + (size_t)(t - nt + 1) * kstep : cA + (size_t)(t + 1) * kstep);
;             const char* a2 = last ? nA : (s2 ? cA2 + (size_t)(t + 2 - nt) * kstep : cA + (size_t)(t + 2) * kstep);
;             const char* b2 = last ? nB : (s2 ? cB2 + (size_t)(t + 2 - nt) * kstep : cB + (size_t)(t + 2) * kstep);
;             const char* a3 = a2 + kstep; const char* b3 = b2 + kstep;
;             if constexpr (Epi::TWO) { if (t == nt) E.mid(acc, cur, wr, wc, fr, fq); }
;             if constexpr (SP2) {
;             PG8_LDB(B0, 0, 0); PG8_LDB(B1, 0, 1); PG8_SCHED; PG8_LDA(At, 0, 0); PG8_STAGE(PG8_SA(1, 1), a1 + hstep, voffA);
;             PG8_WAIT_V(8); PG8_WAIT_L(0); PG8_BAR; PG8_MMA(0, 0, At, B0); PG8_MMA(0, 1, At, B1); PG8_BAR; PG8_SCHED;
;             PG8_LDA(At, 0, 1); PG8_STAGE(PG8_SB(0, 0), b2, voffB); PG8_STAGE(PG8_SB(0, 1), b2 + bhs, voffB); PG8_STAGE(PG8_SA(0, 0), a2, voffA);
.LBB0_314:
	s_add_u32 s40, s6, 0xfff80080
	s_addc_u32 s41, s7, -1
	s_add_i32 s56, 0, 0x10000
	s_cmp_eq_u32 s55, 28
	s_cselect_b32 s43, s27, s41
	s_cselect_b32 s42, s39, s40
	s_cselect_b32 s41, s25, s54
	s_cselect_b32 s40, s52, s53
	s_add_i32 s58, 0, 0x14000
	v_add_u32_e32 v46, s56, v212
	v_add_u32_e32 v70, s58, v212
	ds_read_b128 v[34:37], v46
	ds_read_b128 v[38:41], v46 offset:1024
	ds_read_b128 v[42:45], v46 offset:2048
	ds_read_b128 v[46:49], v46 offset:3072
	ds_read_b128 v[58:61], v70
	ds_read_b128 v[62:65], v70 offset:1024
	ds_read_b128 v[66:69], v70 offset:2048
	ds_read_b128 v[70:73], v70 offset:3072
	v_lshl_add_u64 v[172:173], s[6:7], 0, v[188:189]
	s_add_i32 m0, s44, 0xc000
	ds_read_b128 v[162:165], v220
	global_load_lds_dwordx4 v[172:173], off
	ds_read_b128 v[166:169], v220 offset:1024
	ds_read_b128 v[190:193], v220 offset:2048
	v_lshl_add_u64 v[172:173], s[6:7], 0, v[186:187]
	s_add_i32 m0, s44, 0xe000
	s_nop 0
	global_load_lds_dwordx4 v[172:173], off
	ds_read_b128 v[194:197], v220 offset:3072
	ds_read_b128 v[198:201], v220 offset:4096
	ds_read_b128 v[222:225], v220 offset:5120
	ds_read_b128 v[226:229], v220 offset:6144
	ds_read_b128 v[230:233], v220 offset:7168
	s_waitcnt vmcnt(8)
	s_waitcnt lgkmcnt(0)
	s_barrier
	s_setprio 1
	s_waitcnt lgkmcnt(0)
	v_mfma_f32_16x16x32_bf16 v[158:161], v[34:37], v[162:165], v[158:161]
	v_mfma_f32_16x16x32_bf16 v[154:157], v[42:45], v[162:165], v[154:157]
	s_add_i32 s56, s56, s33
	v_mfma_f32_16x16x32_bf16 v[142:145], v[34:37], v[190:193], v[142:145]
	v_lshl_add_u64 v[172:173], s[40:41], 0, v[0:1]
	v_mfma_f32_16x16x32_bf16 v[138:141], v[42:45], v[190:193], v[138:141]
	s_mov_b32 m0, s56
	v_mfma_f32_16x16x32_bf16 v[126:129], v[34:37], v[198:201], v[126:129]
	v_mfma_f32_16x16x32_bf16 v[122:125], v[42:45], v[198:201], v[122:125]
	v_mfma_f32_16x16x32_bf16 v[110:113], v[34:37], v[226:229], v[110:113]
	v_mfma_f32_16x16x32_bf16 v[106:109], v[42:45], v[226:229], v[106:109]
	v_mfma_f32_16x16x32_bf16 v[158:161], v[38:41], v[166:169], v[158:161]
	v_mfma_f32_16x16x32_bf16 v[154:157], v[46:49], v[166:169], v[154:157]
	v_mfma_f32_16x16x32_bf16 v[142:145], v[38:41], v[194:197], v[142:145]
	v_mfma_f32_16x16x32_bf16 v[138:141], v[46:49], v[194:197], v[138:141]
	v_mfma_f32_16x16x32_bf16 v[126:129], v[38:41], v[222:225], v[126:129]
	v_mfma_f32_16x16x32_bf16 v[122:125], v[46:49], v[222:225], v[122:125]
	v_mfma_f32_16x16x32_bf16 v[110:113], v[38:41], v[230:233], v[110:113]
	v_mfma_f32_16x16x32_bf16 v[106:109], v[46:49], v[230:233], v[106:109]
	s_setprio 0
	s_setprio 1
	v_mfma_f32_16x16x32_bf16 v[150:153], v[58:61], v[162:165], v[150:153]
	v_mfma_f32_16x16x32_bf16 v[146:149], v[66:69], v[162:165], v[146:149]
	v_mfma_f32_16x16x32_bf16 v[134:137], v[58:61], v[190:193], v[134:137]
	v_mfma_f32_16x16x32_bf16 v[130:133], v[66:69], v[190:193], v[130:133]
	v_mfma_f32_16x16x32_bf16 v[118:121], v[58:61], v[198:201], v[118:121]
	v_mfma_f32_16x16x32_bf16 v[114:117], v[66:69], v[198:201], v[114:117]
	v_mfma_f32_16x16x32_bf16 v[102:105], v[58:61], v[226:229], v[102:105]
	v_mfma_f32_16x16x32_bf16 v[98:101], v[66:69], v[226:229], v[98:101]
	v_mfma_f32_16x16x32_bf16 v[150:153], v[62:65], v[166:169], v[150:153]
	v_mfma_f32_16x16x32_bf16 v[146:149], v[70:73], v[166:169], v[146:149]
	v_mfma_f32_16x16x32_bf16 v[134:137], v[62:65], v[194:197], v[134:137]
	v_mfma_f32_16x16x32_bf16 v[130:133], v[70:73], v[194:197], v[130:133]
	v_mfma_f32_16x16x32_bf16 v[118:121], v[62:65], v[222:225], v[118:121]
	v_mfma_f32_16x16x32_bf16 v[114:117], v[70:73], v[222:225], v[114:117]
	v_mfma_f32_16x16x32_bf16 v[102:105], v[62:65], v[230:233], v[102:105]
	v_mfma_f32_16x16x32_bf16 v[98:101], v[70:73], v[230:233], v[98:101]
	s_setprio 0
	s_barrier
	ds_read_b128 v[162:165], v220 offset:16384
	global_load_lds_dwordx4 v[172:173], off
	ds_read_b128 v[166:169], v220 offset:17408
	ds_read_b128 v[190:193], v220 offset:18432
	s_add_i32 m0, s56, 0x2000
	s_add_u32 s56, s40, 0x8000
	v_lshl_add_u64 v[174:175], s[40:41], 0, v[182:183]
	s_addc_u32 s57, s41, 0
	s_add_i32 s58, s58, s33
	global_load_lds_dwordx4 v[174:175], off
	ds_read_b128 v[194:197], v220 offset:19456
	ds_read_b128 v[198:201], v220 offset:20480
	v_lshl_add_u64 v[176:177], s[56:57], 0, v[0:1]
	s_mov_b32 m0, s58
	v_lshl_add_u64 v[238:239], s[42:43], 0, v[180:181]
	global_load_lds_dwordx4 v[176:177], off
	ds_read_b128 v[222:225], v220 offset:21504
	ds_read_b128 v[226:229], v220 offset:22528
	v_lshl_add_u64 v[176:177], s[56:57], 0, v[182:183]
	s_add_i32 m0, s58, 0x2000
	s_nop 0
	global_load_lds_dwordx4 v[176:177], off
	ds_read_b128 v[230:233], v220 offset:23552
	v_lshl_add_u64 v[176:177], s[42:43], 0, v[178:179]
	s_mov_b32 m0, s44
	s_nop 0
	global_load_lds_dwordx4 v[176:177], off
	s_mov_b32 m0, s45
	s_nop 0
	global_load_lds_dwordx4 v[238:239], off
	s_waitcnt vmcnt(8)
	s_waitcnt lgkmcnt(0)
	s_barrier
; #define PG8_STAGE(bufoff, gbase, voff) do { _Pragma("unroll") for (int _i = 0; _i < 2; ++_i) \
;         __builtin_amdgcn_global_load_lds((const unsigned*)((const char*)(gbase) + (voff)[_i]), (LAS unsigned*)(lds + (bufoff) + ldsw + _i * 8192), 16, 0, 0); } while (0)
; #define PG8_LDA(dst, b, h) do { _Pragma("unroll") for (int m = 0; m < 4; ++m) _Pragma("unroll") for (int k = 0; k < 2; ++k) dst[m][k] = *(const LAS bf16x8*)(lds + PG8_SA(b, h) + aoff + m * 2048 + k * 1024); } while (0)
; #define PG8_LDB(dst, b, h) do { _Pragma("unroll") for (int n = 0; n < 2; ++n) _Pragma("unroll") for (int k = 0; k < 2; ++k) dst[n][k] = *(const LAS bf16x8*)(lds + PG8_SB(b, h) + boff + n * 2048 + k * 1024); } while (0)
; #define PG8_MMA(ai, bj, At, Bt) do { __builtin_amdgcn_s_setprio(1); _Pragma("unroll") for (int m = 0; m < 4; ++m) _Pragma("unroll") for (int n = 0; n < 2; ++n) _Pragma("unroll") for (int k = 0; k < 2; ++k) \
;         acc[ai][bj][m][n] = __builtin_amdgcn_mfma_f32_16x16x32_bf16(Bt[n][k], At[m][k], acc[ai][bj][m][n], 0, 0, 0); __builtin_amdgcn_s_setprio(0); } while (0)
; #define PG8_WAIT_V(n) asm volatile("s_waitcnt vmcnt(" #n ")" ::: "memory")
; #define PG8_WAIT_L(n) asm volatile("s_waitcnt lgkmcnt(" #n ")" ::: "memory")
; #define PG8_BAR __builtin_amdgcn_s_barrier()
; #define PG8_SCHED __builtin_amdgcn_sched_barrier(0)
; template <class Epi>
; __device__ __forceinline__ void gemm_phase(LAS unsigned char* lds, const Gemm g, const StaticOrder& S, const Epi& E, const int tid) {
;     ...
;             PG8_WAIT_V(8); PG8_WAIT_L(0); PG8_BAR; PG8_MMA(1, 0, At, B0); PG8_MMA(1, 1, At, B1); PG8_BAR; PG8_SCHED;
;             PG8_LDB(B0, 1, 0); PG8_LDB(B1, 1, 1); PG8_SCHED; PG8_LDA(At, 1, 0); PG8_STAGE(PG8_SA(0, 1), a2 + hstep, voffA);
;             PG8_WAIT_V(8); PG8_WAIT_L(0); PG8_BAR; PG8_MMA(0, 0, At, B0); PG8_MMA(0, 1, At, B1); PG8_BAR; PG8_SCHED;
	s_setprio 1
	s_waitcnt lgkmcnt(0)
	v_mfma_f32_16x16x32_bf16 v[94:97], v[34:37], v[162:165], v[94:97]
	v_mfma_f32_16x16x32_bf16 v[90:93], v[42:45], v[162:165], v[90:93]
	s_add_i32 s56, 0, 0x18000
	v_mfma_f32_16x16x32_bf16 v[78:81], v[34:37], v[190:193], v[78:81]
	s_add_i32 s57, 0, 0x1c000
	v_mfma_f32_16x16x32_bf16 v[74:77], v[42:45], v[190:193], v[74:77]
	v_mfma_f32_16x16x32_bf16 v[30:33], v[34:37], v[198:201], v[30:33]
	v_mfma_f32_16x16x32_bf16 v[26:29], v[42:45], v[198:201], v[26:29]
	v_mfma_f32_16x16x32_bf16 v[14:17], v[34:37], v[226:229], v[14:17]
	v_mfma_f32_16x16x32_bf16 v[10:13], v[42:45], v[226:229], v[10:13]
	v_mfma_f32_16x16x32_bf16 v[94:97], v[38:41], v[166:169], v[94:97]
	v_mfma_f32_16x16x32_bf16 v[90:93], v[46:49], v[166:169], v[90:93]
	v_mfma_f32_16x16x32_bf16 v[78:81], v[38:41], v[194:197], v[78:81]
	v_mfma_f32_16x16x32_bf16 v[74:77], v[46:49], v[194:197], v[74:77]
	v_mfma_f32_16x16x32_bf16 v[30:33], v[38:41], v[222:225], v[30:33]
	v_mfma_f32_16x16x32_bf16 v[26:29], v[46:49], v[222:225], v[26:29]
	v_mfma_f32_16x16x32_bf16 v[14:17], v[38:41], v[230:233], v[14:17]
	v_mfma_f32_16x16x32_bf16 v[10:13], v[46:49], v[230:233], v[10:13]
	s_setprio 0
	s_setprio 1
	v_mfma_f32_16x16x32_bf16 v[22:25], v[58:61], v[198:201], v[22:25]
	v_mfma_f32_16x16x32_bf16 v[18:21], v[66:69], v[198:201], v[18:21]
	v_mfma_f32_16x16x32_bf16 v[6:9], v[58:61], v[226:229], v[6:9]
	v_mfma_f32_16x16x32_bf16 v[2:5], v[66:69], v[226:229], v[2:5]
	v_mfma_f32_16x16x32_bf16 v[34:37], v[58:61], v[162:165], v[86:89]
	v_mfma_f32_16x16x32_bf16 v[38:41], v[66:69], v[162:165], v[82:85]
	v_mfma_f32_16x16x32_bf16 v[42:45], v[58:61], v[190:193], v[54:57]
	v_mfma_f32_16x16x32_bf16 v[46:49], v[66:69], v[190:193], v[50:53]
	v_mfma_f32_16x16x32_bf16 v[22:25], v[62:65], v[222:225], v[22:25]
	v_mfma_f32_16x16x32_bf16 v[18:21], v[70:73], v[222:225], v[18:21]
	v_mfma_f32_16x16x32_bf16 v[6:9], v[62:65], v[230:233], v[6:9]
	v_mfma_f32_16x16x32_bf16 v[2:5], v[70:73], v[230:233], v[2:5]
	v_mfma_f32_16x16x32_bf16 v[34:37], v[62:65], v[166:169], v[34:37]
	v_mfma_f32_16x16x32_bf16 v[38:41], v[70:73], v[166:169], v[38:41]
	v_mfma_f32_16x16x32_bf16 v[42:45], v[62:65], v[194:197], v[42:45]
	v_mfma_f32_16x16x32_bf16 v[46:49], v[70:73], v[194:197], v[46:49]
	s_setprio 0
	s_barrier
	v_add_u32_e32 v62, s56, v212
	v_add_u32_e32 v82, s57, v212
	ds_read_b128 v[50:53], v62
	ds_read_b128 v[54:57], v62 offset:1024
	ds_read_b128 v[58:61], v62 offset:2048
	ds_read_b128 v[62:65], v62 offset:3072
	ds_read_b128 v[66:69], v82
	ds_read_b128 v[70:73], v82 offset:1024
	ds_read_b128 v[162:165], v82 offset:2048
	ds_read_b128 v[166:169], v82 offset:3072
	s_add_u32 s42, s42, 0x80000
	s_addc_u32 s43, s43, 0
	s_mov_b32 m0, s46
	v_lshl_add_u64 v[234:235], s[42:43], 0, v[178:179]
	ds_read_b128 v[82:85], v220 offset:32768
	global_load_lds_dwordx4 v[234:235], off
	ds_read_b128 v[86:89], v220 offset:33792
	ds_read_b128 v[190:193], v220 offset:34816
	v_lshl_add_u64 v[234:235], s[42:43], 0, v[180:181]
	s_mov_b32 m0, s47
	s_nop 0
	global_load_lds_dwordx4 v[234:235], off
	ds_read_b128 v[194:197], v220 offset:35840
	ds_read_b128 v[198:201], v220 offset:36864
	ds_read_b128 v[222:225], v220 offset:37888
	ds_read_b128 v[226:229], v220 offset:38912
	ds_read_b128 v[230:233], v220 offset:39936
	s_waitcnt vmcnt(8)
	s_waitcnt lgkmcnt(0)
	s_barrier
	s_setprio 1
	s_waitcnt lgkmcnt(0)
	v_mfma_f32_16x16x32_bf16 v[158:161], v[50:53], v[82:85], v[158:161]
	v_mfma_f32_16x16x32_bf16 v[154:157], v[58:61], v[82:85], v[154:157]
	v_mfma_f32_16x16x32_bf16 v[142:145], v[50:53], v[190:193], v[142:145]
	v_mfma_f32_16x16x32_bf16 v[138:141], v[58:61], v[190:193], v[138:141]
	v_mfma_f32_16x16x32_bf16 v[126:129], v[50:53], v[198:201], v[126:129]
	v_mfma_f32_16x16x32_bf16 v[122:125], v[58:61], v[198:201], v[122:125]
	v_mfma_f32_16x16x32_bf16 v[110:113], v[50:53], v[226:229], v[110:113]
	v_mfma_f32_16x16x32_bf16 v[106:109], v[58:61], v[226:229], v[106:109]
	v_mfma_f32_16x16x32_bf16 v[158:161], v[54:57], v[86:89], v[158:161]
	v_mfma_f32_16x16x32_bf16 v[154:157], v[62:65], v[86:89], v[154:157]
	v_mfma_f32_16x16x32_bf16 v[142:145], v[54:57], v[194:197], v[142:145]
	v_mfma_f32_16x16x32_bf16 v[138:141], v[62:65], v[194:197], v[138:141]
	v_mfma_f32_16x16x32_bf16 v[126:129], v[54:57], v[222:225], v[126:129]
	v_mfma_f32_16x16x32_bf16 v[122:125], v[62:65], v[222:225], v[122:125]
	v_mfma_f32_16x16x32_bf16 v[110:113], v[54:57], v[230:233], v[110:113]
	v_mfma_f32_16x16x32_bf16 v[106:109], v[62:65], v[230:233], v[106:109]
	s_setprio 0
	s_setprio 1
	v_mfma_f32_16x16x32_bf16 v[150:153], v[66:69], v[82:85], v[150:153]
	v_mfma_f32_16x16x32_bf16 v[82:85], v[162:165], v[82:85], v[146:149]
	v_mfma_f32_16x16x32_bf16 v[146:149], v[166:169], v[86:89], v[82:85]
	v_mfma_f32_16x16x32_bf16 v[82:85], v[66:69], v[190:193], v[134:137]
	v_mfma_f32_16x16x32_bf16 v[134:137], v[70:73], v[194:197], v[82:85]
	v_mfma_f32_16x16x32_bf16 v[82:85], v[162:165], v[190:193], v[130:133]
	v_mfma_f32_16x16x32_bf16 v[130:133], v[166:169], v[194:197], v[82:85]
	v_mfma_f32_16x16x32_bf16 v[82:85], v[66:69], v[198:201], v[118:121]
	v_mfma_f32_16x16x32_bf16 v[118:121], v[70:73], v[222:225], v[82:85]
	v_mfma_f32_16x16x32_bf16 v[82:85], v[162:165], v[198:201], v[114:117]
	v_mfma_f32_16x16x32_bf16 v[114:117], v[166:169], v[222:225], v[82:85]
	v_mfma_f32_16x16x32_bf16 v[82:85], v[66:69], v[226:229], v[102:105]
	v_mfma_f32_16x16x32_bf16 v[102:105], v[70:73], v[230:233], v[82:85]
	v_mfma_f32_16x16x32_bf16 v[82:85], v[162:165], v[226:229], v[98:101]
	v_mfma_f32_16x16x32_bf16 v[150:153], v[70:73], v[86:89], v[150:153]
	v_mfma_f32_16x16x32_bf16 v[98:101], v[166:169], v[230:233], v[82:85]
	s_setprio 0
	s_barrier
; #define PG8_STAGE(bufoff, gbase, voff) do { _Pragma("unroll") for (int _i = 0; _i < 2; ++_i) \
;         __builtin_amdgcn_global_load_lds((const unsigned*)((const char*)(gbase) + (voff)[_i]), (LAS unsigned*)(lds + (bufoff) + ldsw + _i * 8192), 16, 0, 0); } while (0)
; #define PG8_LDA(dst, b, h) do { _Pragma("unroll") for (int m = 0; m < 4; ++m) _Pragma("unroll") for (int k = 0; k < 2; ++k) dst[m][k] = *(const LAS bf16x8*)(lds + PG8_SA(b, h) + aoff + m * 2048 + k * 1024); } while (0)
; #define PG8_MMA(ai, bj, At, Bt) do { __builtin_amdgcn_s_setprio(1); _Pragma("unroll") for (int m = 0; m < 4; ++m) _Pragma("unroll") for (int n = 0; n < 2; ++n) _Pragma("unroll") for (int k = 0; k < 2; ++k) \
;         acc[ai][bj][m][n] = __builtin_amdgcn_mfma_f32_16x16x32_bf16(Bt[n][k], At[m][k], acc[ai][bj][m][n], 0, 0, 0); __builtin_amdgcn_s_setprio(0); } while (0)
; #define PG8_WAIT_V(n) asm volatile("s_waitcnt vmcnt(" #n ")" ::: "memory")
; #define PG8_WAIT_L(n) asm volatile("s_waitcnt lgkmcnt(" #n ")" ::: "memory")
; #define PG8_BAR __builtin_amdgcn_s_barrier()
; #define PG8_SCHED __builtin_amdgcn_sched_barrier(0)
; template <class Epi>
; __device__ __forceinline__ void gemm_phase(LAS unsigned char* lds, const Gemm g, const StaticOrder& S, const Epi& E, const int tid) {
;     ...
;             PG8_LDA(At, 1, 1); PG8_STAGE(PG8_SB(1, 0), b3, voffB); PG8_STAGE(PG8_SB(1, 1), b3 + bhs, voffB); PG8_STAGE(PG8_SA(1, 0), a3, voffA);
;             PG8_WAIT_V(8); PG8_WAIT_L(0); PG8_BAR; PG8_MMA(1, 0, At, B0); PG8_MMA(1, 1, At, B1); PG8_BAR; PG8_SCHED;
;     ...
;         if (ALIGN_EPI) { if (wr == 0) PG8_BAR; }
	s_add_i32 s42, s56, s33
	v_lshl_add_u64 v[86:87], v[172:173], 0, s[70:71]
	s_mov_b32 m0, s42
	s_nop 0
	ds_read_b128 v[82:85], v220 offset:49152
	global_load_lds_dwordx4 v[86:87], off
	ds_read_b128 v[190:193], v220 offset:50176
	ds_read_b128 v[194:197], v220 offset:51200
	s_add_i32 m0, s42, 0x2000
	s_add_u32 s40, s40, 0x8080
	v_lshl_add_u64 v[86:87], v[174:175], 0, s[70:71]
	s_addc_u32 s41, s41, 0
	s_add_i32 s42, s57, s33
	global_load_lds_dwordx4 v[86:87], off
	ds_read_b128 v[198:201], v220 offset:52224
	ds_read_b128 v[222:225], v220 offset:53248
	v_lshl_add_u64 v[86:87], s[40:41], 0, v[0:1]
	s_mov_b32 m0, s42
	s_nop 0
	global_load_lds_dwordx4 v[86:87], off
	ds_read_b128 v[226:229], v220 offset:54272
	ds_read_b128 v[230:233], v220 offset:55296
	v_lshl_add_u64 v[86:87], s[40:41], 0, v[182:183]
	s_add_i32 m0, s42, 0x2000
	s_nop 0
	global_load_lds_dwordx4 v[86:87], off
	ds_read_b128 v[234:237], v220 offset:56320
	v_lshl_add_u64 v[86:87], v[176:177], 0, s[70:71]
	s_mov_b32 m0, s48
	s_nop 0
	global_load_lds_dwordx4 v[86:87], off
	v_lshl_add_u64 v[86:87], v[238:239], 0, s[70:71]
	s_mov_b32 m0, s49
	s_nop 0
	global_load_lds_dwordx4 v[86:87], off
	s_waitcnt vmcnt(8)
	s_waitcnt lgkmcnt(0)
	s_barrier
	s_setprio 1
	s_waitcnt lgkmcnt(0)
	v_mfma_f32_16x16x32_bf16 v[86:89], v[50:53], v[82:85], v[94:97]
	v_mfma_f32_16x16x32_bf16 v[94:97], v[54:57], v[190:193], v[86:89]
	s_add_i32 s55, s55, 2
	v_mfma_f32_16x16x32_bf16 v[86:89], v[58:61], v[82:85], v[90:93]
	s_add_u32 s53, s53, 0x100
	v_mfma_f32_16x16x32_bf16 v[78:81], v[50:53], v[194:197], v[78:81]
	s_addc_u32 s54, s54, 0
	v_mfma_f32_16x16x32_bf16 v[74:77], v[58:61], v[194:197], v[74:77]
	s_add_u32 s6, s6, 0x100
	v_mfma_f32_16x16x32_bf16 v[30:33], v[50:53], v[222:225], v[30:33]
	s_addc_u32 s7, s7, 0
	v_mfma_f32_16x16x32_bf16 v[26:29], v[58:61], v[222:225], v[26:29]
	v_mfma_f32_16x16x32_bf16 v[14:17], v[50:53], v[230:233], v[14:17]
	v_mfma_f32_16x16x32_bf16 v[10:13], v[58:61], v[230:233], v[10:13]
	v_mfma_f32_16x16x32_bf16 v[90:93], v[62:65], v[190:193], v[86:89]
	v_mfma_f32_16x16x32_bf16 v[78:81], v[54:57], v[198:201], v[78:81]
	v_mfma_f32_16x16x32_bf16 v[74:77], v[62:65], v[198:201], v[74:77]
	v_mfma_f32_16x16x32_bf16 v[30:33], v[54:57], v[226:229], v[30:33]
	v_mfma_f32_16x16x32_bf16 v[26:29], v[62:65], v[226:229], v[26:29]
	v_mfma_f32_16x16x32_bf16 v[14:17], v[54:57], v[234:237], v[14:17]
	v_mfma_f32_16x16x32_bf16 v[10:13], v[62:65], v[234:237], v[10:13]
	s_setprio 0
	s_setprio 1
	v_mfma_f32_16x16x32_bf16 v[34:37], v[66:69], v[82:85], v[34:37]
	v_mfma_f32_16x16x32_bf16 v[86:89], v[70:73], v[190:193], v[34:37]
	v_mfma_f32_16x16x32_bf16 v[34:37], v[162:165], v[82:85], v[38:41]
	v_mfma_f32_16x16x32_bf16 v[82:85], v[166:169], v[190:193], v[34:37]
	v_mfma_f32_16x16x32_bf16 v[34:37], v[66:69], v[194:197], v[42:45]
	v_mfma_f32_16x16x32_bf16 v[54:57], v[70:73], v[198:201], v[34:37]
	v_mfma_f32_16x16x32_bf16 v[34:37], v[162:165], v[194:197], v[46:49]
	v_mfma_f32_16x16x32_bf16 v[22:25], v[66:69], v[222:225], v[22:25]
	v_mfma_f32_16x16x32_bf16 v[18:21], v[162:165], v[222:225], v[18:21]
	v_mfma_f32_16x16x32_bf16 v[6:9], v[66:69], v[230:233], v[6:9]
	v_mfma_f32_16x16x32_bf16 v[2:5], v[162:165], v[230:233], v[2:5]
	v_mfma_f32_16x16x32_bf16 v[50:53], v[166:169], v[198:201], v[34:37]
	v_mfma_f32_16x16x32_bf16 v[22:25], v[70:73], v[226:229], v[22:25]
	v_mfma_f32_16x16x32_bf16 v[18:21], v[166:169], v[226:229], v[18:21]
	v_mfma_f32_16x16x32_bf16 v[6:9], v[70:73], v[234:237], v[6:9]
	v_mfma_f32_16x16x32_bf16 v[2:5], v[166:169], v[234:237], v[2:5]
	s_setprio 0
	s_barrier
	s_cmp_gt_u32 s55, 29
	s_cbranch_scc0 .LBB0_314
	s_and_b64 vcc, exec, s[22:23]
	s_cbranch_vccz .LBB0_317
	s_barrier

; #define PG8_STAGE(bufoff, gbase, voff) do { _Pragma("unroll") for (int _i = 0; _i < 2; ++_i) \
;         __builtin_amdgcn_global_load_lds((const unsigned*)((const char*)(gbase) + (voff)[_i]), (LAS unsigned*)(lds + (bufoff) + ldsw + _i * 8192), 16, 0, 0); } while (0)
; #define PG8_LDA(dst, b, h) do { _Pragma("unroll") for (int m = 0; m < 4; ++m) _Pragma("unroll") for (int k = 0; k < 2; ++k) dst[m][k] = *(const LAS bf16x8*)(lds + PG8_SA(b, h) + aoff + m * 2048 + k * 1024); } while (0)
; #define PG8_LDB(dst, b, h) do { _Pragma("unroll") for (int n = 0; n < 2; ++n) _Pragma("unroll") for (int k = 0; k < 2; ++k) dst[n][k] = *(const LAS bf16x8*)(lds + PG8_SB(b, h) + boff + n * 2048 + k * 1024); } while (0)
; #define PG8_MMA(ai, bj, At, Bt) do { __builtin_amdgcn_s_setprio(1); _Pragma("unroll") for (int m = 0; m < 4; ++m) _Pragma("unroll") for (int n = 0; n < 2; ++n) _Pragma("unroll") for (int k = 0; k < 2; ++k) \
;         acc[ai][bj][m][n] = __builtin_amdgcn_mfma_f32_16x16x32_bf16(Bt[n][k], At[m][k], acc[ai][bj][m][n], 0, 0, 0); __builtin_amdgcn_s_setprio(0); } while (0)
; #define PG8_BAR __builtin_amdgcn_s_barrier()
; template <class Epi>
; __device__ __forceinline__ void gemm_phase(LAS unsigned char* lds, const Gemm g, const StaticOrder& S, const Epi& E, const int tid) {
;     ...
;         for (int t = 0; t < ntt; t += 2) {
;             const bool last = (t == ntt - 2);
;             const bool s1 = Epi::TWO && (t >= nt), s2 = Epi::TWO && (t + 2 >= nt);
;             const char* a1 = (s1 ? cA2 + (size_t)(t - nt + 1) * kstep : cA + (size_t)(t + 1) * kstep);
;             const char* a2 = last ? nA : (s2 ? cA2 + (size_t)(t + 2 - nt) * kstep : cA + (size_t)(t + 2) * kstep);
;             const char* b2 = last ? nB : (s2 ? cB2 + (size_t)(t + 2 - nt) * kstep : cB + (size_t)(t + 2) * kstep);
;             const char* a3 = a2 + kstep; const char* b3 = b2 + kstep;
;             if constexpr (Epi::TWO) { if (t == nt) E.mid(acc, cur, wr, wc, fr, fq); }
;             if constexpr (SP2) {
;             PG8_LDB(B0, 0, 0); PG8_LDB(B1, 0, 1); PG8_SCHED; PG8_LDA(At, 0, 0); PG8_STAGE(PG8_SA(1, 1), a1 + hstep, voffA);
;             PG8_WAIT_V(8); PG8_WAIT_L(0); PG8_BAR; PG8_MMA(0, 0, At, B0); PG8_MMA(0, 1, At, B1); PG8_BAR; PG8_SCHED;
;             PG8_LDA(At, 0, 1); PG8_STAGE(PG8_SB(0, 0), b2, voffB); PG8_STAGE(PG8_SB(0, 1), b2 + bhs, voffB); PG8_STAGE(PG8_SA(0, 0), a2, voffA);
.LBB0_546:
	s_add_u32 s28, s26, 0xfff80080
	s_addc_u32 s29, s27, -1
	s_add_i32 s44, 0, 0x10000
	s_cmp_eq_u32 s39, 28
	s_cselect_b32 s35, s19, s29
	s_cselect_b32 s34, s31, s28
	v_add_u32_e32 v0, s44, v149
	s_cselect_b32 s29, s17, s38
	s_cselect_b32 s28, s33, s37
	s_add_i32 s46, 0, 0x14000
	ds_read_b128 v[150:153], v0
	ds_read_b128 v[154:157], v0 offset:1024
	ds_read_b128 v[158:161], v0 offset:2048
	ds_read_b128 v[186:189], v0 offset:3072
	v_add_u32_e32 v0, s46, v149
	ds_read_b128 v[190:193], v0
	ds_read_b128 v[194:197], v0 offset:1024
	ds_read_b128 v[198:201], v0 offset:2048
	ds_read_b128 v[212:215], v0 offset:3072
	v_lshl_add_u64 v[162:163], s[26:27], 0, v[146:147]
	s_add_i32 m0, s57, 0xc000
	ds_read_b128 v[216:219], v184
	global_load_lds_dwordx4 v[162:163], off
	ds_read_b128 v[220:223], v184 offset:1024
	ds_read_b128 v[224:227], v184 offset:2048
	v_lshl_add_u64 v[162:163], s[26:27], 0, v[144:145]
	s_add_i32 m0, s57, 0xe000
	s_nop 0
	global_load_lds_dwordx4 v[162:163], off
	ds_read_b128 v[228:231], v184 offset:3072
	ds_read_b128 v[232:235], v184 offset:4096
	ds_read_b128 v[236:239], v184 offset:5120
	ds_read_b128 v[240:243], v184 offset:6144
	ds_read_b128 v[244:247], v184 offset:7168
	s_waitcnt vmcnt(8)
	s_waitcnt lgkmcnt(0)
	s_barrier
	s_setprio 1
	s_waitcnt lgkmcnt(0)
	v_mfma_f32_16x16x32_bf16 v[126:129], v[150:153], v[216:219], v[126:129]
	v_mfma_f32_16x16x32_bf16 v[122:125], v[158:161], v[216:219], v[122:125]
	s_add_i32 s44, s44, s56
	v_mfma_f32_16x16x32_bf16 v[110:113], v[150:153], v[224:227], v[110:113]
	v_lshl_add_u64 v[162:163], s[28:29], 0, v[132:133]
	v_mfma_f32_16x16x32_bf16 v[106:109], v[158:161], v[224:227], v[106:109]
	s_mov_b32 m0, s44
	v_mfma_f32_16x16x32_bf16 v[94:97], v[150:153], v[232:235], v[94:97]
	v_mfma_f32_16x16x32_bf16 v[90:93], v[158:161], v[232:235], v[90:93]
	v_mfma_f32_16x16x32_bf16 v[78:81], v[150:153], v[240:243], v[78:81]
	v_mfma_f32_16x16x32_bf16 v[74:77], v[158:161], v[240:243], v[74:77]
	v_mfma_f32_16x16x32_bf16 v[126:129], v[154:157], v[220:223], v[126:129]
	v_mfma_f32_16x16x32_bf16 v[122:125], v[186:189], v[220:223], v[122:125]
	v_mfma_f32_16x16x32_bf16 v[110:113], v[154:157], v[228:231], v[110:113]
	v_mfma_f32_16x16x32_bf16 v[106:109], v[186:189], v[228:231], v[106:109]
	v_mfma_f32_16x16x32_bf16 v[94:97], v[154:157], v[236:239], v[94:97]
	v_mfma_f32_16x16x32_bf16 v[90:93], v[186:189], v[236:239], v[90:93]
	v_mfma_f32_16x16x32_bf16 v[78:81], v[154:157], v[244:247], v[78:81]
	v_mfma_f32_16x16x32_bf16 v[74:77], v[186:189], v[244:247], v[74:77]
	s_setprio 0
	s_setprio 1
	v_mfma_f32_16x16x32_bf16 v[118:121], v[190:193], v[216:219], v[118:121]
	v_mfma_f32_16x16x32_bf16 v[114:117], v[198:201], v[216:219], v[114:117]
	v_mfma_f32_16x16x32_bf16 v[102:105], v[190:193], v[224:227], v[102:105]
	v_mfma_f32_16x16x32_bf16 v[98:101], v[198:201], v[224:227], v[98:101]
	v_mfma_f32_16x16x32_bf16 v[86:89], v[190:193], v[232:235], v[86:89]
	v_mfma_f32_16x16x32_bf16 v[82:85], v[198:201], v[232:235], v[82:85]
	v_mfma_f32_16x16x32_bf16 v[70:73], v[190:193], v[240:243], v[70:73]
	v_mfma_f32_16x16x32_bf16 v[66:69], v[198:201], v[240:243], v[66:69]
	v_mfma_f32_16x16x32_bf16 v[118:121], v[194:197], v[220:223], v[118:121]
	v_mfma_f32_16x16x32_bf16 v[114:117], v[212:215], v[220:223], v[114:117]
	v_mfma_f32_16x16x32_bf16 v[102:105], v[194:197], v[228:231], v[102:105]
	v_mfma_f32_16x16x32_bf16 v[98:101], v[212:215], v[228:231], v[98:101]
	v_mfma_f32_16x16x32_bf16 v[86:89], v[194:197], v[236:239], v[86:89]
	v_mfma_f32_16x16x32_bf16 v[82:85], v[212:215], v[236:239], v[82:85]
	v_mfma_f32_16x16x32_bf16 v[70:73], v[194:197], v[244:247], v[70:73]
	v_mfma_f32_16x16x32_bf16 v[66:69], v[212:215], v[244:247], v[66:69]
	s_setprio 0
	s_barrier
	ds_read_b128 v[216:219], v184 offset:16384
	global_load_lds_dwordx4 v[162:163], off
	ds_read_b128 v[220:223], v184 offset:17408
	ds_read_b128 v[224:227], v184 offset:18432
	s_add_i32 m0, s44, 0x2000
	s_add_u32 s44, s28, 0x8000
	v_lshl_add_u64 v[248:249], s[28:29], 0, v[136:137]
	s_addc_u32 s45, s29, 0
	s_add_i32 s46, s46, s56
	global_load_lds_dwordx4 v[248:249], off
	ds_read_b128 v[228:231], v184 offset:19456
	ds_read_b128 v[232:235], v184 offset:20480
	v_lshl_add_u64 v[172:173], s[44:45], 0, v[132:133]
	s_mov_b32 m0, s46
	v_lshl_add_u64 v[174:175], s[34:35], 0, v[134:135]
	global_load_lds_dwordx4 v[172:173], off
	ds_read_b128 v[236:239], v184 offset:21504
	ds_read_b128 v[240:243], v184 offset:22528
	v_lshl_add_u64 v[172:173], s[44:45], 0, v[136:137]
	s_add_i32 m0, s46, 0x2000
	s_nop 0
	global_load_lds_dwordx4 v[172:173], off
	ds_read_b128 v[244:247], v184 offset:23552
	v_lshl_add_u64 v[172:173], s[34:35], 0, v[130:131]
	s_mov_b32 m0, s57
	s_nop 0
	global_load_lds_dwordx4 v[172:173], off
	s_mov_b32 m0, s58
	s_nop 0
	global_load_lds_dwordx4 v[174:175], off
	s_waitcnt vmcnt(8)
	s_waitcnt lgkmcnt(0)
	s_barrier
; #define PG8_STAGE(bufoff, gbase, voff) do { _Pragma("unroll") for (int _i = 0; _i < 2; ++_i) \
;         __builtin_amdgcn_global_load_lds((const unsigned*)((const char*)(gbase) + (voff)[_i]), (LAS unsigned*)(lds + (bufoff) + ldsw + _i * 8192), 16, 0, 0); } while (0)
; #define PG8_LDA(dst, b, h) do { _Pragma("unroll") for (int m = 0; m < 4; ++m) _Pragma("unroll") for (int k = 0; k < 2; ++k) dst[m][k] = *(const LAS bf16x8*)(lds + PG8_SA(b, h) + aoff + m * 2048 + k * 1024); } while (0)
; #define PG8_LDB(dst, b, h) do { _Pragma("unroll") for (int n = 0; n < 2; ++n) _Pragma("unroll") for (int k = 0; k < 2; ++k) dst[n][k] = *(const LAS bf16x8*)(lds + PG8_SB(b, h) + boff + n * 2048 + k * 1024); } while (0)
; #define PG8_MMA(ai, bj, At, Bt) do { __builtin_amdgcn_s_setprio(1); _Pragma("unroll") for (int m = 0; m < 4; ++m) _Pragma("unroll") for (int n = 0; n < 2; ++n) _Pragma("unroll") for (int k = 0; k < 2; ++k) \
;         acc[ai][bj][m][n] = __builtin_amdgcn_mfma_f32_16x16x32_bf16(Bt[n][k], At[m][k], acc[ai][bj][m][n], 0, 0, 0); __builtin_amdgcn_s_setprio(0); } while (0)
; #define PG8_WAIT_V(n) asm volatile("s_waitcnt vmcnt(" #n ")" ::: "memory")
; #define PG8_WAIT_L(n) asm volatile("s_waitcnt lgkmcnt(" #n ")" ::: "memory")
; #define PG8_BAR __builtin_amdgcn_s_barrier()
; #define PG8_SCHED __builtin_amdgcn_sched_barrier(0)
; template <class Epi>
; __device__ __forceinline__ void gemm_phase(LAS unsigned char* lds, const Gemm g, const StaticOrder& S, const Epi& E, const int tid) {
;     ...
;             PG8_WAIT_V(8); PG8_WAIT_L(0); PG8_BAR; PG8_MMA(1, 0, At, B0); PG8_MMA(1, 1, At, B1); PG8_BAR; PG8_SCHED;
;             PG8_LDB(B0, 1, 0); PG8_LDB(B1, 1, 1); PG8_SCHED; PG8_LDA(At, 1, 0); PG8_STAGE(PG8_SA(0, 1), a2 + hstep, voffA);
;             PG8_WAIT_V(8); PG8_WAIT_L(0); PG8_BAR; PG8_MMA(0, 0, At, B0); PG8_MMA(0, 1, At, B1); PG8_BAR; PG8_SCHED;
	s_setprio 1
	s_waitcnt lgkmcnt(0)
	v_mfma_f32_16x16x32_bf16 v[62:65], v[150:153], v[216:219], v[62:65]
	v_mfma_f32_16x16x32_bf16 v[58:61], v[158:161], v[216:219], v[58:61]
	s_add_i32 s44, 0, 0x18000
	v_mfma_f32_16x16x32_bf16 v[46:49], v[150:153], v[224:227], v[46:49]
	v_add_u32_e32 v0, s44, v149
	v_mfma_f32_16x16x32_bf16 v[42:45], v[158:161], v[224:227], v[42:45]
	s_add_i32 s45, 0, 0x1c000
	v_mfma_f32_16x16x32_bf16 v[30:33], v[150:153], v[232:235], v[30:33]
	v_mfma_f32_16x16x32_bf16 v[26:29], v[158:161], v[232:235], v[26:29]
	v_mfma_f32_16x16x32_bf16 v[14:17], v[150:153], v[240:243], v[14:17]
	v_mfma_f32_16x16x32_bf16 v[10:13], v[158:161], v[240:243], v[10:13]
	v_mfma_f32_16x16x32_bf16 v[62:65], v[154:157], v[220:223], v[62:65]
	v_mfma_f32_16x16x32_bf16 v[58:61], v[186:189], v[220:223], v[58:61]
	v_mfma_f32_16x16x32_bf16 v[46:49], v[154:157], v[228:231], v[46:49]
	v_mfma_f32_16x16x32_bf16 v[42:45], v[186:189], v[228:231], v[42:45]
	v_mfma_f32_16x16x32_bf16 v[30:33], v[154:157], v[236:239], v[30:33]
	v_mfma_f32_16x16x32_bf16 v[26:29], v[186:189], v[236:239], v[26:29]
	v_mfma_f32_16x16x32_bf16 v[14:17], v[154:157], v[244:247], v[14:17]
	v_mfma_f32_16x16x32_bf16 v[10:13], v[186:189], v[244:247], v[10:13]
	s_setprio 0
	s_setprio 1
	v_mfma_f32_16x16x32_bf16 v[54:57], v[190:193], v[216:219], v[54:57]
	v_mfma_f32_16x16x32_bf16 v[50:53], v[198:201], v[216:219], v[50:53]
	v_mfma_f32_16x16x32_bf16 v[38:41], v[190:193], v[224:227], v[38:41]
	v_mfma_f32_16x16x32_bf16 v[34:37], v[198:201], v[224:227], v[34:37]
	v_mfma_f32_16x16x32_bf16 v[22:25], v[190:193], v[232:235], v[22:25]
	v_mfma_f32_16x16x32_bf16 v[18:21], v[198:201], v[232:235], v[18:21]
	v_mfma_f32_16x16x32_bf16 v[6:9], v[190:193], v[240:243], v[6:9]
	v_mfma_f32_16x16x32_bf16 v[2:5], v[198:201], v[240:243], v[2:5]
	v_mfma_f32_16x16x32_bf16 v[54:57], v[194:197], v[220:223], v[54:57]
	v_mfma_f32_16x16x32_bf16 v[50:53], v[212:215], v[220:223], v[50:53]
	v_mfma_f32_16x16x32_bf16 v[38:41], v[194:197], v[228:231], v[38:41]
	v_mfma_f32_16x16x32_bf16 v[34:37], v[212:215], v[228:231], v[34:37]
	v_mfma_f32_16x16x32_bf16 v[22:25], v[194:197], v[236:239], v[22:25]
	v_mfma_f32_16x16x32_bf16 v[18:21], v[212:215], v[236:239], v[18:21]
	v_mfma_f32_16x16x32_bf16 v[6:9], v[194:197], v[244:247], v[6:9]
	v_mfma_f32_16x16x32_bf16 v[2:5], v[212:215], v[244:247], v[2:5]
	s_setprio 0
	s_barrier
	ds_read_b128 v[150:153], v0
	ds_read_b128 v[154:157], v0 offset:1024
	ds_read_b128 v[158:161], v0 offset:2048
	ds_read_b128 v[186:189], v0 offset:3072
	v_add_u32_e32 v0, s45, v149
	ds_read_b128 v[190:193], v0
	ds_read_b128 v[194:197], v0 offset:1024
	ds_read_b128 v[198:201], v0 offset:2048
	ds_read_b128 v[212:215], v0 offset:3072
	s_add_u32 s34, s34, 0x80000
	s_addc_u32 s35, s35, 0
	s_mov_b32 m0, s59
	v_lshl_add_u64 v[176:177], s[34:35], 0, v[130:131]
	ds_read_b128 v[216:219], v184 offset:32768
	global_load_lds_dwordx4 v[176:177], off
	ds_read_b128 v[220:223], v184 offset:33792
	ds_read_b128 v[224:227], v184 offset:34816
	v_lshl_add_u64 v[176:177], s[34:35], 0, v[134:135]
	s_mov_b32 m0, s60
	s_nop 0
	global_load_lds_dwordx4 v[176:177], off
	ds_read_b128 v[228:231], v184 offset:35840
	ds_read_b128 v[232:235], v184 offset:36864
	ds_read_b128 v[236:239], v184 offset:37888
	ds_read_b128 v[240:243], v184 offset:38912
	ds_read_b128 v[244:247], v184 offset:39936
	s_waitcnt vmcnt(8)
	s_waitcnt lgkmcnt(0)
	s_barrier
	s_setprio 1
	s_waitcnt lgkmcnt(0)
	v_mfma_f32_16x16x32_bf16 v[126:129], v[150:153], v[216:219], v[126:129]
	v_mfma_f32_16x16x32_bf16 v[122:125], v[158:161], v[216:219], v[122:125]
	s_add_i32 s34, s44, s56
	v_mfma_f32_16x16x32_bf16 v[110:113], v[150:153], v[224:227], v[110:113]
	v_lshl_add_u64 v[162:163], v[162:163], 0, s[70:71]
	v_mfma_f32_16x16x32_bf16 v[106:109], v[158:161], v[224:227], v[106:109]
	s_mov_b32 m0, s34
	v_mfma_f32_16x16x32_bf16 v[94:97], v[150:153], v[232:235], v[94:97]
	v_mfma_f32_16x16x32_bf16 v[90:93], v[158:161], v[232:235], v[90:93]
	v_mfma_f32_16x16x32_bf16 v[78:81], v[150:153], v[240:243], v[78:81]
	v_mfma_f32_16x16x32_bf16 v[74:77], v[158:161], v[240:243], v[74:77]
	v_mfma_f32_16x16x32_bf16 v[126:129], v[154:157], v[220:223], v[126:129]
	v_mfma_f32_16x16x32_bf16 v[122:125], v[186:189], v[220:223], v[122:125]
	v_mfma_f32_16x16x32_bf16 v[110:113], v[154:157], v[228:231], v[110:113]
	v_mfma_f32_16x16x32_bf16 v[106:109], v[186:189], v[228:231], v[106:109]
	v_mfma_f32_16x16x32_bf16 v[94:97], v[154:157], v[236:239], v[94:97]
	v_mfma_f32_16x16x32_bf16 v[90:93], v[186:189], v[236:239], v[90:93]
	v_mfma_f32_16x16x32_bf16 v[78:81], v[154:157], v[244:247], v[78:81]
	v_mfma_f32_16x16x32_bf16 v[74:77], v[186:189], v[244:247], v[74:77]
	s_setprio 0
	s_setprio 1
	v_mfma_f32_16x16x32_bf16 v[118:121], v[190:193], v[216:219], v[118:121]
	v_mfma_f32_16x16x32_bf16 v[114:117], v[198:201], v[216:219], v[114:117]
	v_mfma_f32_16x16x32_bf16 v[102:105], v[190:193], v[224:227], v[102:105]
	v_mfma_f32_16x16x32_bf16 v[98:101], v[198:201], v[224:227], v[98:101]
	v_mfma_f32_16x16x32_bf16 v[86:89], v[190:193], v[232:235], v[86:89]
	v_mfma_f32_16x16x32_bf16 v[82:85], v[198:201], v[232:235], v[82:85]
	v_mfma_f32_16x16x32_bf16 v[70:73], v[190:193], v[240:243], v[70:73]
	v_mfma_f32_16x16x32_bf16 v[66:69], v[198:201], v[240:243], v[66:69]
	v_mfma_f32_16x16x32_bf16 v[118:121], v[194:197], v[220:223], v[118:121]
	v_mfma_f32_16x16x32_bf16 v[114:117], v[212:215], v[220:223], v[114:117]
	v_mfma_f32_16x16x32_bf16 v[102:105], v[194:197], v[228:231], v[102:105]
	v_mfma_f32_16x16x32_bf16 v[98:101], v[212:215], v[228:231], v[98:101]
	v_mfma_f32_16x16x32_bf16 v[86:89], v[194:197], v[236:239], v[86:89]
	v_mfma_f32_16x16x32_bf16 v[82:85], v[212:215], v[236:239], v[82:85]
	v_mfma_f32_16x16x32_bf16 v[70:73], v[194:197], v[244:247], v[70:73]
	v_mfma_f32_16x16x32_bf16 v[66:69], v[212:215], v[244:247], v[66:69]
	s_setprio 0
	s_barrier
; #define PG8_STAGE(bufoff, gbase, voff) do { _Pragma("unroll") for (int _i = 0; _i < 2; ++_i) \
;         __builtin_amdgcn_global_load_lds((const unsigned*)((const char*)(gbase) + (voff)[_i]), (LAS unsigned*)(lds + (bufoff) + ldsw + _i * 8192), 16, 0, 0); } while (0)
; #define PG8_LDA(dst, b, h) do { _Pragma("unroll") for (int m = 0; m < 4; ++m) _Pragma("unroll") for (int k = 0; k < 2; ++k) dst[m][k] = *(const LAS bf16x8*)(lds + PG8_SA(b, h) + aoff + m * 2048 + k * 1024); } while (0)
; #define PG8_MMA(ai, bj, At, Bt) do { __builtin_amdgcn_s_setprio(1); _Pragma("unroll") for (int m = 0; m < 4; ++m) _Pragma("unroll") for (int n = 0; n < 2; ++n) _Pragma("unroll") for (int k = 0; k < 2; ++k) \
;         acc[ai][bj][m][n] = __builtin_amdgcn_mfma_f32_16x16x32_bf16(Bt[n][k], At[m][k], acc[ai][bj][m][n], 0, 0, 0); __builtin_amdgcn_s_setprio(0); } while (0)
; #define PG8_WAIT_V(n) asm volatile("s_waitcnt vmcnt(" #n ")" ::: "memory")
; #define PG8_WAIT_L(n) asm volatile("s_waitcnt lgkmcnt(" #n ")" ::: "memory")
; #define PG8_BAR __builtin_amdgcn_s_barrier()
; #define PG8_SCHED __builtin_amdgcn_sched_barrier(0)
; template <class Epi>
; __device__ __forceinline__ void gemm_phase(LAS unsigned char* lds, const Gemm g, const StaticOrder& S, const Epi& E, const int tid) {
;     ...
;             PG8_LDA(At, 1, 1); PG8_STAGE(PG8_SB(1, 0), b3, voffB); PG8_STAGE(PG8_SB(1, 1), b3 + bhs, voffB); PG8_STAGE(PG8_SA(1, 0), a3, voffA);
;             PG8_WAIT_V(8); PG8_WAIT_L(0); PG8_BAR; PG8_MMA(1, 0, At, B0); PG8_MMA(1, 1, At, B1); PG8_BAR; PG8_SCHED;
;     ...
;         if (ALIGN_EPI) { if (wr == 0) PG8_BAR; }
	ds_read_b128 v[216:219], v184 offset:49152
	global_load_lds_dwordx4 v[162:163], off
	ds_read_b128 v[220:223], v184 offset:50176
	ds_read_b128 v[224:227], v184 offset:51200
	s_add_i32 m0, s34, 0x2000
	s_add_u32 s28, s28, 0x8080
	v_lshl_add_u64 v[162:163], v[248:249], 0, s[70:71]
	s_addc_u32 s29, s29, 0
	s_add_i32 s34, s45, s56
	global_load_lds_dwordx4 v[162:163], off
	ds_read_b128 v[228:231], v184 offset:52224
	ds_read_b128 v[232:235], v184 offset:53248
	v_lshl_add_u64 v[162:163], s[28:29], 0, v[132:133]
	s_mov_b32 m0, s34
	s_nop 0
	global_load_lds_dwordx4 v[162:163], off
	ds_read_b128 v[236:239], v184 offset:54272
	ds_read_b128 v[240:243], v184 offset:55296
	v_lshl_add_u64 v[162:163], s[28:29], 0, v[136:137]
	s_add_i32 m0, s34, 0x2000
	s_nop 0
	global_load_lds_dwordx4 v[162:163], off
	ds_read_b128 v[244:247], v184 offset:56320
	v_lshl_add_u64 v[162:163], v[172:173], 0, s[70:71]
	s_mov_b32 m0, s61
	s_nop 0
	global_load_lds_dwordx4 v[162:163], off
	v_lshl_add_u64 v[162:163], v[174:175], 0, s[70:71]
	s_mov_b32 m0, s62
	s_nop 0
	global_load_lds_dwordx4 v[162:163], off
	s_waitcnt vmcnt(8)
	s_waitcnt lgkmcnt(0)
	s_barrier
	s_setprio 1
	s_waitcnt lgkmcnt(0)
	v_mfma_f32_16x16x32_bf16 v[62:65], v[150:153], v[216:219], v[62:65]
	v_mfma_f32_16x16x32_bf16 v[58:61], v[158:161], v[216:219], v[58:61]
	s_add_i32 s39, s39, 2
	v_mfma_f32_16x16x32_bf16 v[46:49], v[150:153], v[224:227], v[46:49]
	s_add_u32 s37, s37, 0x100
	v_mfma_f32_16x16x32_bf16 v[42:45], v[158:161], v[224:227], v[42:45]
	s_addc_u32 s38, s38, 0
	v_mfma_f32_16x16x32_bf16 v[30:33], v[150:153], v[232:235], v[30:33]
	s_add_u32 s26, s26, 0x100
	v_mfma_f32_16x16x32_bf16 v[26:29], v[158:161], v[232:235], v[26:29]
	s_addc_u32 s27, s27, 0
	v_mfma_f32_16x16x32_bf16 v[14:17], v[150:153], v[240:243], v[14:17]
	v_mfma_f32_16x16x32_bf16 v[10:13], v[158:161], v[240:243], v[10:13]
	v_mfma_f32_16x16x32_bf16 v[62:65], v[154:157], v[220:223], v[62:65]
	v_mfma_f32_16x16x32_bf16 v[58:61], v[186:189], v[220:223], v[58:61]
	v_mfma_f32_16x16x32_bf16 v[46:49], v[154:157], v[228:231], v[46:49]
	v_mfma_f32_16x16x32_bf16 v[42:45], v[186:189], v[228:231], v[42:45]
	v_mfma_f32_16x16x32_bf16 v[30:33], v[154:157], v[236:239], v[30:33]
	v_mfma_f32_16x16x32_bf16 v[26:29], v[186:189], v[236:239], v[26:29]
	v_mfma_f32_16x16x32_bf16 v[14:17], v[154:157], v[244:247], v[14:17]
	v_mfma_f32_16x16x32_bf16 v[10:13], v[186:189], v[244:247], v[10:13]
	s_setprio 0
	s_setprio 1
	v_mfma_f32_16x16x32_bf16 v[54:57], v[190:193], v[216:219], v[54:57]
	v_mfma_f32_16x16x32_bf16 v[50:53], v[198:201], v[216:219], v[50:53]
	v_mfma_f32_16x16x32_bf16 v[38:41], v[190:193], v[224:227], v[38:41]
	v_mfma_f32_16x16x32_bf16 v[34:37], v[198:201], v[224:227], v[34:37]
	v_mfma_f32_16x16x32_bf16 v[22:25], v[190:193], v[232:235], v[22:25]
	v_mfma_f32_16x16x32_bf16 v[18:21], v[198:201], v[232:235], v[18:21]
	v_mfma_f32_16x16x32_bf16 v[6:9], v[190:193], v[240:243], v[6:9]
	v_mfma_f32_16x16x32_bf16 v[2:5], v[198:201], v[240:243], v[2:5]
	v_mfma_f32_16x16x32_bf16 v[54:57], v[194:197], v[220:223], v[54:57]
	v_mfma_f32_16x16x32_bf16 v[50:53], v[212:215], v[220:223], v[50:53]
	v_mfma_f32_16x16x32_bf16 v[38:41], v[194:197], v[228:231], v[38:41]
	v_mfma_f32_16x16x32_bf16 v[34:37], v[212:215], v[228:231], v[34:37]
	v_mfma_f32_16x16x32_bf16 v[22:25], v[194:197], v[236:239], v[22:25]
	v_mfma_f32_16x16x32_bf16 v[18:21], v[212:215], v[236:239], v[18:21]
	v_mfma_f32_16x16x32_bf16 v[6:9], v[194:197], v[244:247], v[6:9]
	v_mfma_f32_16x16x32_bf16 v[2:5], v[212:215], v[244:247], v[2:5]
	s_setprio 0
	s_barrier
	s_cmp_gt_u32 s39, 29
	s_cbranch_scc0 .LBB0_546
	s_and_b64 vcc, exec, s[14:15]
	s_cbranch_vccz .LBB0_549
	s_barrier

; #define PG8_STAGE(bufoff, gbase, voff) do { _Pragma("unroll") for (int _i = 0; _i < 2; ++_i) \
;         __builtin_amdgcn_global_load_lds((const unsigned*)((const char*)(gbase) + (voff)[_i]), (LAS unsigned*)(lds + (bufoff) + ldsw + _i * 8192), 16, 0, 0); } while (0)
; #define PG8_LDA(dst, b, h) do { _Pragma("unroll") for (int m = 0; m < 4; ++m) _Pragma("unroll") for (int k = 0; k < 2; ++k) dst[m][k] = *(const LAS bf16x8*)(lds + PG8_SA(b, h) + aoff + m * 2048 + k * 1024); } while (0)
; #define PG8_LDB(dst, b, h) do { _Pragma("unroll") for (int n = 0; n < 2; ++n) _Pragma("unroll") for (int k = 0; k < 2; ++k) dst[n][k] = *(const LAS bf16x8*)(lds + PG8_SB(b, h) + boff + n * 2048 + k * 1024); } while (0)
; #define PG8_MMA(ai, bj, At, Bt) do { __builtin_amdgcn_s_setprio(1); _Pragma("unroll") for (int m = 0; m < 4; ++m) _Pragma("unroll") for (int n = 0; n < 2; ++n) _Pragma("unroll") for (int k = 0; k < 2; ++k) \
;         acc[ai][bj][m][n] = __builtin_amdgcn_mfma_f32_16x16x32_bf16(Bt[n][k], At[m][k], acc[ai][bj][m][n], 0, 0, 0); __builtin_amdgcn_s_setprio(0); } while (0)
; #define PG8_BAR __builtin_amdgcn_s_barrier()
; template <class Epi>
; __device__ __forceinline__ void gemm_phase(LAS unsigned char* lds, const Gemm g, const StaticOrder& S, const Epi& E, const int tid) {
;     ...
;         for (int t = 0; t < ntt; t += 2) {
;             const bool last = (t == ntt - 2);
;             const bool s1 = Epi::TWO && (t >= nt), s2 = Epi::TWO && (t + 2 >= nt);
;             const char* a1 = (s1 ? cA2 + (size_t)(t - nt + 1) * kstep : cA + (size_t)(t + 1) * kstep);
;             const char* a2 = last ? nA : (s2 ? cA2 + (size_t)(t + 2 - nt) * kstep : cA + (size_t)(t + 2) * kstep);
;             const char* b2 = last ? nB : (s2 ? cB2 + (size_t)(t + 2 - nt) * kstep : cB + (size_t)(t + 2) * kstep);
;             const char* a3 = a2 + kstep; const char* b3 = b2 + kstep;
;             if constexpr (Epi::TWO) { if (t == nt) E.mid(acc, cur, wr, wc, fr, fq); }
;             if constexpr (SP2) {
;             PG8_LDB(B0, 0, 0); PG8_LDB(B1, 0, 1); PG8_SCHED; PG8_LDA(At, 0, 0); PG8_STAGE(PG8_SA(1, 1), a1 + hstep, voffA);
;             PG8_WAIT_V(8); PG8_WAIT_L(0); PG8_BAR; PG8_MMA(0, 0, At, B0); PG8_MMA(0, 1, At, B1); PG8_BAR; PG8_SCHED;
;             PG8_LDA(At, 0, 1); PG8_STAGE(PG8_SB(0, 0), b2, voffB); PG8_STAGE(PG8_SB(0, 1), b2 + bhs, voffB); PG8_STAGE(PG8_SA(0, 0), a2, voffA);
.LBB0_844:
	s_add_u32 s28, s26, 0xfff80080
	s_addc_u32 s29, s27, -1
	s_add_i32 s48, 0, 0x10000
	s_cmp_eq_u32 s47, 28
	s_cselect_b32 s31, s15, s29
	s_cselect_b32 s30, s43, s28
	v_add_u32_e32 v145, s48, v142
	s_cselect_b32 s29, s13, s46
	s_cselect_b32 s28, s44, s45
	s_add_i32 s50, 0, 0x14000
	ds_read_b128 v[146:149], v145
	ds_read_b128 v[150:153], v145 offset:1024
	ds_read_b128 v[154:157], v145 offset:2048
	ds_read_b128 v[158:161], v145 offset:3072
	v_add_u32_e32 v145, s50, v142
	ds_read_b128 v[162:165], v145
	ds_read_b128 v[166:169], v145 offset:1024
	ds_read_b128 v[178:181], v145 offset:2048
	ds_read_b128 v[182:185], v145 offset:3072
	v_lshl_add_u64 v[172:173], s[26:27], 0, v[138:139]
	s_add_i32 m0, s23, 0xc000
	ds_read_b128 v[186:189], v144
	global_load_lds_dwordx4 v[172:173], off
	ds_read_b128 v[190:193], v144 offset:1024
	ds_read_b128 v[194:197], v144 offset:2048
	v_lshl_add_u64 v[172:173], s[26:27], 0, v[136:137]
	s_add_i32 m0, s23, 0xe000
	s_nop 0
	global_load_lds_dwordx4 v[172:173], off
	ds_read_b128 v[198:201], v144 offset:3072
	ds_read_b128 v[212:215], v144 offset:4096
	ds_read_b128 v[216:219], v144 offset:5120
	ds_read_b128 v[220:223], v144 offset:6144
	ds_read_b128 v[224:227], v144 offset:7168
	s_waitcnt vmcnt(8)
	s_waitcnt lgkmcnt(0)
	s_barrier
	s_setprio 1
	s_waitcnt lgkmcnt(0)
	v_mfma_f32_16x16x32_bf16 v[126:129], v[146:149], v[186:189], v[126:129]
	v_mfma_f32_16x16x32_bf16 v[122:125], v[154:157], v[186:189], v[122:125]
	s_add_i32 s48, s48, s37
	v_mfma_f32_16x16x32_bf16 v[118:121], v[146:149], v[194:197], v[118:121]
	v_lshl_add_u64 v[172:173], s[28:29], 0, v[0:1]
	v_mfma_f32_16x16x32_bf16 v[110:113], v[154:157], v[194:197], v[110:113]
	s_mov_b32 m0, s48
	v_mfma_f32_16x16x32_bf16 v[102:105], v[146:149], v[212:215], v[102:105]
	v_mfma_f32_16x16x32_bf16 v[94:97], v[154:157], v[212:215], v[94:97]
	v_mfma_f32_16x16x32_bf16 v[86:89], v[146:149], v[220:223], v[86:89]
	v_mfma_f32_16x16x32_bf16 v[78:81], v[154:157], v[220:223], v[78:81]
	v_mfma_f32_16x16x32_bf16 v[126:129], v[150:153], v[190:193], v[126:129]
	v_mfma_f32_16x16x32_bf16 v[122:125], v[158:161], v[190:193], v[122:125]
	v_mfma_f32_16x16x32_bf16 v[118:121], v[150:153], v[198:201], v[118:121]
	v_mfma_f32_16x16x32_bf16 v[110:113], v[158:161], v[198:201], v[110:113]
	v_mfma_f32_16x16x32_bf16 v[102:105], v[150:153], v[216:219], v[102:105]
	v_mfma_f32_16x16x32_bf16 v[94:97], v[158:161], v[216:219], v[94:97]
	v_mfma_f32_16x16x32_bf16 v[86:89], v[150:153], v[224:227], v[86:89]
	v_mfma_f32_16x16x32_bf16 v[78:81], v[158:161], v[224:227], v[78:81]
	s_setprio 0
	s_setprio 1
	v_mfma_f32_16x16x32_bf16 v[114:117], v[162:165], v[186:189], v[114:117]
	v_mfma_f32_16x16x32_bf16 v[106:109], v[178:181], v[186:189], v[106:109]
	v_mfma_f32_16x16x32_bf16 v[98:101], v[162:165], v[194:197], v[98:101]
	v_mfma_f32_16x16x32_bf16 v[90:93], v[178:181], v[194:197], v[90:93]
	v_mfma_f32_16x16x32_bf16 v[82:85], v[162:165], v[212:215], v[82:85]
	v_mfma_f32_16x16x32_bf16 v[74:77], v[178:181], v[212:215], v[74:77]
	v_mfma_f32_16x16x32_bf16 v[70:73], v[162:165], v[220:223], v[70:73]
	v_mfma_f32_16x16x32_bf16 v[66:69], v[178:181], v[220:223], v[66:69]
	v_mfma_f32_16x16x32_bf16 v[114:117], v[166:169], v[190:193], v[114:117]
	v_mfma_f32_16x16x32_bf16 v[106:109], v[182:185], v[190:193], v[106:109]
	v_mfma_f32_16x16x32_bf16 v[98:101], v[166:169], v[198:201], v[98:101]
	v_mfma_f32_16x16x32_bf16 v[90:93], v[182:185], v[198:201], v[90:93]
	v_mfma_f32_16x16x32_bf16 v[82:85], v[166:169], v[216:219], v[82:85]
	v_mfma_f32_16x16x32_bf16 v[74:77], v[182:185], v[216:219], v[74:77]
	v_mfma_f32_16x16x32_bf16 v[70:73], v[166:169], v[224:227], v[70:73]
	v_mfma_f32_16x16x32_bf16 v[66:69], v[182:185], v[224:227], v[66:69]
	s_setprio 0
	s_barrier
	ds_read_b128 v[186:189], v144 offset:16384
	global_load_lds_dwordx4 v[172:173], off
	ds_read_b128 v[190:193], v144 offset:17408
	ds_read_b128 v[194:197], v144 offset:18432
	s_add_i32 m0, s48, 0x2000
	s_add_u32 s48, s28, 0x8000
	v_lshl_add_u64 v[174:175], s[28:29], 0, v[134:135]
	s_addc_u32 s49, s29, 0
	s_add_i32 s50, s50, s37
	global_load_lds_dwordx4 v[174:175], off
	ds_read_b128 v[198:201], v144 offset:19456
	ds_read_b128 v[212:215], v144 offset:20480
	v_lshl_add_u64 v[176:177], s[48:49], 0, v[0:1]
	s_mov_b32 m0, s50
	v_lshl_add_u64 v[228:229], s[30:31], 0, v[132:133]
	global_load_lds_dwordx4 v[176:177], off
	ds_read_b128 v[216:219], v144 offset:21504
	ds_read_b128 v[220:223], v144 offset:22528
	v_lshl_add_u64 v[176:177], s[48:49], 0, v[134:135]
	s_add_i32 m0, s50, 0x2000
	s_nop 0
	global_load_lds_dwordx4 v[176:177], off
	ds_read_b128 v[224:227], v144 offset:23552
	v_lshl_add_u64 v[176:177], s[30:31], 0, v[130:131]
	s_mov_b32 m0, s23
	s_nop 0
	global_load_lds_dwordx4 v[176:177], off
	s_mov_b32 m0, s25
	s_nop 0
	global_load_lds_dwordx4 v[228:229], off
	s_waitcnt vmcnt(8)
	s_waitcnt lgkmcnt(0)
	s_barrier
; #define PG8_STAGE(bufoff, gbase, voff) do { _Pragma("unroll") for (int _i = 0; _i < 2; ++_i) \
;         __builtin_amdgcn_global_load_lds((const unsigned*)((const char*)(gbase) + (voff)[_i]), (LAS unsigned*)(lds + (bufoff) + ldsw + _i * 8192), 16, 0, 0); } while (0)
; #define PG8_LDA(dst, b, h) do { _Pragma("unroll") for (int m = 0; m < 4; ++m) _Pragma("unroll") for (int k = 0; k < 2; ++k) dst[m][k] = *(const LAS bf16x8*)(lds + PG8_SA(b, h) + aoff + m * 2048 + k * 1024); } while (0)
; #define PG8_LDB(dst, b, h) do { _Pragma("unroll") for (int n = 0; n < 2; ++n) _Pragma("unroll") for (int k = 0; k < 2; ++k) dst[n][k] = *(const LAS bf16x8*)(lds + PG8_SB(b, h) + boff + n * 2048 + k * 1024); } while (0)
; #define PG8_MMA(ai, bj, At, Bt) do { __builtin_amdgcn_s_setprio(1); _Pragma("unroll") for (int m = 0; m < 4; ++m) _Pragma("unroll") for (int n = 0; n < 2; ++n) _Pragma("unroll") for (int k = 0; k < 2; ++k) \
;         acc[ai][bj][m][n] = __builtin_amdgcn_mfma_f32_16x16x32_bf16(Bt[n][k], At[m][k], acc[ai][bj][m][n], 0, 0, 0); __builtin_amdgcn_s_setprio(0); } while (0)
; #define PG8_WAIT_V(n) asm volatile("s_waitcnt vmcnt(" #n ")" ::: "memory")
; #define PG8_WAIT_L(n) asm volatile("s_waitcnt lgkmcnt(" #n ")" ::: "memory")
; #define PG8_BAR __builtin_amdgcn_s_barrier()
; #define PG8_SCHED __builtin_amdgcn_sched_barrier(0)
; template <class Epi>
; __device__ __forceinline__ void gemm_phase(LAS unsigned char* lds, const Gemm g, const StaticOrder& S, const Epi& E, const int tid) {
;     ...
;             PG8_WAIT_V(8); PG8_WAIT_L(0); PG8_BAR; PG8_MMA(1, 0, At, B0); PG8_MMA(1, 1, At, B1); PG8_BAR; PG8_SCHED;
;             PG8_LDB(B0, 1, 0); PG8_LDB(B1, 1, 1); PG8_SCHED; PG8_LDA(At, 1, 0); PG8_STAGE(PG8_SA(0, 1), a2 + hstep, voffA);
;             PG8_WAIT_V(8); PG8_WAIT_L(0); PG8_BAR; PG8_MMA(0, 0, At, B0); PG8_MMA(0, 1, At, B1); PG8_BAR; PG8_SCHED;
	s_setprio 1
	s_waitcnt lgkmcnt(0)
	v_mfma_f32_16x16x32_bf16 v[62:65], v[146:149], v[186:189], v[62:65]
	v_mfma_f32_16x16x32_bf16 v[58:61], v[154:157], v[186:189], v[58:61]
	s_add_i32 s48, 0, 0x18000
	v_mfma_f32_16x16x32_bf16 v[54:57], v[146:149], v[194:197], v[54:57]
	v_add_u32_e32 v145, s48, v142
	v_mfma_f32_16x16x32_bf16 v[46:49], v[154:157], v[194:197], v[46:49]
	s_add_i32 s49, 0, 0x1c000
	v_mfma_f32_16x16x32_bf16 v[38:41], v[146:149], v[212:215], v[38:41]
	v_mfma_f32_16x16x32_bf16 v[30:33], v[154:157], v[212:215], v[30:33]
	v_mfma_f32_16x16x32_bf16 v[22:25], v[146:149], v[220:223], v[22:25]
	v_mfma_f32_16x16x32_bf16 v[14:17], v[154:157], v[220:223], v[14:17]
	v_mfma_f32_16x16x32_bf16 v[62:65], v[150:153], v[190:193], v[62:65]
	v_mfma_f32_16x16x32_bf16 v[58:61], v[158:161], v[190:193], v[58:61]
	v_mfma_f32_16x16x32_bf16 v[54:57], v[150:153], v[198:201], v[54:57]
	v_mfma_f32_16x16x32_bf16 v[46:49], v[158:161], v[198:201], v[46:49]
	v_mfma_f32_16x16x32_bf16 v[38:41], v[150:153], v[216:219], v[38:41]
	v_mfma_f32_16x16x32_bf16 v[30:33], v[158:161], v[216:219], v[30:33]
	v_mfma_f32_16x16x32_bf16 v[22:25], v[150:153], v[224:227], v[22:25]
	v_mfma_f32_16x16x32_bf16 v[14:17], v[158:161], v[224:227], v[14:17]
	s_setprio 0
	s_setprio 1
	v_mfma_f32_16x16x32_bf16 v[50:53], v[162:165], v[186:189], v[50:53]
	v_mfma_f32_16x16x32_bf16 v[42:45], v[178:181], v[186:189], v[42:45]
	v_mfma_f32_16x16x32_bf16 v[34:37], v[162:165], v[194:197], v[34:37]
	v_mfma_f32_16x16x32_bf16 v[26:29], v[178:181], v[194:197], v[26:29]
	v_mfma_f32_16x16x32_bf16 v[18:21], v[162:165], v[212:215], v[18:21]
	v_mfma_f32_16x16x32_bf16 v[10:13], v[178:181], v[212:215], v[10:13]
	v_mfma_f32_16x16x32_bf16 v[6:9], v[162:165], v[220:223], v[6:9]
	v_mfma_f32_16x16x32_bf16 v[2:5], v[178:181], v[220:223], v[2:5]
	v_mfma_f32_16x16x32_bf16 v[50:53], v[166:169], v[190:193], v[50:53]
	v_mfma_f32_16x16x32_bf16 v[42:45], v[182:185], v[190:193], v[42:45]
	v_mfma_f32_16x16x32_bf16 v[34:37], v[166:169], v[198:201], v[34:37]
	v_mfma_f32_16x16x32_bf16 v[26:29], v[182:185], v[198:201], v[26:29]
	v_mfma_f32_16x16x32_bf16 v[18:21], v[166:169], v[216:219], v[18:21]
	v_mfma_f32_16x16x32_bf16 v[10:13], v[182:185], v[216:219], v[10:13]
	v_mfma_f32_16x16x32_bf16 v[6:9], v[166:169], v[224:227], v[6:9]
	v_mfma_f32_16x16x32_bf16 v[2:5], v[182:185], v[224:227], v[2:5]
	s_setprio 0
	s_barrier
	ds_read_b128 v[146:149], v145
	ds_read_b128 v[150:153], v145 offset:1024
	ds_read_b128 v[154:157], v145 offset:2048
	ds_read_b128 v[158:161], v145 offset:3072
	v_add_u32_e32 v145, s49, v142
	ds_read_b128 v[162:165], v145
	ds_read_b128 v[166:169], v145 offset:1024
	ds_read_b128 v[178:181], v145 offset:2048
	ds_read_b128 v[182:185], v145 offset:3072
	s_add_u32 s30, s30, 0x80000
	s_addc_u32 s31, s31, 0
	s_mov_b32 m0, s38
	v_lshl_add_u64 v[230:231], s[30:31], 0, v[130:131]
	ds_read_b128 v[186:189], v144 offset:32768
	global_load_lds_dwordx4 v[230:231], off
	ds_read_b128 v[190:193], v144 offset:33792
	ds_read_b128 v[194:197], v144 offset:34816
	v_lshl_add_u64 v[230:231], s[30:31], 0, v[132:133]
	s_mov_b32 m0, s39
	s_nop 0
	global_load_lds_dwordx4 v[230:231], off
	ds_read_b128 v[198:201], v144 offset:35840
	ds_read_b128 v[212:215], v144 offset:36864
	ds_read_b128 v[216:219], v144 offset:37888
	ds_read_b128 v[220:223], v144 offset:38912
	ds_read_b128 v[224:227], v144 offset:39936
	s_waitcnt vmcnt(8)
	s_waitcnt lgkmcnt(0)
	s_barrier
	s_setprio 1
	s_waitcnt lgkmcnt(0)
	v_mfma_f32_16x16x32_bf16 v[126:129], v[146:149], v[186:189], v[126:129]
	v_mfma_f32_16x16x32_bf16 v[122:125], v[154:157], v[186:189], v[122:125]
	s_add_i32 s30, s48, s37
	v_mfma_f32_16x16x32_bf16 v[118:121], v[146:149], v[194:197], v[118:121]
	v_lshl_add_u64 v[172:173], v[172:173], 0, s[70:71]
	v_mfma_f32_16x16x32_bf16 v[110:113], v[154:157], v[194:197], v[110:113]
	s_mov_b32 m0, s30
	v_mfma_f32_16x16x32_bf16 v[102:105], v[146:149], v[212:215], v[102:105]
	v_mfma_f32_16x16x32_bf16 v[94:97], v[154:157], v[212:215], v[94:97]
	v_mfma_f32_16x16x32_bf16 v[86:89], v[146:149], v[220:223], v[86:89]
	v_mfma_f32_16x16x32_bf16 v[78:81], v[154:157], v[220:223], v[78:81]
	v_mfma_f32_16x16x32_bf16 v[126:129], v[150:153], v[190:193], v[126:129]
	v_mfma_f32_16x16x32_bf16 v[122:125], v[158:161], v[190:193], v[122:125]
	v_mfma_f32_16x16x32_bf16 v[118:121], v[150:153], v[198:201], v[118:121]
	v_mfma_f32_16x16x32_bf16 v[110:113], v[158:161], v[198:201], v[110:113]
	v_mfma_f32_16x16x32_bf16 v[102:105], v[150:153], v[216:219], v[102:105]
	v_mfma_f32_16x16x32_bf16 v[94:97], v[158:161], v[216:219], v[94:97]
	v_mfma_f32_16x16x32_bf16 v[86:89], v[150:153], v[224:227], v[86:89]
	v_mfma_f32_16x16x32_bf16 v[78:81], v[158:161], v[224:227], v[78:81]
	s_setprio 0
	s_setprio 1
	v_mfma_f32_16x16x32_bf16 v[114:117], v[162:165], v[186:189], v[114:117]
	v_mfma_f32_16x16x32_bf16 v[106:109], v[178:181], v[186:189], v[106:109]
	v_mfma_f32_16x16x32_bf16 v[98:101], v[162:165], v[194:197], v[98:101]
	v_mfma_f32_16x16x32_bf16 v[90:93], v[178:181], v[194:197], v[90:93]
	v_mfma_f32_16x16x32_bf16 v[82:85], v[162:165], v[212:215], v[82:85]
	v_mfma_f32_16x16x32_bf16 v[74:77], v[178:181], v[212:215], v[74:77]
	v_mfma_f32_16x16x32_bf16 v[70:73], v[162:165], v[220:223], v[70:73]
	v_mfma_f32_16x16x32_bf16 v[66:69], v[178:181], v[220:223], v[66:69]
	v_mfma_f32_16x16x32_bf16 v[114:117], v[166:169], v[190:193], v[114:117]
	v_mfma_f32_16x16x32_bf16 v[106:109], v[182:185], v[190:193], v[106:109]
	v_mfma_f32_16x16x32_bf16 v[98:101], v[166:169], v[198:201], v[98:101]
	v_mfma_f32_16x16x32_bf16 v[90:93], v[182:185], v[198:201], v[90:93]
	v_mfma_f32_16x16x32_bf16 v[82:85], v[166:169], v[216:219], v[82:85]
	v_mfma_f32_16x16x32_bf16 v[74:77], v[182:185], v[216:219], v[74:77]
	v_mfma_f32_16x16x32_bf16 v[70:73], v[166:169], v[224:227], v[70:73]
	v_mfma_f32_16x16x32_bf16 v[66:69], v[182:185], v[224:227], v[66:69]
	s_setprio 0
	s_barrier
; #define PG8_STAGE(bufoff, gbase, voff) do { _Pragma("unroll") for (int _i = 0; _i < 2; ++_i) \
;         __builtin_amdgcn_global_load_lds((const unsigned*)((const char*)(gbase) + (voff)[_i]), (LAS unsigned*)(lds + (bufoff) + ldsw + _i * 8192), 16, 0, 0); } while (0)
; #define PG8_LDA(dst, b, h) do { _Pragma("unroll") for (int m = 0; m < 4; ++m) _Pragma("unroll") for (int k = 0; k < 2; ++k) dst[m][k] = *(const LAS bf16x8*)(lds + PG8_SA(b, h) + aoff + m * 2048 + k * 1024); } while (0)
; #define PG8_MMA(ai, bj, At, Bt) do { __builtin_amdgcn_s_setprio(1); _Pragma("unroll") for (int m = 0; m < 4; ++m) _Pragma("unroll") for (int n = 0; n < 2; ++n) _Pragma("unroll") for (int k = 0; k < 2; ++k) \
;         acc[ai][bj][m][n] = __builtin_amdgcn_mfma_f32_16x16x32_bf16(Bt[n][k], At[m][k], acc[ai][bj][m][n], 0, 0, 0); __builtin_amdgcn_s_setprio(0); } while (0)
; #define PG8_WAIT_V(n) asm volatile("s_waitcnt vmcnt(" #n ")" ::: "memory")
; #define PG8_WAIT_L(n) asm volatile("s_waitcnt lgkmcnt(" #n ")" ::: "memory")
; #define PG8_BAR __builtin_amdgcn_s_barrier()
; #define PG8_SCHED __builtin_amdgcn_sched_barrier(0)
; template <class Epi>
; __device__ __forceinline__ void gemm_phase(LAS unsigned char* lds, const Gemm g, const StaticOrder& S, const Epi& E, const int tid) {
;     ...
;             PG8_LDA(At, 1, 1); PG8_STAGE(PG8_SB(1, 0), b3, voffB); PG8_STAGE(PG8_SB(1, 1), b3 + bhs, voffB); PG8_STAGE(PG8_SA(1, 0), a3, voffA);
;             PG8_WAIT_V(8); PG8_WAIT_L(0); PG8_BAR; PG8_MMA(1, 0, At, B0); PG8_MMA(1, 1, At, B1); PG8_BAR; PG8_SCHED;
;     ...
;         if (ALIGN_EPI) { if (wr == 0) PG8_BAR; }
	ds_read_b128 v[186:189], v144 offset:49152
	global_load_lds_dwordx4 v[172:173], off
	ds_read_b128 v[190:193], v144 offset:50176
	ds_read_b128 v[194:197], v144 offset:51200
	s_add_i32 m0, s30, 0x2000
	s_add_u32 s28, s28, 0x8080
	v_lshl_add_u64 v[172:173], v[174:175], 0, s[70:71]
	s_addc_u32 s29, s29, 0
	s_add_i32 s30, s49, s37
	global_load_lds_dwordx4 v[172:173], off
	ds_read_b128 v[198:201], v144 offset:52224
	ds_read_b128 v[212:215], v144 offset:53248
	v_lshl_add_u64 v[172:173], s[28:29], 0, v[0:1]
	s_mov_b32 m0, s30
	s_nop 0
	global_load_lds_dwordx4 v[172:173], off
	ds_read_b128 v[216:219], v144 offset:54272
	ds_read_b128 v[220:223], v144 offset:55296
	v_lshl_add_u64 v[172:173], s[28:29], 0, v[134:135]
	s_add_i32 m0, s30, 0x2000
	s_nop 0
	global_load_lds_dwordx4 v[172:173], off
	ds_read_b128 v[224:227], v144 offset:56320
	v_lshl_add_u64 v[172:173], v[176:177], 0, s[70:71]
	s_mov_b32 m0, s40
	s_nop 0
	global_load_lds_dwordx4 v[172:173], off
	v_lshl_add_u64 v[172:173], v[228:229], 0, s[70:71]
	s_mov_b32 m0, s41
	s_nop 0
	global_load_lds_dwordx4 v[172:173], off
	s_waitcnt vmcnt(8)
	s_waitcnt lgkmcnt(0)
	s_barrier
	s_setprio 1
	s_waitcnt lgkmcnt(0)
	v_mfma_f32_16x16x32_bf16 v[62:65], v[146:149], v[186:189], v[62:65]
	v_mfma_f32_16x16x32_bf16 v[58:61], v[154:157], v[186:189], v[58:61]
	s_add_i32 s47, s47, 2
	v_mfma_f32_16x16x32_bf16 v[54:57], v[146:149], v[194:197], v[54:57]
	s_add_u32 s45, s45, 0x100
	v_mfma_f32_16x16x32_bf16 v[46:49], v[154:157], v[194:197], v[46:49]
	s_addc_u32 s46, s46, 0
	v_mfma_f32_16x16x32_bf16 v[38:41], v[146:149], v[212:215], v[38:41]
	s_add_u32 s26, s26, 0x100
	v_mfma_f32_16x16x32_bf16 v[30:33], v[154:157], v[212:215], v[30:33]
	s_addc_u32 s27, s27, 0
	v_mfma_f32_16x16x32_bf16 v[22:25], v[146:149], v[220:223], v[22:25]
	v_mfma_f32_16x16x32_bf16 v[14:17], v[154:157], v[220:223], v[14:17]
	v_mfma_f32_16x16x32_bf16 v[62:65], v[150:153], v[190:193], v[62:65]
	v_mfma_f32_16x16x32_bf16 v[58:61], v[158:161], v[190:193], v[58:61]
	v_mfma_f32_16x16x32_bf16 v[54:57], v[150:153], v[198:201], v[54:57]
	v_mfma_f32_16x16x32_bf16 v[46:49], v[158:161], v[198:201], v[46:49]
	v_mfma_f32_16x16x32_bf16 v[38:41], v[150:153], v[216:219], v[38:41]
	v_mfma_f32_16x16x32_bf16 v[30:33], v[158:161], v[216:219], v[30:33]
	v_mfma_f32_16x16x32_bf16 v[22:25], v[150:153], v[224:227], v[22:25]
	v_mfma_f32_16x16x32_bf16 v[14:17], v[158:161], v[224:227], v[14:17]
	s_setprio 0
	s_setprio 1
	v_mfma_f32_16x16x32_bf16 v[50:53], v[162:165], v[186:189], v[50:53]
	v_mfma_f32_16x16x32_bf16 v[42:45], v[178:181], v[186:189], v[42:45]
	v_mfma_f32_16x16x32_bf16 v[34:37], v[162:165], v[194:197], v[34:37]
	v_mfma_f32_16x16x32_bf16 v[26:29], v[178:181], v[194:197], v[26:29]
	v_mfma_f32_16x16x32_bf16 v[18:21], v[162:165], v[212:215], v[18:21]
	v_mfma_f32_16x16x32_bf16 v[10:13], v[178:181], v[212:215], v[10:13]
	v_mfma_f32_16x16x32_bf16 v[6:9], v[162:165], v[220:223], v[6:9]
	v_mfma_f32_16x16x32_bf16 v[2:5], v[178:181], v[220:223], v[2:5]
	v_mfma_f32_16x16x32_bf16 v[50:53], v[166:169], v[190:193], v[50:53]
	v_mfma_f32_16x16x32_bf16 v[42:45], v[182:185], v[190:193], v[42:45]
	v_mfma_f32_16x16x32_bf16 v[34:37], v[166:169], v[198:201], v[34:37]
	v_mfma_f32_16x16x32_bf16 v[26:29], v[182:185], v[198:201], v[26:29]
	v_mfma_f32_16x16x32_bf16 v[18:21], v[166:169], v[216:219], v[18:21]
	v_mfma_f32_16x16x32_bf16 v[10:13], v[182:185], v[216:219], v[10:13]
	v_mfma_f32_16x16x32_bf16 v[6:9], v[166:169], v[224:227], v[6:9]
	v_mfma_f32_16x16x32_bf16 v[2:5], v[182:185], v[224:227], v[2:5]
	s_setprio 0
	s_barrier
	s_cmp_gt_u32 s47, 29
	s_cbranch_scc0 .LBB0_844
	s_and_b64 vcc, exec, s[10:11]
	s_cbranch_vccz .LBB0_847
	s_barrier

; #define PG8_STAGE(bufoff, gbase, voff) do { _Pragma("unroll") for (int _i = 0; _i < 2; ++_i) \
;         __builtin_amdgcn_global_load_lds((const unsigned*)((const char*)(gbase) + (voff)[_i]), (LAS unsigned*)(lds + (bufoff) + ldsw + _i * 8192), 16, 0, 0); } while (0)
; #define PG8_LDA(dst, b, h) do { _Pragma("unroll") for (int m = 0; m < 4; ++m) _Pragma("unroll") for (int k = 0; k < 2; ++k) dst[m][k] = *(const LAS bf16x8*)(lds + PG8_SA(b, h) + aoff + m * 2048 + k * 1024); } while (0)
; #define PG8_LDB(dst, b, h) do { _Pragma("unroll") for (int n = 0; n < 2; ++n) _Pragma("unroll") for (int k = 0; k < 2; ++k) dst[n][k] = *(const LAS bf16x8*)(lds + PG8_SB(b, h) + boff + n * 2048 + k * 1024); } while (0)
; #define PG8_MMA(ai, bj, At, Bt) do { __builtin_amdgcn_s_setprio(1); _Pragma("unroll") for (int m = 0; m < 4; ++m) _Pragma("unroll") for (int n = 0; n < 2; ++n) _Pragma("unroll") for (int k = 0; k < 2; ++k) \
;         acc[ai][bj][m][n] = __builtin_amdgcn_mfma_f32_16x16x32_bf16(Bt[n][k], At[m][k], acc[ai][bj][m][n], 0, 0, 0); __builtin_amdgcn_s_setprio(0); } while (0)
; #define PG8_BAR __builtin_amdgcn_s_barrier()
; template <class Epi>
; __device__ __forceinline__ void gemm_phase(LAS unsigned char* lds, const Gemm g, const StaticOrder& S, const Epi& E, const int tid) {
;     ...
;         for (int t = 0; t < ntt; t += 2) {
;             const bool last = (t == ntt - 2);
;             const bool s1 = Epi::TWO && (t >= nt), s2 = Epi::TWO && (t + 2 >= nt);
;             const char* a1 = (s1 ? cA2 + (size_t)(t - nt + 1) * kstep : cA + (size_t)(t + 1) * kstep);
;             const char* a2 = last ? nA : (s2 ? cA2 + (size_t)(t + 2 - nt) * kstep : cA + (size_t)(t + 2) * kstep);
;             const char* b2 = last ? nB : (s2 ? cB2 + (size_t)(t + 2 - nt) * kstep : cB + (size_t)(t + 2) * kstep);
;             const char* a3 = a2 + kstep; const char* b3 = b2 + kstep;
;             if constexpr (Epi::TWO) { if (t == nt) E.mid(acc, cur, wr, wc, fr, fq); }
;             if constexpr (SP2) {
;             PG8_LDB(B0, 0, 0); PG8_LDB(B1, 0, 1); PG8_SCHED; PG8_LDA(At, 0, 0); PG8_STAGE(PG8_SA(1, 1), a1 + hstep, voffA);
;             PG8_WAIT_V(8); PG8_WAIT_L(0); PG8_BAR; PG8_MMA(0, 0, At, B0); PG8_MMA(0, 1, At, B1); PG8_BAR; PG8_SCHED;
;             PG8_LDA(At, 0, 1); PG8_STAGE(PG8_SB(0, 0), b2, voffB); PG8_STAGE(PG8_SB(0, 1), b2 + bhs, voffB); PG8_STAGE(PG8_SA(0, 0), a2, voffA);
.LBB0_861:
	s_add_u32 s30, s28, 0xfff80080
	s_addc_u32 s31, s29, -1
	s_add_i32 s51, 0, 0x10000
	s_cmp_eq_u32 s50, 28
	s_cselect_b32 s35, s17, s31
	s_cselect_b32 s34, s46, s30
	v_add_u32_e32 v145, s51, v142
	s_cselect_b32 s31, s15, s49
	s_cselect_b32 s30, s47, s48
	s_add_i32 s54, 0, 0x14000
	ds_read_b128 v[146:149], v145
	ds_read_b128 v[150:153], v145 offset:1024
	ds_read_b128 v[154:157], v145 offset:2048
	ds_read_b128 v[158:161], v145 offset:3072
	v_add_u32_e32 v145, s54, v142
	ds_read_b128 v[162:165], v145
	ds_read_b128 v[166:169], v145 offset:1024
	ds_read_b128 v[178:181], v145 offset:2048
	ds_read_b128 v[182:185], v145 offset:3072
	v_lshl_add_u64 v[172:173], s[28:29], 0, v[138:139]
	s_add_i32 m0, s25, 0xc000
	ds_read_b128 v[186:189], v144
	global_load_lds_dwordx4 v[172:173], off
	ds_read_b128 v[190:193], v144 offset:1024
	ds_read_b128 v[194:197], v144 offset:2048
	v_lshl_add_u64 v[172:173], s[28:29], 0, v[136:137]
	s_add_i32 m0, s25, 0xe000
	s_nop 0
	global_load_lds_dwordx4 v[172:173], off
	ds_read_b128 v[198:201], v144 offset:3072
	ds_read_b128 v[212:215], v144 offset:4096
	ds_read_b128 v[216:219], v144 offset:5120
	ds_read_b128 v[220:223], v144 offset:6144
	ds_read_b128 v[224:227], v144 offset:7168
	s_waitcnt vmcnt(8)
	s_waitcnt lgkmcnt(0)
	s_barrier
	s_setprio 1
	s_waitcnt lgkmcnt(0)
	v_mfma_f32_16x16x32_bf16 v[126:129], v[146:149], v[186:189], v[126:129]
	v_mfma_f32_16x16x32_bf16 v[122:125], v[154:157], v[186:189], v[122:125]
	s_add_i32 s51, s51, s40
	v_mfma_f32_16x16x32_bf16 v[118:121], v[146:149], v[194:197], v[118:121]
	v_lshl_add_u64 v[172:173], s[30:31], 0, v[0:1]
	v_mfma_f32_16x16x32_bf16 v[110:113], v[154:157], v[194:197], v[110:113]
	s_mov_b32 m0, s51
	v_mfma_f32_16x16x32_bf16 v[102:105], v[146:149], v[212:215], v[102:105]
	v_mfma_f32_16x16x32_bf16 v[94:97], v[154:157], v[212:215], v[94:97]
	v_mfma_f32_16x16x32_bf16 v[86:89], v[146:149], v[220:223], v[86:89]
	v_mfma_f32_16x16x32_bf16 v[78:81], v[154:157], v[220:223], v[78:81]
	v_mfma_f32_16x16x32_bf16 v[126:129], v[150:153], v[190:193], v[126:129]
	v_mfma_f32_16x16x32_bf16 v[122:125], v[158:161], v[190:193], v[122:125]
	v_mfma_f32_16x16x32_bf16 v[118:121], v[150:153], v[198:201], v[118:121]
	v_mfma_f32_16x16x32_bf16 v[110:113], v[158:161], v[198:201], v[110:113]
	v_mfma_f32_16x16x32_bf16 v[102:105], v[150:153], v[216:219], v[102:105]
	v_mfma_f32_16x16x32_bf16 v[94:97], v[158:161], v[216:219], v[94:97]
	v_mfma_f32_16x16x32_bf16 v[86:89], v[150:153], v[224:227], v[86:89]
	v_mfma_f32_16x16x32_bf16 v[78:81], v[158:161], v[224:227], v[78:81]
	s_setprio 0
	s_setprio 1
	v_mfma_f32_16x16x32_bf16 v[114:117], v[162:165], v[186:189], v[114:117]
	v_mfma_f32_16x16x32_bf16 v[106:109], v[178:181], v[186:189], v[106:109]
	v_mfma_f32_16x16x32_bf16 v[98:101], v[162:165], v[194:197], v[98:101]
	v_mfma_f32_16x16x32_bf16 v[90:93], v[178:181], v[194:197], v[90:93]
	v_mfma_f32_16x16x32_bf16 v[82:85], v[162:165], v[212:215], v[82:85]
	v_mfma_f32_16x16x32_bf16 v[74:77], v[178:181], v[212:215], v[74:77]
	v_mfma_f32_16x16x32_bf16 v[70:73], v[162:165], v[220:223], v[70:73]
	v_mfma_f32_16x16x32_bf16 v[66:69], v[178:181], v[220:223], v[66:69]
	v_mfma_f32_16x16x32_bf16 v[114:117], v[166:169], v[190:193], v[114:117]
	v_mfma_f32_16x16x32_bf16 v[106:109], v[182:185], v[190:193], v[106:109]
	v_mfma_f32_16x16x32_bf16 v[98:101], v[166:169], v[198:201], v[98:101]
	v_mfma_f32_16x16x32_bf16 v[90:93], v[182:185], v[198:201], v[90:93]
	v_mfma_f32_16x16x32_bf16 v[82:85], v[166:169], v[216:219], v[82:85]
	v_mfma_f32_16x16x32_bf16 v[74:77], v[182:185], v[216:219], v[74:77]
	v_mfma_f32_16x16x32_bf16 v[70:73], v[166:169], v[224:227], v[70:73]
	v_mfma_f32_16x16x32_bf16 v[66:69], v[182:185], v[224:227], v[66:69]
	s_setprio 0
	s_barrier
	ds_read_b128 v[186:189], v144 offset:16384
	global_load_lds_dwordx4 v[172:173], off
	ds_read_b128 v[190:193], v144 offset:17408
	ds_read_b128 v[194:197], v144 offset:18432
	s_add_i32 m0, s51, 0x2000
	s_add_u32 s52, s30, 0x8000
	v_lshl_add_u64 v[174:175], s[30:31], 0, v[134:135]
	s_addc_u32 s53, s31, 0
	s_add_i32 s51, s54, s40
	global_load_lds_dwordx4 v[174:175], off
	ds_read_b128 v[198:201], v144 offset:19456
	ds_read_b128 v[212:215], v144 offset:20480
	v_lshl_add_u64 v[176:177], s[52:53], 0, v[0:1]
	s_mov_b32 m0, s51
	v_lshl_add_u64 v[228:229], s[34:35], 0, v[132:133]
	global_load_lds_dwordx4 v[176:177], off
	ds_read_b128 v[216:219], v144 offset:21504
	ds_read_b128 v[220:223], v144 offset:22528
	v_lshl_add_u64 v[176:177], s[52:53], 0, v[134:135]
	s_add_i32 m0, s51, 0x2000
	s_nop 0
	global_load_lds_dwordx4 v[176:177], off
	ds_read_b128 v[224:227], v144 offset:23552
	v_lshl_add_u64 v[176:177], s[34:35], 0, v[130:131]
	s_mov_b32 m0, s25
	s_nop 0
	global_load_lds_dwordx4 v[176:177], off
	s_mov_b32 m0, s27
	s_nop 0
	global_load_lds_dwordx4 v[228:229], off
	s_waitcnt vmcnt(8)
	s_waitcnt lgkmcnt(0)
	s_barrier
; #define PG8_STAGE(bufoff, gbase, voff) do { _Pragma("unroll") for (int _i = 0; _i < 2; ++_i) \
;         __builtin_amdgcn_global_load_lds((const unsigned*)((const char*)(gbase) + (voff)[_i]), (LAS unsigned*)(lds + (bufoff) + ldsw + _i * 8192), 16, 0, 0); } while (0)
; #define PG8_LDA(dst, b, h) do { _Pragma("unroll") for (int m = 0; m < 4; ++m) _Pragma("unroll") for (int k = 0; k < 2; ++k) dst[m][k] = *(const LAS bf16x8*)(lds + PG8_SA(b, h) + aoff + m * 2048 + k * 1024); } while (0)
; #define PG8_LDB(dst, b, h) do { _Pragma("unroll") for (int n = 0; n < 2; ++n) _Pragma("unroll") for (int k = 0; k < 2; ++k) dst[n][k] = *(const LAS bf16x8*)(lds + PG8_SB(b, h) + boff + n * 2048 + k * 1024); } while (0)
; #define PG8_MMA(ai, bj, At, Bt) do { __builtin_amdgcn_s_setprio(1); _Pragma("unroll") for (int m = 0; m < 4; ++m) _Pragma("unroll") for (int n = 0; n < 2; ++n) _Pragma("unroll") for (int k = 0; k < 2; ++k) \
;         acc[ai][bj][m][n] = __builtin_amdgcn_mfma_f32_16x16x32_bf16(Bt[n][k], At[m][k], acc[ai][bj][m][n], 0, 0, 0); __builtin_amdgcn_s_setprio(0); } while (0)
; #define PG8_WAIT_V(n) asm volatile("s_waitcnt vmcnt(" #n ")" ::: "memory")
; #define PG8_WAIT_L(n) asm volatile("s_waitcnt lgkmcnt(" #n ")" ::: "memory")
; #define PG8_BAR __builtin_amdgcn_s_barrier()
; #define PG8_SCHED __builtin_amdgcn_sched_barrier(0)
; template <class Epi>
; __device__ __forceinline__ void gemm_phase(LAS unsigned char* lds, const Gemm g, const StaticOrder& S, const Epi& E, const int tid) {
;     ...
;             PG8_WAIT_V(8); PG8_WAIT_L(0); PG8_BAR; PG8_MMA(1, 0, At, B0); PG8_MMA(1, 1, At, B1); PG8_BAR; PG8_SCHED;
;             PG8_LDB(B0, 1, 0); PG8_LDB(B1, 1, 1); PG8_SCHED; PG8_LDA(At, 1, 0); PG8_STAGE(PG8_SA(0, 1), a2 + hstep, voffA);
;             PG8_WAIT_V(8); PG8_WAIT_L(0); PG8_BAR; PG8_MMA(0, 0, At, B0); PG8_MMA(0, 1, At, B1); PG8_BAR; PG8_SCHED;
	s_setprio 1
	s_waitcnt lgkmcnt(0)
	v_mfma_f32_16x16x32_bf16 v[62:65], v[146:149], v[186:189], v[62:65]
	v_mfma_f32_16x16x32_bf16 v[58:61], v[154:157], v[186:189], v[58:61]
	s_add_i32 s51, 0, 0x18000
	v_mfma_f32_16x16x32_bf16 v[54:57], v[146:149], v[194:197], v[54:57]
	v_add_u32_e32 v145, s51, v142
	v_mfma_f32_16x16x32_bf16 v[46:49], v[154:157], v[194:197], v[46:49]
	s_add_i32 s52, 0, 0x1c000
	v_mfma_f32_16x16x32_bf16 v[38:41], v[146:149], v[212:215], v[38:41]
	v_mfma_f32_16x16x32_bf16 v[30:33], v[154:157], v[212:215], v[30:33]
	v_mfma_f32_16x16x32_bf16 v[22:25], v[146:149], v[220:223], v[22:25]
	v_mfma_f32_16x16x32_bf16 v[14:17], v[154:157], v[220:223], v[14:17]
	v_mfma_f32_16x16x32_bf16 v[62:65], v[150:153], v[190:193], v[62:65]
	v_mfma_f32_16x16x32_bf16 v[58:61], v[158:161], v[190:193], v[58:61]
	v_mfma_f32_16x16x32_bf16 v[54:57], v[150:153], v[198:201], v[54:57]
	v_mfma_f32_16x16x32_bf16 v[46:49], v[158:161], v[198:201], v[46:49]
	v_mfma_f32_16x16x32_bf16 v[38:41], v[150:153], v[216:219], v[38:41]
	v_mfma_f32_16x16x32_bf16 v[30:33], v[158:161], v[216:219], v[30:33]
	v_mfma_f32_16x16x32_bf16 v[22:25], v[150:153], v[224:227], v[22:25]
	v_mfma_f32_16x16x32_bf16 v[14:17], v[158:161], v[224:227], v[14:17]
	s_setprio 0
	s_setprio 1
	v_mfma_f32_16x16x32_bf16 v[50:53], v[162:165], v[186:189], v[50:53]
	v_mfma_f32_16x16x32_bf16 v[42:45], v[178:181], v[186:189], v[42:45]
	v_mfma_f32_16x16x32_bf16 v[34:37], v[162:165], v[194:197], v[34:37]
	v_mfma_f32_16x16x32_bf16 v[26:29], v[178:181], v[194:197], v[26:29]
	v_mfma_f32_16x16x32_bf16 v[18:21], v[162:165], v[212:215], v[18:21]
	v_mfma_f32_16x16x32_bf16 v[10:13], v[178:181], v[212:215], v[10:13]
	v_mfma_f32_16x16x32_bf16 v[6:9], v[162:165], v[220:223], v[6:9]
	v_mfma_f32_16x16x32_bf16 v[2:5], v[178:181], v[220:223], v[2:5]
	v_mfma_f32_16x16x32_bf16 v[50:53], v[166:169], v[190:193], v[50:53]
	v_mfma_f32_16x16x32_bf16 v[42:45], v[182:185], v[190:193], v[42:45]
	v_mfma_f32_16x16x32_bf16 v[34:37], v[166:169], v[198:201], v[34:37]
	v_mfma_f32_16x16x32_bf16 v[26:29], v[182:185], v[198:201], v[26:29]
	v_mfma_f32_16x16x32_bf16 v[18:21], v[166:169], v[216:219], v[18:21]
	v_mfma_f32_16x16x32_bf16 v[10:13], v[182:185], v[216:219], v[10:13]
	v_mfma_f32_16x16x32_bf16 v[6:9], v[166:169], v[224:227], v[6:9]
	v_mfma_f32_16x16x32_bf16 v[2:5], v[182:185], v[224:227], v[2:5]
	s_setprio 0
	s_barrier
	ds_read_b128 v[146:149], v145
	ds_read_b128 v[150:153], v145 offset:1024
	ds_read_b128 v[154:157], v145 offset:2048
	ds_read_b128 v[158:161], v145 offset:3072
	v_add_u32_e32 v145, s52, v142
	ds_read_b128 v[162:165], v145
	ds_read_b128 v[166:169], v145 offset:1024
	ds_read_b128 v[178:181], v145 offset:2048
	ds_read_b128 v[182:185], v145 offset:3072
	s_add_u32 s34, s34, 0x80000
	s_addc_u32 s35, s35, 0
	s_mov_b32 m0, s41
	v_lshl_add_u64 v[230:231], s[34:35], 0, v[130:131]
	ds_read_b128 v[186:189], v144 offset:32768
	global_load_lds_dwordx4 v[230:231], off
	ds_read_b128 v[190:193], v144 offset:33792
	ds_read_b128 v[194:197], v144 offset:34816
	v_lshl_add_u64 v[230:231], s[34:35], 0, v[132:133]
	s_mov_b32 m0, s42
	s_nop 0
	global_load_lds_dwordx4 v[230:231], off
	ds_read_b128 v[198:201], v144 offset:35840
	ds_read_b128 v[212:215], v144 offset:36864
	ds_read_b128 v[216:219], v144 offset:37888
	ds_read_b128 v[220:223], v144 offset:38912
	ds_read_b128 v[224:227], v144 offset:39936
	s_waitcnt vmcnt(8)
	s_waitcnt lgkmcnt(0)
	s_barrier
	s_setprio 1
	s_waitcnt lgkmcnt(0)
	v_mfma_f32_16x16x32_bf16 v[126:129], v[146:149], v[186:189], v[126:129]
	v_mfma_f32_16x16x32_bf16 v[122:125], v[154:157], v[186:189], v[122:125]
	s_add_i32 s34, s51, s40
	v_mfma_f32_16x16x32_bf16 v[118:121], v[146:149], v[194:197], v[118:121]
	v_lshl_add_u64 v[172:173], v[172:173], 0, s[70:71]
	v_mfma_f32_16x16x32_bf16 v[110:113], v[154:157], v[194:197], v[110:113]
	s_mov_b32 m0, s34
	v_mfma_f32_16x16x32_bf16 v[102:105], v[146:149], v[212:215], v[102:105]
	v_mfma_f32_16x16x32_bf16 v[94:97], v[154:157], v[212:215], v[94:97]
	v_mfma_f32_16x16x32_bf16 v[86:89], v[146:149], v[220:223], v[86:89]
	v_mfma_f32_16x16x32_bf16 v[78:81], v[154:157], v[220:223], v[78:81]
	v_mfma_f32_16x16x32_bf16 v[126:129], v[150:153], v[190:193], v[126:129]
	v_mfma_f32_16x16x32_bf16 v[122:125], v[158:161], v[190:193], v[122:125]
	v_mfma_f32_16x16x32_bf16 v[118:121], v[150:153], v[198:201], v[118:121]
	v_mfma_f32_16x16x32_bf16 v[110:113], v[158:161], v[198:201], v[110:113]
	v_mfma_f32_16x16x32_bf16 v[102:105], v[150:153], v[216:219], v[102:105]
	v_mfma_f32_16x16x32_bf16 v[94:97], v[158:161], v[216:219], v[94:97]
	v_mfma_f32_16x16x32_bf16 v[86:89], v[150:153], v[224:227], v[86:89]
	v_mfma_f32_16x16x32_bf16 v[78:81], v[158:161], v[224:227], v[78:81]
	s_setprio 0
	s_setprio 1
	v_mfma_f32_16x16x32_bf16 v[114:117], v[162:165], v[186:189], v[114:117]
	v_mfma_f32_16x16x32_bf16 v[106:109], v[178:181], v[186:189], v[106:109]
	v_mfma_f32_16x16x32_bf16 v[98:101], v[162:165], v[194:197], v[98:101]
	v_mfma_f32_16x16x32_bf16 v[90:93], v[178:181], v[194:197], v[90:93]
	v_mfma_f32_16x16x32_bf16 v[82:85], v[162:165], v[212:215], v[82:85]
	v_mfma_f32_16x16x32_bf16 v[74:77], v[178:181], v[212:215], v[74:77]
	v_mfma_f32_16x16x32_bf16 v[70:73], v[162:165], v[220:223], v[70:73]
	v_mfma_f32_16x16x32_bf16 v[66:69], v[178:181], v[220:223], v[66:69]
	v_mfma_f32_16x16x32_bf16 v[114:117], v[166:169], v[190:193], v[114:117]
	v_mfma_f32_16x16x32_bf16 v[106:109], v[182:185], v[190:193], v[106:109]
	v_mfma_f32_16x16x32_bf16 v[98:101], v[166:169], v[198:201], v[98:101]
	v_mfma_f32_16x16x32_bf16 v[90:93], v[182:185], v[198:201], v[90:93]
	v_mfma_f32_16x16x32_bf16 v[82:85], v[166:169], v[216:219], v[82:85]
	v_mfma_f32_16x16x32_bf16 v[74:77], v[182:185], v[216:219], v[74:77]
	v_mfma_f32_16x16x32_bf16 v[70:73], v[166:169], v[224:227], v[70:73]
	v_mfma_f32_16x16x32_bf16 v[66:69], v[182:185], v[224:227], v[66:69]
	s_setprio 0
	s_barrier
; #define PG8_STAGE(bufoff, gbase, voff) do { _Pragma("unroll") for (int _i = 0; _i < 2; ++_i) \
;         __builtin_amdgcn_global_load_lds((const unsigned*)((const char*)(gbase) + (voff)[_i]), (LAS unsigned*)(lds + (bufoff) + ldsw + _i * 8192), 16, 0, 0); } while (0)
; #define PG8_LDA(dst, b, h) do { _Pragma("unroll") for (int m = 0; m < 4; ++m) _Pragma("unroll") for (int k = 0; k < 2; ++k) dst[m][k] = *(const LAS bf16x8*)(lds + PG8_SA(b, h) + aoff + m * 2048 + k * 1024); } while (0)
; #define PG8_MMA(ai, bj, At, Bt) do { __builtin_amdgcn_s_setprio(1); _Pragma("unroll") for (int m = 0; m < 4; ++m) _Pragma("unroll") for (int n = 0; n < 2; ++n) _Pragma("unroll") for (int k = 0; k < 2; ++k) \
;         acc[ai][bj][m][n] = __builtin_amdgcn_mfma_f32_16x16x32_bf16(Bt[n][k], At[m][k], acc[ai][bj][m][n], 0, 0, 0); __builtin_amdgcn_s_setprio(0); } while (0)
; #define PG8_WAIT_V(n) asm volatile("s_waitcnt vmcnt(" #n ")" ::: "memory")
; #define PG8_WAIT_L(n) asm volatile("s_waitcnt lgkmcnt(" #n ")" ::: "memory")
; #define PG8_BAR __builtin_amdgcn_s_barrier()
; #define PG8_SCHED __builtin_amdgcn_sched_barrier(0)
; template <class Epi>
; __device__ __forceinline__ void gemm_phase(LAS unsigned char* lds, const Gemm g, const StaticOrder& S, const Epi& E, const int tid) {
;     ...
;             PG8_LDA(At, 1, 1); PG8_STAGE(PG8_SB(1, 0), b3, voffB); PG8_STAGE(PG8_SB(1, 1), b3 + bhs, voffB); PG8_STAGE(PG8_SA(1, 0), a3, voffA);
;             PG8_WAIT_V(8); PG8_WAIT_L(0); PG8_BAR; PG8_MMA(1, 0, At, B0); PG8_MMA(1, 1, At, B1); PG8_BAR; PG8_SCHED;
;     ...
;         if (ALIGN_EPI) { if (wr == 0) PG8_BAR; }
	ds_read_b128 v[186:189], v144 offset:49152
	global_load_lds_dwordx4 v[172:173], off
	ds_read_b128 v[190:193], v144 offset:50176
	ds_read_b128 v[194:197], v144 offset:51200
	s_add_i32 m0, s34, 0x2000
	s_add_u32 s30, s30, 0x8080
	v_lshl_add_u64 v[172:173], v[174:175], 0, s[70:71]
	s_addc_u32 s31, s31, 0
	s_add_i32 s34, s52, s40
	global_load_lds_dwordx4 v[172:173], off
	ds_read_b128 v[198:201], v144 offset:52224
	ds_read_b128 v[212:215], v144 offset:53248
	v_lshl_add_u64 v[172:173], s[30:31], 0, v[0:1]
	s_mov_b32 m0, s34
	s_nop 0
	global_load_lds_dwordx4 v[172:173], off
	ds_read_b128 v[216:219], v144 offset:54272
	ds_read_b128 v[220:223], v144 offset:55296
	v_lshl_add_u64 v[172:173], s[30:31], 0, v[134:135]
	s_add_i32 m0, s34, 0x2000
	s_nop 0
	global_load_lds_dwordx4 v[172:173], off
	ds_read_b128 v[224:227], v144 offset:56320
	v_lshl_add_u64 v[172:173], v[176:177], 0, s[70:71]
	s_mov_b32 m0, s43
	s_nop 0
	global_load_lds_dwordx4 v[172:173], off
	v_lshl_add_u64 v[172:173], v[228:229], 0, s[70:71]
	s_mov_b32 m0, s44
	s_nop 0
	global_load_lds_dwordx4 v[172:173], off
	s_waitcnt vmcnt(8)
	s_waitcnt lgkmcnt(0)
	s_barrier
	s_setprio 1
	s_waitcnt lgkmcnt(0)
	v_mfma_f32_16x16x32_bf16 v[62:65], v[146:149], v[186:189], v[62:65]
	v_mfma_f32_16x16x32_bf16 v[58:61], v[154:157], v[186:189], v[58:61]
	s_add_i32 s50, s50, 2
	v_mfma_f32_16x16x32_bf16 v[54:57], v[146:149], v[194:197], v[54:57]
	s_add_u32 s48, s48, 0x100
	v_mfma_f32_16x16x32_bf16 v[46:49], v[154:157], v[194:197], v[46:49]
	s_addc_u32 s49, s49, 0
	v_mfma_f32_16x16x32_bf16 v[38:41], v[146:149], v[212:215], v[38:41]
	s_add_u32 s28, s28, 0x100
	v_mfma_f32_16x16x32_bf16 v[30:33], v[154:157], v[212:215], v[30:33]
	s_addc_u32 s29, s29, 0
	v_mfma_f32_16x16x32_bf16 v[22:25], v[146:149], v[220:223], v[22:25]
	v_mfma_f32_16x16x32_bf16 v[14:17], v[154:157], v[220:223], v[14:17]
	v_mfma_f32_16x16x32_bf16 v[62:65], v[150:153], v[190:193], v[62:65]
	v_mfma_f32_16x16x32_bf16 v[58:61], v[158:161], v[190:193], v[58:61]
	v_mfma_f32_16x16x32_bf16 v[54:57], v[150:153], v[198:201], v[54:57]
	v_mfma_f32_16x16x32_bf16 v[46:49], v[158:161], v[198:201], v[46:49]
	v_mfma_f32_16x16x32_bf16 v[38:41], v[150:153], v[216:219], v[38:41]
	v_mfma_f32_16x16x32_bf16 v[30:33], v[158:161], v[216:219], v[30:33]
	v_mfma_f32_16x16x32_bf16 v[22:25], v[150:153], v[224:227], v[22:25]
	v_mfma_f32_16x16x32_bf16 v[14:17], v[158:161], v[224:227], v[14:17]
	s_setprio 0
	s_setprio 1
	v_mfma_f32_16x16x32_bf16 v[50:53], v[162:165], v[186:189], v[50:53]
	v_mfma_f32_16x16x32_bf16 v[42:45], v[178:181], v[186:189], v[42:45]
	v_mfma_f32_16x16x32_bf16 v[34:37], v[162:165], v[194:197], v[34:37]
	v_mfma_f32_16x16x32_bf16 v[26:29], v[178:181], v[194:197], v[26:29]
	v_mfma_f32_16x16x32_bf16 v[18:21], v[162:165], v[212:215], v[18:21]
	v_mfma_f32_16x16x32_bf16 v[10:13], v[178:181], v[212:215], v[10:13]
	v_mfma_f32_16x16x32_bf16 v[6:9], v[162:165], v[220:223], v[6:9]
	v_mfma_f32_16x16x32_bf16 v[2:5], v[178:181], v[220:223], v[2:5]
	v_mfma_f32_16x16x32_bf16 v[50:53], v[166:169], v[190:193], v[50:53]
	v_mfma_f32_16x16x32_bf16 v[42:45], v[182:185], v[190:193], v[42:45]
	v_mfma_f32_16x16x32_bf16 v[34:37], v[166:169], v[198:201], v[34:37]
	v_mfma_f32_16x16x32_bf16 v[26:29], v[182:185], v[198:201], v[26:29]
	v_mfma_f32_16x16x32_bf16 v[18:21], v[166:169], v[216:219], v[18:21]
	v_mfma_f32_16x16x32_bf16 v[10:13], v[182:185], v[216:219], v[10:13]
	v_mfma_f32_16x16x32_bf16 v[6:9], v[166:169], v[224:227], v[6:9]
	v_mfma_f32_16x16x32_bf16 v[2:5], v[182:185], v[224:227], v[2:5]
	s_setprio 0
	s_barrier
	s_cmp_gt_u32 s50, 29
	s_cbranch_scc0 .LBB0_861
	s_and_b64 vcc, exec, s[12:13]
	s_cbranch_vccz .LBB0_864
	s_barrier
